# non-temporal hint on the single-use loads of the latency-bound scan phase (hgrn_b2, s5_c) and of the four split-K fixup phases, on top of v22
# baseline (speedup 1.0000x reference)
; DI unsigned pk2(float lo, float hi) { unsigned r; asm volatile("v_cvt_pk_bf16_f32 %0, %1, %2" : "=v"(r) : "v"(lo), "v"(hi)); return r; }
; DI float bflo(unsigned u) { return __uint_as_float(u << 16); }
; DI float bfhi(unsigned u) { return __uint_as_float(u & 0xffff0000u); }
; template <int NB> DI void hgrn_b2_steps(const Prm& p, int item, int v, int d4, float (&S)[4]) {
;     u32x2 uu[NB]; f32x4 al[NB];
; #pragma unroll
;     for (int i = 0; i < NB; ++i) { uu[i] = *(const u32x2*)(p.UT + (size_t)(item + i) * 16384 + v * 128 + d4); al[i] = *(const f32x4*)(p.AL + (size_t)(item + i) * 128 + d4); }
; #pragma unroll
;     for (int i = 0; i < NB; ++i) { u32x2 o; o.x = pk2(S[0], S[1]); o.y = pk2(S[2], S[3]);
;         *(u32x2*)(p.UT + (size_t)(item + i) * 16384 + v * 128 + d4) = o;
;         S[0] = al[i][0] * S[0] + bflo(uu[i].x); S[1] = al[i][1] * S[1] + bfhi(uu[i].x); S[2] = al[i][2] * S[2] + bflo(uu[i].y); S[3] = al[i][3] * S[3] + bfhi(uu[i].y); }
; }
.LBB0_847:
	v_add_co_u32_e32 v80, vcc, 0x8000, v10
	global_load_dwordx2 v[78:79], v[10:11], off nt
	global_load_dwordx4 v[26:29], v[12:13], off offset:-512 nt
	v_addc_co_u32_e32 v81, vcc, 0, v11, vcc
	v_add_u32_e32 v0, s15, v2
	global_load_dwordx2 v[82:83], v[80:81], off nt
	global_load_dwordx4 v[30:33], v[12:13], off nt
	v_add_u32_e32 v34, 15, v0
	v_ashrrev_i32_e32 v35, 31, v34
	v_add_u32_e32 v38, 16, v0
	v_lshlrev_b64 v[36:37], 15, v[34:35]
	v_ashrrev_i32_e32 v39, 31, v38
	v_add_u32_e32 v42, 17, v0
	v_lshl_add_u64 v[84:85], v[4:5], 0, v[36:37]
	v_lshlrev_b64 v[34:35], 9, v[34:35]
	v_lshlrev_b64 v[40:41], 15, v[38:39]
	v_ashrrev_i32_e32 v43, 31, v42
	global_load_dwordx2 v[86:87], v[84:85], off nt
	v_lshl_add_u64 v[34:35], v[6:7], 0, v[34:35]
	v_lshl_add_u64 v[88:89], v[4:5], 0, v[40:41]
	v_lshlrev_b64 v[38:39], 9, v[38:39]
	v_lshlrev_b64 v[44:45], 15, v[42:43]
	global_load_dwordx4 v[34:37], v[34:35], off nt
	v_lshl_add_u64 v[38:39], v[6:7], 0, v[38:39]
	global_load_dwordx2 v[90:91], v[88:89], off nt
	v_lshl_add_u64 v[92:93], v[4:5], 0, v[44:45]
	v_lshlrev_b64 v[42:43], 9, v[42:43]
	global_load_dwordx4 v[38:41], v[38:39], off nt
	v_lshl_add_u64 v[42:43], v[6:7], 0, v[42:43]
	global_load_dwordx2 v[94:95], v[92:93], off nt
	v_add_u32_e32 v46, 18, v0
	global_load_dwordx4 v[42:45], v[42:43], off nt
	v_ashrrev_i32_e32 v47, 31, v46
	v_lshlrev_b64 v[48:49], 15, v[46:47]
	v_add_u32_e32 v50, 19, v0
	v_lshl_add_u64 v[96:97], v[4:5], 0, v[48:49]
	v_lshlrev_b64 v[46:47], 9, v[46:47]
	v_ashrrev_i32_e32 v51, 31, v50
	v_add_u32_e32 v54, 20, v0
	global_load_dwordx2 v[98:99], v[96:97], off nt
	v_lshl_add_u64 v[46:47], v[6:7], 0, v[46:47]
	v_lshlrev_b64 v[52:53], 15, v[50:51]
	v_ashrrev_i32_e32 v55, 31, v54
	v_add_u32_e32 v58, 21, v0
	global_load_dwordx4 v[46:49], v[46:47], off nt
	v_lshl_add_u64 v[100:101], v[4:5], 0, v[52:53]
	v_lshlrev_b64 v[50:51], 9, v[50:51]
	v_lshlrev_b64 v[56:57], 15, v[54:55]
	v_ashrrev_i32_e32 v59, 31, v58
	v_add_u32_e32 v62, 22, v0
	global_load_dwordx2 v[102:103], v[100:101], off nt
	v_lshl_add_u64 v[50:51], v[6:7], 0, v[50:51]
	v_lshl_add_u64 v[106:107], v[4:5], 0, v[56:57]
	v_lshlrev_b64 v[54:55], 9, v[54:55]
	v_lshlrev_b64 v[60:61], 15, v[58:59]
	v_ashrrev_i32_e32 v63, 31, v62
	v_add_u32_e32 v66, 23, v0
	global_load_dwordx4 v[50:53], v[50:51], off nt
	v_lshl_add_u64 v[54:55], v[6:7], 0, v[54:55]
	global_load_dwordx2 v[108:109], v[106:107], off nt
	v_lshl_add_u64 v[110:111], v[4:5], 0, v[60:61]
	v_lshlrev_b64 v[58:59], 9, v[58:59]
	v_lshlrev_b64 v[64:65], 15, v[62:63]
	v_ashrrev_i32_e32 v67, 31, v66
	v_add_u32_e32 v70, 24, v0
	global_load_dwordx4 v[54:57], v[54:55], off nt
	v_lshl_add_u64 v[58:59], v[6:7], 0, v[58:59]
	global_load_dwordx2 v[112:113], v[110:111], off nt
	v_lshl_add_u64 v[114:115], v[4:5], 0, v[64:65]
	v_lshlrev_b64 v[62:63], 9, v[62:63]
	v_lshlrev_b64 v[68:69], 15, v[66:67]
	v_ashrrev_i32_e32 v71, 31, v70
	global_load_dwordx4 v[58:61], v[58:59], off nt
	v_lshl_add_u64 v[62:63], v[6:7], 0, v[62:63]
	global_load_dwordx2 v[116:117], v[114:115], off nt
	v_lshl_add_u64 v[118:119], v[4:5], 0, v[68:69]
	v_lshlrev_b64 v[66:67], 9, v[66:67]
	v_lshlrev_b64 v[72:73], 15, v[70:71]
	v_add_u32_e32 v74, 25, v0
	global_load_dwordx4 v[62:65], v[62:63], off nt
	v_lshl_add_u64 v[66:67], v[6:7], 0, v[66:67]
	global_load_dwordx2 v[120:121], v[118:119], off nt
	v_lshl_add_u64 v[122:123], v[4:5], 0, v[72:73]
	v_lshlrev_b64 v[70:71], 9, v[70:71]
	v_ashrrev_i32_e32 v75, 31, v74
	global_load_dwordx4 v[66:69], v[66:67], off nt
	v_lshl_add_u64 v[70:71], v[6:7], 0, v[70:71]
	global_load_dwordx2 v[124:125], v[122:123], off nt
	v_lshlrev_b64 v[76:77], 15, v[74:75]
	global_load_dwordx4 v[70:73], v[70:71], off nt
	v_lshl_add_u64 v[126:127], v[4:5], 0, v[76:77]
	v_lshlrev_b64 v[74:75], 9, v[74:75]
	global_load_dwordx2 v[128:129], v[126:127], off nt
	v_lshl_add_u64 v[74:75], v[6:7], 0, v[74:75]
	global_load_dwordx4 v[74:77], v[74:75], off nt
	v_cvt_pk_bf16_f32 v8, v8, v9
	v_cvt_pk_bf16_f32 v9, v14, v15
	global_store_dwordx2 v[10:11], v[8:9], off
	s_waitcnt vmcnt(26)
	v_lshlrev_b32_e32 v8, 16, v78
	v_and_b32_e32 v9, 0xffff0000, v78
	s_waitcnt vmcnt(25)
	v_pk_fma_f32 v[8:9], v[16:17], v[26:27], v[8:9]
	s_waitcnt vmcnt(24)
	v_lshlrev_b32_e32 v16, 16, v82
	v_and_b32_e32 v17, 0xffff0000, v82
	v_cvt_pk_bf16_f32 v14, v8, v9
	s_waitcnt vmcnt(23)
	v_pk_fma_f32 v[8:9], v[30:31], v[8:9], v[16:17]
	v_lshlrev_b32_e32 v16, 16, v79
	v_and_b32_e32 v17, 0xffff0000, v79
	v_pk_fma_f32 v[16:17], v[18:19], v[28:29], v[16:17]
	s_waitcnt vmcnt(22)
	v_lshlrev_b32_e32 v18, 16, v87
	v_cvt_pk_bf16_f32 v15, v16, v17
	global_store_dwordx2 v[80:81], v[14:15], off
	v_lshlrev_b32_e32 v14, 16, v83
	v_and_b32_e32 v15, 0xffff0000, v83
	v_pk_fma_f32 v[14:15], v[32:33], v[16:17], v[14:15]
	v_cvt_pk_bf16_f32 v16, v8, v9
	v_and_b32_e32 v19, 0xffff0000, v87
	v_cvt_pk_bf16_f32 v17, v14, v15
	global_store_dwordx2 v[84:85], v[16:17], off
	v_lshlrev_b32_e32 v16, 16, v86
	v_and_b32_e32 v17, 0xffff0000, v86
	s_waitcnt vmcnt(23)
	v_pk_fma_f32 v[8:9], v[34:35], v[8:9], v[16:17]
	s_waitcnt vmcnt(22)
	v_lshlrev_b32_e32 v28, 16, v90
	v_cvt_pk_bf16_f32 v16, v8, v9
	v_and_b32_e32 v29, 0xffff0000, v90
	v_pk_fma_f32 v[14:15], v[36:37], v[14:15], v[18:19]
	s_waitcnt vmcnt(21)
	v_pk_fma_f32 v[8:9], v[38:39], v[8:9], v[28:29]
	v_cvt_pk_bf16_f32 v17, v14, v15
	s_waitcnt vmcnt(20)
	v_lshlrev_b32_e32 v28, 16, v94
	v_and_b32_e32 v29, 0xffff0000, v94
	global_store_dwordx2 v[88:89], v[16:17], off
	v_lshlrev_b32_e32 v16, 16, v91
	v_and_b32_e32 v17, 0xffff0000, v91
	s_waitcnt vmcnt(20)
	v_pk_fma_f32 v[28:29], v[42:43], v[8:9], v[28:29]
	v_pk_fma_f32 v[14:15], v[40:41], v[14:15], v[16:17]
	v_cvt_pk_bf16_f32 v8, v8, v9
	s_waitcnt vmcnt(19)
; DI unsigned pk2(float lo, float hi) { unsigned r; asm volatile("v_cvt_pk_bf16_f32 %0, %1, %2" : "=v"(r) : "v"(lo), "v"(hi)); return r; }
; DI float bflo(unsigned u) { return __uint_as_float(u << 16); }
; DI float bfhi(unsigned u) { return __uint_as_float(u & 0xffff0000u); }
; template <int NB> DI void hgrn_b2_steps(const Prm& p, int item, int v, int d4, float (&S)[4]) {
;     u32x2 uu[NB]; f32x4 al[NB];
; #pragma unroll
;     for (int i = 0; i < NB; ++i) { uu[i] = *(const u32x2*)(p.UT + (size_t)(item + i) * 16384 + v * 128 + d4); al[i] = *(const f32x4*)(p.AL + (size_t)(item + i) * 128 + d4); }
; #pragma unroll
;     for (int i = 0; i < NB; ++i) { u32x2 o; o.x = pk2(S[0], S[1]); o.y = pk2(S[2], S[3]);
;         *(u32x2*)(p.UT + (size_t)(item + i) * 16384 + v * 128 + d4) = o;
;         S[0] = al[i][0] * S[0] + bflo(uu[i].x); S[1] = al[i][1] * S[1] + bfhi(uu[i].x); S[2] = al[i][2] * S[2] + bflo(uu[i].y); S[3] = al[i][3] * S[3] + bfhi(uu[i].y); }
; }
; DI void hgrn_b2(const Prm& p, int gtid, int GT) {
;     for (int idx = gtid; idx < 64 * 4096; idx += GT) {
;         const int bhx = idx >> 12, e = idx & 4095, v = e >> 5, d4 = (e & 31) * 4; const bool smp = bhx >= 32;
;         float S[4] = {0.f, 0.f, 0.f, 0.f};
;         if (smp) {
; #pragma unroll
;             for (int j = 0; j < 4; ++j) S[j] = p.state_hgrn[((size_t)(bhx - 32) * 128 + d4 + j) * 128 + v];
;             hgrn_b2_steps<1>(p, 2080 + (bhx - 32), v, d4, S); }
;         else { for (int c0 = 0; c0 < 65; c0 += 13) hgrn_b2_steps<13>(p, bhx * 65 + c0, v, d4, S); }
	v_lshlrev_b32_e32 v30, 16, v98
	v_cvt_pk_bf16_f32 v9, v14, v15
	global_store_dwordx2 v[92:93], v[8:9], off
	v_lshlrev_b32_e32 v8, 16, v95
	v_and_b32_e32 v9, 0xffff0000, v95
	v_pk_fma_f32 v[8:9], v[44:45], v[14:15], v[8:9]
	v_cvt_pk_bf16_f32 v14, v28, v29
	v_and_b32_e32 v31, 0xffff0000, v98
	v_cvt_pk_bf16_f32 v15, v8, v9
	global_store_dwordx2 v[96:97], v[14:15], off
	v_lshlrev_b32_e32 v14, 16, v99
	v_and_b32_e32 v15, 0xffff0000, v99
	s_waitcnt vmcnt(20)
	v_pk_fma_f32 v[30:31], v[46:47], v[28:29], v[30:31]
	v_pk_fma_f32 v[8:9], v[48:49], v[8:9], v[14:15]
	v_cvt_pk_bf16_f32 v14, v30, v31
	s_waitcnt vmcnt(19)
	v_lshlrev_b32_e32 v32, 16, v102
	v_cvt_pk_bf16_f32 v15, v8, v9
	v_and_b32_e32 v33, 0xffff0000, v102
	global_store_dwordx2 v[100:101], v[14:15], off
	v_lshlrev_b32_e32 v14, 16, v103
	v_and_b32_e32 v15, 0xffff0000, v103
	s_waitcnt vmcnt(18)
	v_lshlrev_b32_e32 v26, 16, v108
	v_pk_fma_f32 v[32:33], v[50:51], v[30:31], v[32:33]
	v_and_b32_e32 v27, 0xffff0000, v108
	v_lshlrev_b32_e32 v34, 16, v109
	v_pk_fma_f32 v[14:15], v[52:53], v[8:9], v[14:15]
	v_cvt_pk_bf16_f32 v8, v32, v33
	v_and_b32_e32 v35, 0xffff0000, v109
	v_cvt_pk_bf16_f32 v9, v14, v15
	global_store_dwordx2 v[106:107], v[8:9], off
	s_waitcnt vmcnt(17)
	v_lshlrev_b32_e32 v8, 16, v112
	v_and_b32_e32 v9, 0xffff0000, v112
	v_lshlrev_b32_e32 v16, 16, v113
	v_and_b32_e32 v17, 0xffff0000, v113
	v_pk_fma_f32 v[18:19], v[54:55], v[32:33], v[26:27]
	v_pk_fma_f32 v[14:15], v[56:57], v[14:15], v[34:35]
	v_cvt_pk_bf16_f32 v26, v18, v19
	s_waitcnt vmcnt(16)
	v_pk_fma_f32 v[18:19], v[58:59], v[18:19], v[8:9]
	s_waitcnt vmcnt(15)
	v_lshlrev_b32_e32 v8, 16, v116
	v_and_b32_e32 v9, 0xffff0000, v116
	v_pk_fma_f32 v[16:17], v[60:61], v[14:15], v[16:17]
	v_lshlrev_b32_e32 v34, 16, v117
	v_and_b32_e32 v35, 0xffff0000, v117
	v_cvt_pk_bf16_f32 v27, v14, v15
	global_store_dwordx2 v[110:111], v[26:27], off
	v_cvt_pk_bf16_f32 v14, v18, v19
	v_cvt_pk_bf16_f32 v15, v16, v17
	s_waitcnt vmcnt(15)
	v_pk_fma_f32 v[28:29], v[62:63], v[18:19], v[8:9]
	s_waitcnt vmcnt(14)
	v_lshlrev_b32_e32 v8, 16, v120
	v_and_b32_e32 v9, 0xffff0000, v120
	v_pk_fma_f32 v[34:35], v[64:65], v[16:17], v[34:35]
	v_lshlrev_b32_e32 v36, 16, v121
	v_and_b32_e32 v37, 0xffff0000, v121
	global_store_dwordx2 v[114:115], v[14:15], off
	v_cvt_pk_bf16_f32 v14, v28, v29
	v_cvt_pk_bf16_f32 v15, v34, v35
	s_waitcnt vmcnt(14)
	v_pk_fma_f32 v[30:31], v[66:67], v[28:29], v[8:9]
	s_waitcnt vmcnt(13)
	v_lshlrev_b32_e32 v8, 16, v124
	v_and_b32_e32 v9, 0xffff0000, v124
	v_pk_fma_f32 v[36:37], v[68:69], v[34:35], v[36:37]
	v_lshlrev_b32_e32 v38, 16, v125
	v_and_b32_e32 v39, 0xffff0000, v125
	global_store_dwordx2 v[118:119], v[14:15], off
	v_cvt_pk_bf16_f32 v14, v30, v31
	v_cvt_pk_bf16_f32 v15, v36, v37
	s_waitcnt vmcnt(13)
	v_pk_fma_f32 v[32:33], v[70:71], v[30:31], v[8:9]
	v_pk_fma_f32 v[38:39], v[72:73], v[36:37], v[38:39]
	global_store_dwordx2 v[122:123], v[14:15], off
	v_cvt_pk_bf16_f32 v14, v32, v33
	v_cvt_pk_bf16_f32 v15, v38, v39
	s_waitcnt vmcnt(13)
	v_lshlrev_b32_e32 v8, 16, v128
	v_and_b32_e32 v9, 0xffff0000, v128
	global_store_dwordx2 v[126:127], v[14:15], off
	v_lshlrev_b32_e32 v14, 16, v129
	v_and_b32_e32 v15, 0xffff0000, v129
	s_mov_b64 s[16:17], 0x68000
	s_waitcnt vmcnt(13)
	v_pk_fma_f32 v[8:9], v[74:75], v[32:33], v[8:9]
	v_pk_fma_f32 v[14:15], v[76:77], v[38:39], v[14:15]
	s_add_i32 s15, s15, 13
	v_lshl_add_u64 v[10:11], v[10:11], 0, s[16:17]
	s_mov_b64 s[16:17], 0x1a00
	v_lshl_add_u64 v[12:13], v[12:13], 0, s[16:17]
	s_cmp_lt_u32 s15, 52
	v_mov_b32_e32 v16, v8
	v_mov_b32_e32 v17, v9
	v_mov_b32_e32 v18, v14
	v_mov_b32_e32 v19, v15
	s_cbranch_scc1 .LBB0_847
	v_subrev_u32_e32 v0, 32, v23
	v_mov_b64_e32 v[2:3], v[0:1]
.LBB0_849:
	s_or_saveexec_b64 s[12:13], s[12:13]
	v_mov_b64_e32 v[12:13], 0x2080000
	v_lshlrev_b32_e32 v4, 2, v24
	s_xor_b64 exec, exec, s[12:13]
	s_cbranch_execz .LBB0_844
	v_readlane_b32 s16, v254, 54
	v_subrev_u32_e32 v2, 32, v23
	v_mov_b32_e32 v3, v1
	v_mov_b32_e32 v5, v1
	v_readlane_b32 s20, v254, 58
	v_readlane_b32 s21, v254, 59
	v_lshlrev_b64 v[12:13], 16, v[2:3]
	v_readlane_b32 s17, v254, 55
	v_lshl_add_u64 v[8:9], s[20:21], 0, v[4:5]
	v_readlane_b32 s18, v254, 56
	v_readlane_b32 s19, v254, 57
	v_readlane_b32 s22, v254, 60
	v_readlane_b32 s23, v254, 61
	v_readlane_b32 s24, v254, 62
	v_readlane_b32 s25, v254, 63
	v_readlane_b32 s26, v255, 0
	v_readlane_b32 s27, v255, 1
	v_readlane_b32 s28, v255, 2
	v_readlane_b32 s29, v255, 3
	v_readlane_b32 s30, v255, 4
	v_readlane_b32 s31, v255, 5
	v_lshlrev_b32_e32 v14, 9, v22
	v_mov_b32_e32 v15, v1
	v_lshl_add_u64 v[8:9], v[8:9], 0, v[12:13]
	v_lshl_add_u64 v[8:9], v[8:9], 0, v[14:15]
	v_add_u32_e32 v16, 0x800, v23
	v_mov_b32_e32 v17, v1
	v_readlane_b32 s16, v255, 8
	global_load_dword v12, v[8:9], off
	global_load_dword v13, v[8:9], off offset:512
	global_load_dword v14, v[8:9], off offset:1024
	global_load_dword v15, v[8:9], off offset:1536
	v_lshlrev_b64 v[8:9], 15, v[16:17]
	v_readlane_b32 s17, v255, 9
	v_mov_b32_e32 v7, v1
	v_readlane_b32 s18, v255, 10
	v_lshl_add_u64 v[8:9], s[16:17], 0, v[8:9]
	v_lshl_add_u64 v[8:9], v[8:9], 0, v[0:1]
	v_lshl_add_u64 v[8:9], v[8:9], 0, v[6:7]
	v_readlane_b32 s19, v255, 11
	global_load_dwordx2 v[18:19], v[8:9], off nt
	v_lshlrev_b64 v[8:9], 9, v[16:17]
	v_lshl_add_u64 v[8:9], s[18:19], 0, v[8:9]
	v_mov_b32_e32 v11, v1
	v_lshl_add_u64 v[8:9], v[8:9], 0, v[10:11]
	global_load_dwordx4 v[8:11], v[8:9], off nt
	v_lshlrev_b32_e32 v16, 15, v16
	v_lshl_add_u64 v[16:17], s[16:17], 0, v[16:17]
	v_lshl_add_u64 v[16:17], v[16:17], 0, v[0:1]
	v_lshl_add_u64 v[6:7], v[16:17], 0, v[6:7]
	v_readlane_b32 s20, v255, 12
	v_readlane_b32 s21, v255, 13
	v_readlane_b32 s22, v255, 14
	v_readlane_b32 s23, v255, 15
	v_readlane_b32 s24, v255, 16
	v_readlane_b32 s25, v255, 17
	v_readlane_b32 s26, v255, 18
	v_readlane_b32 s27, v255, 19
	v_readlane_b32 s28, v255, 20
	v_readlane_b32 s29, v255, 21
	v_readlane_b32 s30, v255, 22
	v_readlane_b32 s31, v255, 23
	s_waitcnt vmcnt(4)
	v_cvt_pk_bf16_f32 v16, v12, v13
	s_waitcnt vmcnt(2)
	v_cvt_pk_bf16_f32 v17, v14, v15
	global_store_dwordx2 v[6:7], v[16:17], off
	s_waitcnt vmcnt(2)
	v_lshlrev_b32_e32 v6, 16, v18
	v_and_b32_e32 v7, 0xffff0000, v18
	v_lshlrev_b32_e32 v16, 16, v19
	v_and_b32_e32 v17, 0xffff0000, v19
	s_waitcnt vmcnt(1)
	v_pk_fma_f32 v[8:9], v[12:13], v[8:9], v[6:7]
	v_pk_fma_f32 v[14:15], v[14:15], v[10:11], v[16:17]
	v_mov_b64_e32 v[12:13], 0x2100000
	s_branch .LBB0_844

; DI unsigned pk2(float lo, float hi) { unsigned r; asm volatile("v_cvt_pk_bf16_f32 %0, %1, %2" : "=v"(r) : "v"(lo), "v"(hi)); return r; }
; template <int NB> DI void s5_c_steps(const Prm& p, int col, size_t base, float ar, float ai, float& xr, float& xi) {
;     f32x2v xl[NB];
; #pragma unroll
;     for (int i = 0; i < NB; ++i) xl[i] = *(const f32x2v*)(p.XLOC + (size_t)(col + i) * 4096 + base);
; #pragma unroll
;     for (int i = 0; i < NB; ++i) { *(unsigned*)(p.XPREV + (size_t)(col + i) * 4096 + base) = pk2(xr, xi);
;         const float nr = ar * xr - ai * xi + xl[i].x, ni = ar * xi + ai * xr + xl[i].y; xr = nr; xi = ni; }
; }
; DI void s5_c(const Prm& p, int gtid) {
;     if (gtid >= 16 * 2048) return;
;     const int seq = gtid >> 11, g = (gtid >> 6) & 31, n = gtid & 63; const bool smp = seq >= 8; const int b = seq & 7;
;     float xr = 0.f, xi = 0.f; if (smp) { xr = p.ssm_re0[(b * 32 + g) * 64 + n]; xi = p.ssm_im0[(b * 32 + g) * 64 + n]; }
;     const float ar = p.A16[2 * (g * 64 + n)], ai = p.A16[2 * (g * 64 + n) + 1];
;     const size_t base = (size_t)g * 128 + 2 * n;
;     if (smp) s5_c_steps<4>(p, 2056 + 4 * b, base, ar, ai, xr, xi);
;     else { for (int c0 = 0; c0 < 256; c0 += 16) s5_c_steps<16>(p, 257 * b + c0, base, ar, ai, xr, xi); s5_c_steps<1>(p, 257 * b + 256, base, ar, ai, xr, xi); }
.LBB0_857:
	s_or_b64 exec, exec, s[10:11]
	v_lshlrev_b32_e32 v0, 3, v162
	v_and_b32_e32 v0, 0x3ff8, v0
	global_load_dwordx2 v[0:1], v0, s[40:41] nt
	v_lshlrev_b32_e32 v14, 7, v70
	v_lshlrev_b32_e32 v15, 1, v152
	v_or_b32_e32 v2, v14, v15
	v_readlane_b32 s12, v255, 8
	v_lshlrev_b32_e32 v6, 2, v2
	v_mov_b32_e32 v7, v5
	v_readlane_b32 s16, v255, 12
	v_readlane_b32 s17, v255, 13
	v_lshlrev_b32_e32 v2, 1, v2
	v_readlane_b32 s13, v255, 9
	v_lshl_add_u64 v[8:9], s[16:17], 0, v[6:7]
	v_readlane_b32 s14, v255, 10
	v_readlane_b32 s15, v255, 11
	v_readlane_b32 s18, v255, 14
	v_readlane_b32 s19, v255, 15
	v_readlane_b32 s20, v255, 16
	v_readlane_b32 s21, v255, 17
	v_readlane_b32 s22, v255, 18
	v_readlane_b32 s23, v255, 19
	v_readlane_b32 s24, v255, 20
	v_readlane_b32 s25, v255, 21
	v_readlane_b32 s26, v255, 22
	v_readlane_b32 s27, v255, 23
	s_and_saveexec_b64 s[0:1], vcc
	s_xor_b64 s[0:1], exec, s[0:1]
	s_cbranch_execz .LBB0_861
	v_readlane_b32 s12, v255, 8
	v_mov_b32_e32 v3, v5
	v_readlane_b32 s18, v255, 14
	v_readlane_b32 s19, v255, 15
	v_mul_u32_u24_e32 v7, 0x101, v71
	v_lshlrev_b32_e32 v4, 13, v7
	v_lshl_add_u64 v[12:13], s[18:19], 0, v[2:3]
	v_add_u32_e32 v3, v14, v15
	v_lshlrev_b32_e32 v14, 1, v3
	v_mov_b32_e32 v15, v5
	v_lshl_add_u64 v[14:15], v[4:5], 0, v[14:15]
	v_lshlrev_b32_e32 v4, 14, v7
	v_lshlrev_b32_e32 v18, 2, v3
	v_mov_b32_e32 v19, v5
	v_readlane_b32 s16, v255, 12
	v_readlane_b32 s17, v255, 13
	v_lshl_add_u64 v[14:15], s[18:19], 0, v[14:15]
	s_mov_b64 s[10:11], 0xa000
	v_lshl_add_u64 v[18:19], v[4:5], 0, v[18:19]
	v_lshl_add_u64 v[14:15], v[14:15], 0, s[10:11]
	v_lshl_add_u64 v[18:19], s[16:17], 0, v[18:19]
	s_mov_b64 s[10:11], 0x14000
	s_waitcnt vmcnt(0)
	v_pk_mov_b32 v[10:11], v[0:1], v[0:1] op_sel:[1,0]
	v_lshl_add_u64 v[18:19], v[18:19], 0, s[10:11]
	s_mov_b32 s10, -16
	v_readlane_b32 s13, v255, 9
	v_readlane_b32 s14, v255, 10
	v_readlane_b32 s15, v255, 11
	v_readlane_b32 s20, v255, 16
	v_readlane_b32 s21, v255, 17
	v_readlane_b32 s22, v255, 18
	v_readlane_b32 s23, v255, 19
	v_readlane_b32 s24, v255, 20
	v_readlane_b32 s25, v255, 21
	v_readlane_b32 s26, v255, 22
	v_readlane_b32 s27, v255, 23
.LBB0_859:
	v_add_co_u32_e32 v20, vcc, 0xfffec000, v18
	v_add_u32_e32 v3, s10, v7
	s_nop 0
	v_addc_co_u32_e32 v21, vcc, -1, v19, vcc
	global_load_dwordx2 v[46:47], v[20:21], off nt
	v_add_co_u32_e32 v20, vcc, 0xffff0000, v18
	v_add_u32_e32 v4, 22, v3
	s_nop 0
	v_addc_co_u32_e32 v21, vcc, -1, v19, vcc
	global_load_dwordx2 v[40:41], v[20:21], off nt
	v_add_co_u32_e32 v20, vcc, 0xffff4000, v18
	v_lshlrev_b64 v[24:25], 14, v[4:5]
	s_nop 0
	v_addc_co_u32_e32 v21, vcc, -1, v19, vcc
	global_load_dwordx2 v[30:31], v[20:21], off nt
	v_add_co_u32_e32 v20, vcc, 0xffff8000, v18
	v_add_u32_e32 v34, 24, v3
	s_nop 0
	v_addc_co_u32_e32 v21, vcc, -1, v19, vcc
	global_load_dwordx2 v[22:23], v[20:21], off nt
	v_add_co_u32_e32 v20, vcc, 0xffffc000, v18
	v_mov_b32_e32 v35, v5
	s_nop 0
	v_addc_co_u32_e32 v21, vcc, -1, v19, vcc
	global_load_dwordx2 v[20:21], v[20:21], off nt
	s_nop 0
	global_load_dwordx2 v[28:29], v[18:19], off nt
	v_add_u32_e32 v44, 26, v3
	v_mov_b32_e32 v45, v5
	v_add_u32_e32 v54, 28, v3
	v_mov_b32_e32 v55, v5
	v_lshl_add_u64 v[24:25], v[8:9], 0, v[24:25]
	v_lshlrev_b64 v[36:37], 14, v[34:35]
	v_lshlrev_b64 v[48:49], 14, v[44:45]
	v_lshlrev_b64 v[56:57], 14, v[54:55]
	global_load_dwordx2 v[26:27], v[24:25], off nt
	v_lshl_add_u64 v[36:37], v[8:9], 0, v[36:37]
	v_lshl_add_u64 v[48:49], v[8:9], 0, v[48:49]
	v_lshl_add_u64 v[56:57], v[8:9], 0, v[56:57]
	global_load_dwordx2 v[38:39], v[36:37], off nt
	global_load_dwordx2 v[50:51], v[48:49], off nt
	global_load_dwordx2 v[58:59], v[56:57], off nt
	v_add_u32_e32 v24, 23, v3
	v_mov_b32_e32 v25, v5
	v_lshlrev_b64 v[32:33], 14, v[24:25]
	v_lshl_add_u64 v[32:33], v[8:9], 0, v[32:33]
	global_load_dwordx2 v[32:33], v[32:33], off nt
	v_add_u32_e32 v36, 25, v3
	v_mov_b32_e32 v37, v5
	v_lshlrev_b64 v[42:43], 14, v[36:37]
	v_lshl_add_u64 v[42:43], v[8:9], 0, v[42:43]
	global_load_dwordx2 v[42:43], v[42:43], off nt
	v_add_u32_e32 v48, 27, v3
	v_mov_b32_e32 v49, v5
	v_lshlrev_b64 v[52:53], 14, v[48:49]
	v_lshl_add_u64 v[52:53], v[8:9], 0, v[52:53]
	global_load_dwordx2 v[52:53], v[52:53], off nt
	v_add_u32_e32 v56, 29, v3
	v_mov_b32_e32 v57, v5
	v_lshlrev_b64 v[60:61], 14, v[56:57]
	v_lshl_add_u64 v[60:61], v[8:9], 0, v[60:61]
	global_load_dwordx2 v[60:61], v[60:61], off nt
	v_add_u32_e32 v62, 30, v3
	v_mov_b32_e32 v63, v5
	v_lshlrev_b64 v[64:65], 14, v[62:63]
	v_lshl_add_u64 v[64:65], v[8:9], 0, v[64:65]
	global_load_dwordx2 v[66:67], v[64:65], off nt
	v_add_u32_e32 v64, 31, v3
	v_mov_b32_e32 v65, v5
	v_lshlrev_b64 v[68:69], 14, v[64:65]
	v_lshl_add_u64 v[68:69], v[8:9], 0, v[68:69]
	global_load_dwordx2 v[68:69], v[68:69], off nt
	s_mov_b32 s11, 0xffff6000
	v_add_co_u32_e32 v72, vcc, s11, v14
	v_cvt_pk_bf16_f32 v3, v16, v17
	v_mul_f32_e32 v74, v1, v16
	s_nop 0
	v_addc_co_u32_e32 v73, vcc, -1, v15, vcc
	global_store_dword v[72:73], v3, off
	v_mul_f32_e32 v72, v1, v17
	v_pk_fma_f32 v[72:73], v[0:1], v[16:17], v[72:73] op_sel_hi:[1,1,0] neg_lo:[0,0,1] neg_hi:[0,0,1]
	v_pk_fma_f32 v[16:17], v[0:1], v[16:17], v[74:75] op_sel:[0,1,0] op_sel_hi:[1,0,0]
	s_movk_i32 s11, 0x8000
	s_waitcnt vmcnt(16)
	v_pk_add_f32 v[72:73], v[72:73], v[46:47]
	v_pk_add_f32 v[16:17], v[16:17], v[46:47] op_sel:[0,1] op_sel_hi:[1,0]
	v_add_co_u32_e32 v46, vcc, s11, v14
	v_cvt_pk_bf16_f32 v3, v72, v16
	v_pk_mul_f32 v[16:17], v[10:11], v[16:17] op_sel_hi:[1,0]
	s_nop 0
	v_addc_co_u32_e32 v47, vcc, -1, v15, vcc
	global_store_dword v[46:47], v3, off
	v_pk_fma_f32 v[46:47], v[0:1], v[72:73], v[16:17] neg_lo:[0,0,1] neg_hi:[0,0,1]
	v_pk_fma_f32 v[16:17], v[0:1], v[72:73], v[16:17] op_sel_hi:[1,0,1]
	s_movk_i32 s11, 0xa000
	v_mov_b32_e32 v47, v17
	s_waitcnt vmcnt(16)
; DI unsigned pk2(float lo, float hi) { unsigned r; asm volatile("v_cvt_pk_bf16_f32 %0, %1, %2" : "=v"(r) : "v"(lo), "v"(hi)); return r; }
; template <int NB> DI void s5_c_steps(const Prm& p, int col, size_t base, float ar, float ai, float& xr, float& xi) {
;     f32x2v xl[NB];
; #pragma unroll
;     for (int i = 0; i < NB; ++i) xl[i] = *(const f32x2v*)(p.XLOC + (size_t)(col + i) * 4096 + base);
; #pragma unroll
;     for (int i = 0; i < NB; ++i) { *(unsigned*)(p.XPREV + (size_t)(col + i) * 4096 + base) = pk2(xr, xi);
;         const float nr = ar * xr - ai * xi + xl[i].x, ni = ar * xi + ai * xr + xl[i].y; xr = nr; xi = ni; }
; }
	v_pk_add_f32 v[16:17], v[40:41], v[46:47]
	v_add_co_u32_e32 v40, vcc, s11, v14
	v_cvt_pk_bf16_f32 v3, v16, v17
	v_mul_f32_e32 v46, v11, v17
	s_nop 0
	v_addc_co_u32_e32 v41, vcc, -1, v15, vcc
	global_store_dword v[40:41], v3, off
	v_mul_f32_e32 v40, v1, v17
	v_pk_fma_f32 v[40:41], v[0:1], v[16:17], v[40:41] op_sel_hi:[1,1,0] neg_lo:[0,0,1] neg_hi:[0,0,1]
	v_pk_fma_f32 v[16:17], v[10:11], v[16:17], v[46:47] op_sel_hi:[1,1,0]
	s_movk_i32 s11, 0xc000
	s_waitcnt vmcnt(16)
	v_pk_add_f32 v[40:41], v[30:31], v[40:41]
	v_pk_add_f32 v[16:17], v[30:31], v[16:17] op_sel:[1,0] op_sel_hi:[0,1]
	v_add_co_u32_e32 v30, vcc, s11, v14
	v_cvt_pk_bf16_f32 v3, v40, v16
	v_pk_mul_f32 v[16:17], v[10:11], v[16:17] op_sel_hi:[1,0]
	s_nop 0
	v_addc_co_u32_e32 v31, vcc, -1, v15, vcc
	global_store_dword v[30:31], v3, off
	v_pk_fma_f32 v[30:31], v[0:1], v[40:41], v[16:17] neg_lo:[0,0,1] neg_hi:[0,0,1]
	v_pk_fma_f32 v[16:17], v[0:1], v[40:41], v[16:17] op_sel_hi:[1,0,1]
	s_movk_i32 s11, 0xe000
	v_mov_b32_e32 v31, v17
	s_waitcnt vmcnt(16)
	v_pk_add_f32 v[16:17], v[22:23], v[30:31]
	v_add_co_u32_e32 v22, vcc, s11, v14
	v_cvt_pk_bf16_f32 v3, v16, v17
	v_mul_f32_e32 v30, v11, v17
	s_nop 0
	v_addc_co_u32_e32 v23, vcc, -1, v15, vcc
	global_store_dword v[22:23], v3, off
	v_mul_f32_e32 v22, v1, v17
	v_pk_fma_f32 v[22:23], v[0:1], v[16:17], v[22:23] op_sel_hi:[1,1,0] neg_lo:[0,0,1] neg_hi:[0,0,1]
	v_pk_fma_f32 v[16:17], v[10:11], v[16:17], v[30:31] op_sel_hi:[1,1,0]
	s_waitcnt vmcnt(16)
	v_pk_add_f32 v[22:23], v[20:21], v[22:23]
	v_pk_add_f32 v[16:17], v[20:21], v[16:17] op_sel:[1,0] op_sel_hi:[0,1]
	v_cvt_pk_bf16_f32 v3, v22, v16
	v_pk_mul_f32 v[16:17], v[10:11], v[16:17] op_sel_hi:[1,0]
	v_lshlrev_b64 v[20:21], 13, v[4:5]
	v_pk_fma_f32 v[30:31], v[0:1], v[22:23], v[16:17] neg_lo:[0,0,1] neg_hi:[0,0,1]
	v_pk_fma_f32 v[16:17], v[0:1], v[22:23], v[16:17] op_sel_hi:[1,0,1]
	v_lshl_add_u64 v[20:21], v[12:13], 0, v[20:21]
	v_mov_b32_e32 v31, v17
	s_waitcnt vmcnt(15)
	v_pk_add_f32 v[16:17], v[28:29], v[30:31]
	global_store_dword v[14:15], v3, off
	v_mul_f32_e32 v4, v1, v17
	v_cvt_pk_bf16_f32 v3, v16, v17
	global_store_dword v[20:21], v3, off
	v_pk_fma_f32 v[20:21], v[0:1], v[16:17], v[4:5] op_sel_hi:[1,1,0] neg_lo:[0,0,1] neg_hi:[0,0,1]
	v_mul_f32_e32 v4, v11, v17
	v_pk_fma_f32 v[16:17], v[10:11], v[16:17], v[4:5] op_sel_hi:[1,1,0]
	s_waitcnt vmcnt(16)
	v_pk_add_f32 v[20:21], v[26:27], v[20:21]
	v_pk_add_f32 v[16:17], v[26:27], v[16:17] op_sel:[1,0] op_sel_hi:[0,1]
	v_cvt_pk_bf16_f32 v3, v20, v16
	v_pk_mul_f32 v[16:17], v[10:11], v[16:17] op_sel_hi:[1,0]
	v_lshlrev_b64 v[22:23], 13, v[24:25]
	v_pk_fma_f32 v[24:25], v[0:1], v[20:21], v[16:17] neg_lo:[0,0,1] neg_hi:[0,0,1]
	v_pk_fma_f32 v[16:17], v[0:1], v[20:21], v[16:17] op_sel_hi:[1,0,1]
	v_lshl_add_u64 v[22:23], v[12:13], 0, v[22:23]
	v_mov_b32_e32 v25, v17
	s_waitcnt vmcnt(12)
	v_pk_add_f32 v[16:17], v[32:33], v[24:25]
	global_store_dword v[22:23], v3, off
	v_mul_f32_e32 v4, v1, v17
	v_pk_fma_f32 v[20:21], v[0:1], v[16:17], v[4:5] op_sel_hi:[1,1,0] neg_lo:[0,0,1] neg_hi:[0,0,1]
	v_mul_f32_e32 v4, v11, v17
	v_lshlrev_b64 v[22:23], 13, v[34:35]
	v_cvt_pk_bf16_f32 v3, v16, v17
	v_pk_fma_f32 v[16:17], v[10:11], v[16:17], v[4:5] op_sel_hi:[1,1,0]
	v_lshl_add_u64 v[22:23], v[12:13], 0, v[22:23]
	v_pk_add_f32 v[16:17], v[38:39], v[16:17] op_sel:[1,0] op_sel_hi:[0,1]
	global_store_dword v[22:23], v3, off
	v_pk_add_f32 v[20:21], v[38:39], v[20:21]
	v_lshlrev_b64 v[22:23], 13, v[36:37]
	v_cvt_pk_bf16_f32 v3, v20, v16
	v_pk_mul_f32 v[16:17], v[10:11], v[16:17] op_sel_hi:[1,0]
	v_lshl_add_u64 v[22:23], v[12:13], 0, v[22:23]
	v_pk_fma_f32 v[24:25], v[0:1], v[20:21], v[16:17] neg_lo:[0,0,1] neg_hi:[0,0,1]
	v_pk_fma_f32 v[16:17], v[0:1], v[20:21], v[16:17] op_sel_hi:[1,0,1]
	global_store_dword v[22:23], v3, off
	v_mov_b32_e32 v25, v17
	s_waitcnt vmcnt(14)
	v_pk_add_f32 v[16:17], v[42:43], v[24:25]
	v_lshlrev_b64 v[22:23], 13, v[44:45]
	v_mul_f32_e32 v4, v1, v17
	v_pk_fma_f32 v[20:21], v[0:1], v[16:17], v[4:5] op_sel_hi:[1,1,0] neg_lo:[0,0,1] neg_hi:[0,0,1]
	v_mul_f32_e32 v4, v11, v17
	v_cvt_pk_bf16_f32 v3, v16, v17
	v_pk_fma_f32 v[16:17], v[10:11], v[16:17], v[4:5] op_sel_hi:[1,1,0]
	v_lshl_add_u64 v[22:23], v[12:13], 0, v[22:23]
	v_pk_add_f32 v[16:17], v[50:51], v[16:17] op_sel:[1,0] op_sel_hi:[0,1]
	global_store_dword v[22:23], v3, off
	v_pk_add_f32 v[20:21], v[50:51], v[20:21]
	v_lshlrev_b64 v[22:23], 13, v[48:49]
	v_cvt_pk_bf16_f32 v3, v20, v16
	v_pk_mul_f32 v[16:17], v[10:11], v[16:17] op_sel_hi:[1,0]
	v_lshl_add_u64 v[22:23], v[12:13], 0, v[22:23]
	v_pk_fma_f32 v[24:25], v[0:1], v[20:21], v[16:17] neg_lo:[0,0,1] neg_hi:[0,0,1]
	v_pk_fma_f32 v[16:17], v[0:1], v[20:21], v[16:17] op_sel_hi:[1,0,1]
	global_store_dword v[22:23], v3, off
	v_mov_b32_e32 v25, v17
	s_waitcnt vmcnt(15)
	v_pk_add_f32 v[16:17], v[52:53], v[24:25]
	v_lshlrev_b64 v[22:23], 13, v[54:55]
	v_mul_f32_e32 v4, v1, v17
	v_pk_fma_f32 v[20:21], v[0:1], v[16:17], v[4:5] op_sel_hi:[1,1,0] neg_lo:[0,0,1] neg_hi:[0,0,1]
	v_mul_f32_e32 v4, v11, v17
	v_cvt_pk_bf16_f32 v3, v16, v17
	v_pk_fma_f32 v[16:17], v[10:11], v[16:17], v[4:5] op_sel_hi:[1,1,0]
	v_lshl_add_u64 v[22:23], v[12:13], 0, v[22:23]
	v_pk_add_f32 v[16:17], v[58:59], v[16:17] op_sel:[1,0] op_sel_hi:[0,1]
	global_store_dword v[22:23], v3, off
	v_pk_add_f32 v[20:21], v[58:59], v[20:21]
	v_lshlrev_b64 v[22:23], 13, v[56:57]
	v_cvt_pk_bf16_f32 v3, v20, v16
	v_pk_mul_f32 v[16:17], v[10:11], v[16:17] op_sel_hi:[1,0]
	v_lshl_add_u64 v[22:23], v[12:13], 0, v[22:23]
	v_pk_fma_f32 v[24:25], v[0:1], v[20:21], v[16:17] neg_lo:[0,0,1] neg_hi:[0,0,1]
	v_pk_fma_f32 v[16:17], v[0:1], v[20:21], v[16:17] op_sel_hi:[1,0,1]
	global_store_dword v[22:23], v3, off
	v_mov_b32_e32 v25, v17
	s_waitcnt vmcnt(16)
	v_pk_add_f32 v[16:17], v[60:61], v[24:25]
	v_lshlrev_b64 v[22:23], 13, v[62:63]
	v_mul_f32_e32 v4, v1, v17
	v_pk_fma_f32 v[20:21], v[0:1], v[16:17], v[4:5] op_sel_hi:[1,1,0] neg_lo:[0,0,1] neg_hi:[0,0,1]
	v_mul_f32_e32 v4, v11, v17
	v_lshl_add_u64 v[22:23], v[12:13], 0, v[22:23]
	v_cvt_pk_bf16_f32 v3, v16, v17
	v_pk_fma_f32 v[16:17], v[10:11], v[16:17], v[4:5] op_sel_hi:[1,1,0]
	global_store_dword v[22:23], v3, off
	s_waitcnt vmcnt(16)
	v_pk_add_f32 v[16:17], v[66:67], v[16:17] op_sel:[1,0] op_sel_hi:[0,1]
	v_lshlrev_b64 v[22:23], 13, v[64:65]
	v_pk_add_f32 v[20:21], v[66:67], v[20:21]
	v_lshl_add_u64 v[22:23], v[12:13], 0, v[22:23]
	v_cvt_pk_bf16_f32 v3, v20, v16
	v_pk_mul_f32 v[16:17], v[10:11], v[16:17] op_sel_hi:[1,0]
	global_store_dword v[22:23], v3, off
	v_pk_fma_f32 v[22:23], v[0:1], v[20:21], v[16:17] neg_lo:[0,0,1] neg_hi:[0,0,1]
	v_pk_fma_f32 v[16:17], v[0:1], v[20:21], v[16:17] op_sel_hi:[1,0,1]
	s_mov_b64 s[12:13], 0x20000
	v_mov_b32_e32 v23, v17
	s_add_i32 s10, s10, 16
	v_lshl_add_u64 v[14:15], v[14:15], 0, s[12:13]
	s_mov_b64 s[12:13], 0x40000
	s_waitcnt vmcnt(16)
	v_pk_add_f32 v[16:17], v[68:69], v[22:23]
	v_lshl_add_u64 v[18:19], v[18:19], 0, s[12:13]
	s_cmpk_gt_u32 s10, 0xef
	s_cbranch_scc0 .LBB0_859
; DI unsigned pk2(float lo, float hi) { unsigned r; asm volatile("v_cvt_pk_bf16_f32 %0, %1, %2" : "=v"(r) : "v"(lo), "v"(hi)); return r; }
; template <int NB> DI void s5_c_steps(const Prm& p, int col, size_t base, float ar, float ai, float& xr, float& xi) {
;     f32x2v xl[NB];
; #pragma unroll
;     for (int i = 0; i < NB; ++i) xl[i] = *(const f32x2v*)(p.XLOC + (size_t)(col + i) * 4096 + base);
; #pragma unroll
;     for (int i = 0; i < NB; ++i) { *(unsigned*)(p.XPREV + (size_t)(col + i) * 4096 + base) = pk2(xr, xi);
;         const float nr = ar * xr - ai * xi + xl[i].x, ni = ar * xi + ai * xr + xl[i].y; xr = nr; xi = ni; }
; }
; DI void s5_c(const Prm& p, int gtid) {
;     if (gtid >= 16 * 2048) return;
;     const int seq = gtid >> 11, g = (gtid >> 6) & 31, n = gtid & 63; const bool smp = seq >= 8; const int b = seq & 7;
;     float xr = 0.f, xi = 0.f; if (smp) { xr = p.ssm_re0[(b * 32 + g) * 64 + n]; xi = p.ssm_im0[(b * 32 + g) * 64 + n]; }
;     const float ar = p.A16[2 * (g * 64 + n)], ai = p.A16[2 * (g * 64 + n) + 1];
;     const size_t base = (size_t)g * 128 + 2 * n;
;     if (smp) s5_c_steps<4>(p, 2056 + 4 * b, base, ar, ai, xr, xi);
;     else { for (int c0 = 0; c0 < 256; c0 += 16) s5_c_steps<16>(p, 257 * b + c0, base, ar, ai, xr, xi); s5_c_steps<1>(p, 257 * b + 256, base, ar, ai, xr, xi); }
	s_mov_b32 s10, 0x101000
	v_mov_b32_e32 v3, 0x100000
	v_mad_u32_u24 v3, v71, s10, v3
	v_readlane_b32 s12, v255, 8
	v_lshlrev_b32_e32 v4, 2, v3
	v_mov_b32_e32 v5, 0
	v_readlane_b32 s16, v255, 12
	v_readlane_b32 s17, v255, 13
	v_mov_b32_e32 v7, v5
	v_readlane_b32 s18, v255, 14
	v_lshl_add_u64 v[8:9], s[16:17], 0, v[4:5]
	v_lshl_add_u64 v[6:7], v[8:9], 0, v[6:7]
	global_load_dwordx2 v[6:7], v[6:7], off nt
	v_readlane_b32 s19, v255, 15
	v_lshlrev_b32_e32 v4, 1, v3
	v_mov_b32_e32 v3, v5
	v_lshl_add_u64 v[8:9], s[18:19], 0, v[4:5]
	v_lshl_add_u64 v[2:3], v[8:9], 0, v[2:3]
	v_cvt_pk_bf16_f32 v12, v16, v17
	global_store_dword v[2:3], v12, off
	v_pk_mul_f32 v[2:3], v[10:11], v[16:17] op_sel:[0,1]
	v_readlane_b32 s13, v255, 9
	v_pk_fma_f32 v[4:5], v[0:1], v[16:17], v[2:3] neg_lo:[0,0,1] neg_hi:[0,0,1]
	v_pk_fma_f32 v[0:1], v[0:1], v[16:17], v[2:3] op_sel_hi:[1,0,1]
	v_readlane_b32 s14, v255, 10
	v_mov_b32_e32 v5, v1
	v_readlane_b32 s15, v255, 11
	v_readlane_b32 s20, v255, 16
	v_readlane_b32 s21, v255, 17
	v_readlane_b32 s22, v255, 18
	v_readlane_b32 s23, v255, 19
	v_readlane_b32 s24, v255, 20
	v_readlane_b32 s25, v255, 21
	v_readlane_b32 s26, v255, 22
	v_readlane_b32 s27, v255, 23
	s_waitcnt vmcnt(1)
	v_pk_add_f32 v[10:11], v[4:5], v[6:7]
.LBB0_861:
	s_or_saveexec_b64 s[0:1], s[0:1]
	v_mov_b64_e32 v[4:5], 0x2180000
	v_mov_b64_e32 v[6:7], 0x2184000
	s_xor_b64 exec, exec, s[0:1]
	s_cbranch_execz .LBB0_863
	v_lshlrev_b32_e32 v3, 14, v71
	v_add_u32_e32 v14, 0x808000, v3
	v_lshlrev_b32_e32 v4, 2, v14
	v_mov_b32_e32 v5, 0
	v_lshl_add_u64 v[6:7], v[8:9], 0, v[4:5]
	global_load_dwordx2 v[6:7], v[6:7], off nt
	v_add_u32_e32 v18, 0x809000, v3
	v_lshlrev_b32_e32 v4, 2, v18
	v_lshl_add_u64 v[10:11], v[8:9], 0, v[4:5]
	global_load_dwordx2 v[10:11], v[10:11], off nt
	v_add_u32_e32 v19, 0x80a000, v3
	v_lshlrev_b32_e32 v4, 2, v19
	v_lshl_add_u64 v[12:13], v[8:9], 0, v[4:5]
	global_load_dwordx2 v[12:13], v[12:13], off nt
	v_add_u32_e32 v20, 0x80b000, v3
	v_lshlrev_b32_e32 v4, 2, v20
	v_lshl_add_u64 v[8:9], v[8:9], 0, v[4:5]
	global_load_dwordx2 v[8:9], v[8:9], off nt
	v_readlane_b32 s12, v255, 8
	v_lshlrev_b32_e32 v4, 1, v14
	v_readlane_b32 s18, v255, 14
	v_readlane_b32 s19, v255, 15
	v_mov_b32_e32 v3, v5
	s_waitcnt vmcnt(5)
	v_cvt_pk_bf16_f32 v21, v16, v17
	v_readlane_b32 s13, v255, 9
	v_lshl_add_u64 v[14:15], s[18:19], 0, v[4:5]
	v_lshl_add_u64 v[14:15], v[14:15], 0, v[2:3]
	s_waitcnt vmcnt(4)
	v_mul_f32_e32 v4, v17, v1
	global_store_dword v[14:15], v21, off
	v_pk_fma_f32 v[14:15], v[16:17], v[0:1], v[4:5] op_sel_hi:[1,1,0] neg_lo:[0,0,1] neg_hi:[0,0,1]
	v_mul_f32_e32 v4, v16, v1
	v_pk_fma_f32 v[16:17], v[16:17], v[0:1], v[4:5] op_sel:[1,0,0] op_sel_hi:[0,1,0]
	v_lshlrev_b32_e32 v4, 1, v18
	v_readlane_b32 s14, v255, 10
	v_readlane_b32 s15, v255, 11
	v_readlane_b32 s16, v255, 12
	v_readlane_b32 s17, v255, 13
	v_readlane_b32 s20, v255, 16
	v_readlane_b32 s21, v255, 17
	v_readlane_b32 s22, v255, 18
	v_readlane_b32 s23, v255, 19
	v_readlane_b32 s24, v255, 20
	v_readlane_b32 s25, v255, 21
	v_readlane_b32 s26, v255, 22
	v_readlane_b32 s27, v255, 23
	s_waitcnt vmcnt(4)
	v_pk_add_f32 v[14:15], v[14:15], v[6:7]
	v_pk_add_f32 v[6:7], v[16:17], v[6:7] op_sel:[0,1] op_sel_hi:[1,0]
	v_lshl_add_u64 v[16:17], s[18:19], 0, v[4:5]
	v_cvt_pk_bf16_f32 v21, v14, v6
	v_pk_mul_f32 v[6:7], v[0:1], v[6:7] op_sel:[1,0] op_sel_hi:[0,0]
	v_lshl_add_u64 v[16:17], v[16:17], 0, v[2:3]
	v_lshlrev_b32_e32 v4, 1, v19
	v_pk_fma_f32 v[18:19], v[0:1], v[14:15], v[6:7] neg_lo:[0,0,1] neg_hi:[0,0,1]
	v_pk_fma_f32 v[6:7], v[0:1], v[14:15], v[6:7] op_sel_hi:[1,0,1]
	global_store_dword v[16:17], v21, off
	v_lshl_add_u64 v[16:17], s[18:19], 0, v[4:5]
	v_mov_b32_e32 v19, v7
	v_lshl_add_u64 v[16:17], v[16:17], 0, v[2:3]
	s_waitcnt vmcnt(4)
	v_pk_add_f32 v[6:7], v[10:11], v[18:19]
	s_nop 0
	v_cvt_pk_bf16_f32 v4, v6, v7
	global_store_dword v[16:17], v4, off
	v_mul_f32_e32 v4, v1, v7
	v_pk_fma_f32 v[10:11], v[0:1], v[6:7], v[4:5] op_sel_hi:[1,1,0] neg_lo:[0,0,1] neg_hi:[0,0,1]
	v_mul_f32_e32 v4, v0, v7
	v_pk_fma_f32 v[6:7], v[0:1], v[6:7], v[4:5] op_sel:[1,0,0] op_sel_hi:[0,1,0]
	v_lshlrev_b32_e32 v4, 1, v20
	v_lshl_add_u64 v[4:5], s[18:19], 0, v[4:5]
	s_waitcnt vmcnt(4)
	v_pk_add_f32 v[6:7], v[12:13], v[6:7] op_sel:[1,0] op_sel_hi:[0,1]
	v_lshl_add_u64 v[2:3], v[4:5], 0, v[2:3]
	v_pk_add_f32 v[10:11], v[12:13], v[10:11]
	s_nop 0
	v_cvt_pk_bf16_f32 v12, v10, v6
	global_store_dword v[2:3], v12, off
	v_pk_mul_f32 v[2:3], v[0:1], v[6:7] op_sel:[1,0] op_sel_hi:[0,0]
	v_pk_fma_f32 v[4:5], v[0:1], v[10:11], v[2:3] neg_lo:[0,0,1] neg_hi:[0,0,1]
	v_pk_fma_f32 v[0:1], v[0:1], v[10:11], v[2:3] op_sel_hi:[1,0,1]
	v_mov_b64_e32 v[6:7], 0x218c000
	v_mov_b32_e32 v5, v1
	s_waitcnt vmcnt(4)
	v_pk_add_f32 v[10:11], v[8:9], v[4:5]
	v_mov_b64_e32 v[4:5], 0x2188000

; DI unsigned pk2(float lo, float hi) { unsigned r; asm volatile("v_cvt_pk_bf16_f32 %0, %1, %2" : "=v"(r) : "v"(lo), "v"(hi)); return r; }
; template <int NB> DI void s5_c_steps(const Prm& p, int col, size_t base, float ar, float ai, float& xr, float& xi) {
;     f32x2v xl[NB];
; #pragma unroll
;     for (int i = 0; i < NB; ++i) xl[i] = *(const f32x2v*)(p.XLOC + (size_t)(col + i) * 4096 + base);
; #pragma unroll
;     for (int i = 0; i < NB; ++i) { *(unsigned*)(p.XPREV + (size_t)(col + i) * 4096 + base) = pk2(xr, xi);
;         const float nr = ar * xr - ai * xi + xl[i].x, ni = ar * xi + ai * xr + xl[i].y; xr = nr; xi = ni; }
; }
; DI void s5_c(const Prm& p, int gtid) {
;     if (gtid >= 16 * 2048) return;
;     const int seq = gtid >> 11, g = (gtid >> 6) & 31, n = gtid & 63; const bool smp = seq >= 8; const int b = seq & 7;
;     float xr = 0.f, xi = 0.f; if (smp) { xr = p.ssm_re0[(b * 32 + g) * 64 + n]; xi = p.ssm_im0[(b * 32 + g) * 64 + n]; }
;     const float ar = p.A16[2 * (g * 64 + n)], ai = p.A16[2 * (g * 64 + n) + 1];
;     const size_t base = (size_t)g * 128 + 2 * n;
;     if (smp) s5_c_steps<4>(p, 2056 + 4 * b, base, ar, ai, xr, xi);
;     else { for (int c0 = 0; c0 < 256; c0 += 16) s5_c_steps<16>(p, 257 * b + c0, base, ar, ai, xr, xi); s5_c_steps<1>(p, 257 * b + 256, base, ar, ai, xr, xi); }
.LBB0_869:
	s_or_b64 exec, exec, s[4:5]
	v_lshlrev_b32_e32 v0, 3, v162
	v_and_b32_e32 v0, 0x3ff8, v0
	global_load_dwordx2 v[0:1], v0, s[40:41] nt
	v_lshlrev_b32_e32 v16, 7, v70
	v_lshlrev_b32_e32 v17, 1, v152
	v_or_b32_e32 v2, v16, v17
	v_readlane_b32 s12, v255, 8
	v_lshlrev_b32_e32 v6, 2, v2
	v_mov_b32_e32 v7, v5
	v_readlane_b32 s16, v255, 12
	v_readlane_b32 s17, v255, 13
	v_lshlrev_b32_e32 v2, 1, v2
	v_readlane_b32 s13, v255, 9
	v_lshl_add_u64 v[8:9], s[16:17], 0, v[6:7]
	v_readlane_b32 s14, v255, 10
	v_readlane_b32 s15, v255, 11
	v_readlane_b32 s18, v255, 14
	v_readlane_b32 s19, v255, 15
	v_readlane_b32 s20, v255, 16
	v_readlane_b32 s21, v255, 17
	v_readlane_b32 s22, v255, 18
	v_readlane_b32 s23, v255, 19
	v_readlane_b32 s24, v255, 20
	v_readlane_b32 s25, v255, 21
	v_readlane_b32 s26, v255, 22
	v_readlane_b32 s27, v255, 23
	s_and_saveexec_b64 s[0:1], vcc
	s_xor_b64 s[0:1], exec, s[0:1]
	s_cbranch_execz .LBB0_873
	v_readlane_b32 s12, v255, 8
	v_mov_b32_e32 v3, v5
	v_readlane_b32 s18, v255, 14
	v_readlane_b32 s19, v255, 15
	v_mul_u32_u24_e32 v7, 0x101, v71
	v_lshlrev_b32_e32 v4, 13, v7
	v_lshl_add_u64 v[12:13], s[18:19], 0, v[2:3]
	v_add_u32_e32 v3, v16, v17
	v_lshlrev_b32_e32 v16, 1, v3
	v_mov_b32_e32 v17, v5
	v_lshl_add_u64 v[16:17], v[4:5], 0, v[16:17]
	v_lshlrev_b32_e32 v4, 14, v7
	v_lshlrev_b32_e32 v18, 2, v3
	v_mov_b32_e32 v19, v5
	v_readlane_b32 s16, v255, 12
	v_readlane_b32 s17, v255, 13
	v_lshl_add_u64 v[16:17], s[18:19], 0, v[16:17]
	s_mov_b64 s[4:5], 0xa000
	v_lshl_add_u64 v[18:19], v[4:5], 0, v[18:19]
	v_lshl_add_u64 v[16:17], v[16:17], 0, s[4:5]
	v_lshl_add_u64 v[18:19], s[16:17], 0, v[18:19]
	s_mov_b64 s[4:5], 0x14000
	s_waitcnt vmcnt(0)
	v_pk_mov_b32 v[10:11], v[0:1], v[0:1] op_sel:[1,0]
	v_lshl_add_u64 v[18:19], v[18:19], 0, s[4:5]
	s_mov_b32 s4, -16
	v_readlane_b32 s13, v255, 9
	v_readlane_b32 s14, v255, 10
	v_readlane_b32 s15, v255, 11
	v_readlane_b32 s20, v255, 16
	v_readlane_b32 s21, v255, 17
	v_readlane_b32 s22, v255, 18
	v_readlane_b32 s23, v255, 19
	v_readlane_b32 s24, v255, 20
	v_readlane_b32 s25, v255, 21
	v_readlane_b32 s26, v255, 22
	v_readlane_b32 s27, v255, 23
.LBB0_871:
	v_add_co_u32_e32 v20, vcc, 0xfffec000, v18
	v_add_u32_e32 v3, s4, v7
	s_nop 0
	v_addc_co_u32_e32 v21, vcc, -1, v19, vcc
	global_load_dwordx2 v[46:47], v[20:21], off nt
	v_add_co_u32_e32 v20, vcc, 0xffff0000, v18
	v_add_u32_e32 v4, 22, v3
	s_nop 0
	v_addc_co_u32_e32 v21, vcc, -1, v19, vcc
	global_load_dwordx2 v[40:41], v[20:21], off nt
	v_add_co_u32_e32 v20, vcc, 0xffff4000, v18
	v_lshlrev_b64 v[24:25], 14, v[4:5]
	s_nop 0
	v_addc_co_u32_e32 v21, vcc, -1, v19, vcc
	global_load_dwordx2 v[30:31], v[20:21], off nt
	v_add_co_u32_e32 v20, vcc, 0xffff8000, v18
	v_add_u32_e32 v34, 24, v3
	s_nop 0
	v_addc_co_u32_e32 v21, vcc, -1, v19, vcc
	global_load_dwordx2 v[22:23], v[20:21], off nt
	v_add_co_u32_e32 v20, vcc, 0xffffc000, v18
	v_mov_b32_e32 v35, v5
	s_nop 0
	v_addc_co_u32_e32 v21, vcc, -1, v19, vcc
	global_load_dwordx2 v[20:21], v[20:21], off nt
	s_nop 0
	global_load_dwordx2 v[28:29], v[18:19], off nt
	v_add_u32_e32 v44, 26, v3
	v_mov_b32_e32 v45, v5
	v_add_u32_e32 v54, 28, v3
	v_mov_b32_e32 v55, v5
	v_lshl_add_u64 v[24:25], v[8:9], 0, v[24:25]
	v_lshlrev_b64 v[36:37], 14, v[34:35]
	v_lshlrev_b64 v[48:49], 14, v[44:45]
	v_lshlrev_b64 v[56:57], 14, v[54:55]
	global_load_dwordx2 v[26:27], v[24:25], off nt
	v_lshl_add_u64 v[36:37], v[8:9], 0, v[36:37]
	v_lshl_add_u64 v[48:49], v[8:9], 0, v[48:49]
	v_lshl_add_u64 v[56:57], v[8:9], 0, v[56:57]
	global_load_dwordx2 v[38:39], v[36:37], off nt
	global_load_dwordx2 v[50:51], v[48:49], off nt
	global_load_dwordx2 v[58:59], v[56:57], off nt
	v_add_u32_e32 v24, 23, v3
	v_mov_b32_e32 v25, v5
	v_lshlrev_b64 v[32:33], 14, v[24:25]
	v_lshl_add_u64 v[32:33], v[8:9], 0, v[32:33]
	global_load_dwordx2 v[32:33], v[32:33], off nt
	v_add_u32_e32 v36, 25, v3
	v_mov_b32_e32 v37, v5
	v_lshlrev_b64 v[42:43], 14, v[36:37]
	v_lshl_add_u64 v[42:43], v[8:9], 0, v[42:43]
	global_load_dwordx2 v[42:43], v[42:43], off nt
	v_add_u32_e32 v48, 27, v3
	v_mov_b32_e32 v49, v5
	v_lshlrev_b64 v[52:53], 14, v[48:49]
	v_lshl_add_u64 v[52:53], v[8:9], 0, v[52:53]
	global_load_dwordx2 v[52:53], v[52:53], off nt
	v_add_u32_e32 v56, 29, v3
	v_mov_b32_e32 v57, v5
	v_lshlrev_b64 v[60:61], 14, v[56:57]
	v_lshl_add_u64 v[60:61], v[8:9], 0, v[60:61]
	global_load_dwordx2 v[60:61], v[60:61], off nt
	v_add_u32_e32 v62, 30, v3
	v_mov_b32_e32 v63, v5
	v_lshlrev_b64 v[64:65], 14, v[62:63]
	v_lshl_add_u64 v[64:65], v[8:9], 0, v[64:65]
	global_load_dwordx2 v[66:67], v[64:65], off nt
	v_add_u32_e32 v64, 31, v3
	v_mov_b32_e32 v65, v5
	v_lshlrev_b64 v[68:69], 14, v[64:65]
	v_lshl_add_u64 v[68:69], v[8:9], 0, v[68:69]
	global_load_dwordx2 v[68:69], v[68:69], off nt
	s_mov_b32 s5, 0xffff6000
	v_add_co_u32_e32 v72, vcc, s5, v16
	v_cvt_pk_bf16_f32 v3, v14, v15
	v_mul_f32_e32 v74, v1, v14
	s_nop 0
	v_addc_co_u32_e32 v73, vcc, -1, v17, vcc
	global_store_dword v[72:73], v3, off
	v_mul_f32_e32 v72, v1, v15
	v_pk_fma_f32 v[72:73], v[0:1], v[14:15], v[72:73] op_sel_hi:[1,1,0] neg_lo:[0,0,1] neg_hi:[0,0,1]
	v_pk_fma_f32 v[14:15], v[0:1], v[14:15], v[74:75] op_sel:[0,1,0] op_sel_hi:[1,0,0]
	s_movk_i32 s5, 0x8000
	s_waitcnt vmcnt(16)
	v_pk_add_f32 v[72:73], v[72:73], v[46:47]
	v_pk_add_f32 v[14:15], v[14:15], v[46:47] op_sel:[0,1] op_sel_hi:[1,0]
	v_add_co_u32_e32 v46, vcc, s5, v16
	v_cvt_pk_bf16_f32 v3, v72, v14
	v_pk_mul_f32 v[14:15], v[10:11], v[14:15] op_sel_hi:[1,0]
	s_nop 0
	v_addc_co_u32_e32 v47, vcc, -1, v17, vcc
	global_store_dword v[46:47], v3, off
	v_pk_fma_f32 v[46:47], v[0:1], v[72:73], v[14:15] neg_lo:[0,0,1] neg_hi:[0,0,1]
	v_pk_fma_f32 v[14:15], v[0:1], v[72:73], v[14:15] op_sel_hi:[1,0,1]
	s_movk_i32 s5, 0xa000
	v_mov_b32_e32 v47, v15
	s_waitcnt vmcnt(16)
; DI unsigned pk2(float lo, float hi) { unsigned r; asm volatile("v_cvt_pk_bf16_f32 %0, %1, %2" : "=v"(r) : "v"(lo), "v"(hi)); return r; }
; template <int NB> DI void s5_c_steps(const Prm& p, int col, size_t base, float ar, float ai, float& xr, float& xi) {
;     f32x2v xl[NB];
; #pragma unroll
;     for (int i = 0; i < NB; ++i) xl[i] = *(const f32x2v*)(p.XLOC + (size_t)(col + i) * 4096 + base);
; #pragma unroll
;     for (int i = 0; i < NB; ++i) { *(unsigned*)(p.XPREV + (size_t)(col + i) * 4096 + base) = pk2(xr, xi);
;         const float nr = ar * xr - ai * xi + xl[i].x, ni = ar * xi + ai * xr + xl[i].y; xr = nr; xi = ni; }
; }
	v_pk_add_f32 v[14:15], v[40:41], v[46:47]
	v_add_co_u32_e32 v40, vcc, s5, v16
	v_cvt_pk_bf16_f32 v3, v14, v15
	v_mul_f32_e32 v46, v11, v15
	s_nop 0
	v_addc_co_u32_e32 v41, vcc, -1, v17, vcc
	global_store_dword v[40:41], v3, off
	v_mul_f32_e32 v40, v1, v15
	v_pk_fma_f32 v[40:41], v[0:1], v[14:15], v[40:41] op_sel_hi:[1,1,0] neg_lo:[0,0,1] neg_hi:[0,0,1]
	v_pk_fma_f32 v[14:15], v[10:11], v[14:15], v[46:47] op_sel_hi:[1,1,0]
	s_movk_i32 s5, 0xc000
	s_waitcnt vmcnt(16)
	v_pk_add_f32 v[40:41], v[30:31], v[40:41]
	v_pk_add_f32 v[14:15], v[30:31], v[14:15] op_sel:[1,0] op_sel_hi:[0,1]
	v_add_co_u32_e32 v30, vcc, s5, v16
	v_cvt_pk_bf16_f32 v3, v40, v14
	v_pk_mul_f32 v[14:15], v[10:11], v[14:15] op_sel_hi:[1,0]
	s_nop 0
	v_addc_co_u32_e32 v31, vcc, -1, v17, vcc
	global_store_dword v[30:31], v3, off
	v_pk_fma_f32 v[30:31], v[0:1], v[40:41], v[14:15] neg_lo:[0,0,1] neg_hi:[0,0,1]
	v_pk_fma_f32 v[14:15], v[0:1], v[40:41], v[14:15] op_sel_hi:[1,0,1]
	s_movk_i32 s5, 0xe000
	v_mov_b32_e32 v31, v15
	s_waitcnt vmcnt(16)
	v_pk_add_f32 v[14:15], v[22:23], v[30:31]
	v_add_co_u32_e32 v22, vcc, s5, v16
	v_cvt_pk_bf16_f32 v3, v14, v15
	v_mul_f32_e32 v30, v11, v15
	s_nop 0
	v_addc_co_u32_e32 v23, vcc, -1, v17, vcc
	global_store_dword v[22:23], v3, off
	v_mul_f32_e32 v22, v1, v15
	v_pk_fma_f32 v[22:23], v[0:1], v[14:15], v[22:23] op_sel_hi:[1,1,0] neg_lo:[0,0,1] neg_hi:[0,0,1]
	v_pk_fma_f32 v[14:15], v[10:11], v[14:15], v[30:31] op_sel_hi:[1,1,0]
	s_waitcnt vmcnt(16)
	v_pk_add_f32 v[22:23], v[20:21], v[22:23]
	v_pk_add_f32 v[14:15], v[20:21], v[14:15] op_sel:[1,0] op_sel_hi:[0,1]
	v_cvt_pk_bf16_f32 v3, v22, v14
	v_pk_mul_f32 v[14:15], v[10:11], v[14:15] op_sel_hi:[1,0]
	v_lshlrev_b64 v[20:21], 13, v[4:5]
	v_pk_fma_f32 v[30:31], v[0:1], v[22:23], v[14:15] neg_lo:[0,0,1] neg_hi:[0,0,1]
	v_pk_fma_f32 v[14:15], v[0:1], v[22:23], v[14:15] op_sel_hi:[1,0,1]
	v_lshl_add_u64 v[20:21], v[12:13], 0, v[20:21]
	v_mov_b32_e32 v31, v15
	s_waitcnt vmcnt(15)
	v_pk_add_f32 v[14:15], v[28:29], v[30:31]
	global_store_dword v[16:17], v3, off
	v_mul_f32_e32 v4, v1, v15
	v_cvt_pk_bf16_f32 v3, v14, v15
	global_store_dword v[20:21], v3, off
	v_pk_fma_f32 v[20:21], v[0:1], v[14:15], v[4:5] op_sel_hi:[1,1,0] neg_lo:[0,0,1] neg_hi:[0,0,1]
	v_mul_f32_e32 v4, v11, v15
	v_pk_fma_f32 v[14:15], v[10:11], v[14:15], v[4:5] op_sel_hi:[1,1,0]
	s_waitcnt vmcnt(16)
	v_pk_add_f32 v[20:21], v[26:27], v[20:21]
	v_pk_add_f32 v[14:15], v[26:27], v[14:15] op_sel:[1,0] op_sel_hi:[0,1]
	v_cvt_pk_bf16_f32 v3, v20, v14
	v_pk_mul_f32 v[14:15], v[10:11], v[14:15] op_sel_hi:[1,0]
	v_lshlrev_b64 v[22:23], 13, v[24:25]
	v_pk_fma_f32 v[24:25], v[0:1], v[20:21], v[14:15] neg_lo:[0,0,1] neg_hi:[0,0,1]
	v_pk_fma_f32 v[14:15], v[0:1], v[20:21], v[14:15] op_sel_hi:[1,0,1]
	v_lshl_add_u64 v[22:23], v[12:13], 0, v[22:23]
	v_mov_b32_e32 v25, v15
	s_waitcnt vmcnt(12)
	v_pk_add_f32 v[14:15], v[32:33], v[24:25]
	global_store_dword v[22:23], v3, off
	v_mul_f32_e32 v4, v1, v15
	v_pk_fma_f32 v[20:21], v[0:1], v[14:15], v[4:5] op_sel_hi:[1,1,0] neg_lo:[0,0,1] neg_hi:[0,0,1]
	v_mul_f32_e32 v4, v11, v15
	v_lshlrev_b64 v[22:23], 13, v[34:35]
	v_cvt_pk_bf16_f32 v3, v14, v15
	v_pk_fma_f32 v[14:15], v[10:11], v[14:15], v[4:5] op_sel_hi:[1,1,0]
	v_lshl_add_u64 v[22:23], v[12:13], 0, v[22:23]
	v_pk_add_f32 v[14:15], v[38:39], v[14:15] op_sel:[1,0] op_sel_hi:[0,1]
	global_store_dword v[22:23], v3, off
	v_pk_add_f32 v[20:21], v[38:39], v[20:21]
	v_lshlrev_b64 v[22:23], 13, v[36:37]
	v_cvt_pk_bf16_f32 v3, v20, v14
	v_pk_mul_f32 v[14:15], v[10:11], v[14:15] op_sel_hi:[1,0]
	v_lshl_add_u64 v[22:23], v[12:13], 0, v[22:23]
	v_pk_fma_f32 v[24:25], v[0:1], v[20:21], v[14:15] neg_lo:[0,0,1] neg_hi:[0,0,1]
	v_pk_fma_f32 v[14:15], v[0:1], v[20:21], v[14:15] op_sel_hi:[1,0,1]
	global_store_dword v[22:23], v3, off
	v_mov_b32_e32 v25, v15
	s_waitcnt vmcnt(14)
	v_pk_add_f32 v[14:15], v[42:43], v[24:25]
	v_lshlrev_b64 v[22:23], 13, v[44:45]
	v_mul_f32_e32 v4, v1, v15
	v_pk_fma_f32 v[20:21], v[0:1], v[14:15], v[4:5] op_sel_hi:[1,1,0] neg_lo:[0,0,1] neg_hi:[0,0,1]
	v_mul_f32_e32 v4, v11, v15
	v_cvt_pk_bf16_f32 v3, v14, v15
	v_pk_fma_f32 v[14:15], v[10:11], v[14:15], v[4:5] op_sel_hi:[1,1,0]
	v_lshl_add_u64 v[22:23], v[12:13], 0, v[22:23]
	v_pk_add_f32 v[14:15], v[50:51], v[14:15] op_sel:[1,0] op_sel_hi:[0,1]
	global_store_dword v[22:23], v3, off
	v_pk_add_f32 v[20:21], v[50:51], v[20:21]
	v_lshlrev_b64 v[22:23], 13, v[48:49]
	v_cvt_pk_bf16_f32 v3, v20, v14
	v_pk_mul_f32 v[14:15], v[10:11], v[14:15] op_sel_hi:[1,0]
	v_lshl_add_u64 v[22:23], v[12:13], 0, v[22:23]
	v_pk_fma_f32 v[24:25], v[0:1], v[20:21], v[14:15] neg_lo:[0,0,1] neg_hi:[0,0,1]
	v_pk_fma_f32 v[14:15], v[0:1], v[20:21], v[14:15] op_sel_hi:[1,0,1]
	global_store_dword v[22:23], v3, off
	v_mov_b32_e32 v25, v15
	s_waitcnt vmcnt(15)
	v_pk_add_f32 v[14:15], v[52:53], v[24:25]
	v_lshlrev_b64 v[22:23], 13, v[54:55]
	v_mul_f32_e32 v4, v1, v15
	v_pk_fma_f32 v[20:21], v[0:1], v[14:15], v[4:5] op_sel_hi:[1,1,0] neg_lo:[0,0,1] neg_hi:[0,0,1]
	v_mul_f32_e32 v4, v11, v15
	v_cvt_pk_bf16_f32 v3, v14, v15
	v_pk_fma_f32 v[14:15], v[10:11], v[14:15], v[4:5] op_sel_hi:[1,1,0]
	v_lshl_add_u64 v[22:23], v[12:13], 0, v[22:23]
	v_pk_add_f32 v[14:15], v[58:59], v[14:15] op_sel:[1,0] op_sel_hi:[0,1]
	global_store_dword v[22:23], v3, off
	v_pk_add_f32 v[20:21], v[58:59], v[20:21]
	v_lshlrev_b64 v[22:23], 13, v[56:57]
	v_cvt_pk_bf16_f32 v3, v20, v14
	v_pk_mul_f32 v[14:15], v[10:11], v[14:15] op_sel_hi:[1,0]
	v_lshl_add_u64 v[22:23], v[12:13], 0, v[22:23]
	v_pk_fma_f32 v[24:25], v[0:1], v[20:21], v[14:15] neg_lo:[0,0,1] neg_hi:[0,0,1]
	v_pk_fma_f32 v[14:15], v[0:1], v[20:21], v[14:15] op_sel_hi:[1,0,1]
	global_store_dword v[22:23], v3, off
	v_mov_b32_e32 v25, v15
	s_waitcnt vmcnt(16)
	v_pk_add_f32 v[14:15], v[60:61], v[24:25]
	v_lshlrev_b64 v[22:23], 13, v[62:63]
	v_mul_f32_e32 v4, v1, v15
	v_pk_fma_f32 v[20:21], v[0:1], v[14:15], v[4:5] op_sel_hi:[1,1,0] neg_lo:[0,0,1] neg_hi:[0,0,1]
	v_mul_f32_e32 v4, v11, v15
	v_lshl_add_u64 v[22:23], v[12:13], 0, v[22:23]
	v_cvt_pk_bf16_f32 v3, v14, v15
	v_pk_fma_f32 v[14:15], v[10:11], v[14:15], v[4:5] op_sel_hi:[1,1,0]
	global_store_dword v[22:23], v3, off
	s_waitcnt vmcnt(16)
	v_pk_add_f32 v[14:15], v[66:67], v[14:15] op_sel:[1,0] op_sel_hi:[0,1]
	v_lshlrev_b64 v[22:23], 13, v[64:65]
	v_pk_add_f32 v[20:21], v[66:67], v[20:21]
	v_lshl_add_u64 v[22:23], v[12:13], 0, v[22:23]
	v_cvt_pk_bf16_f32 v3, v20, v14
	v_pk_mul_f32 v[14:15], v[10:11], v[14:15] op_sel_hi:[1,0]
	global_store_dword v[22:23], v3, off
	v_pk_fma_f32 v[22:23], v[0:1], v[20:21], v[14:15] neg_lo:[0,0,1] neg_hi:[0,0,1]
	v_pk_fma_f32 v[14:15], v[0:1], v[20:21], v[14:15] op_sel_hi:[1,0,1]
	s_mov_b64 s[6:7], 0x20000
	v_mov_b32_e32 v23, v15
	s_add_i32 s4, s4, 16
	v_lshl_add_u64 v[16:17], v[16:17], 0, s[6:7]
	s_mov_b64 s[6:7], 0x40000
	s_waitcnt vmcnt(16)
	v_pk_add_f32 v[14:15], v[68:69], v[22:23]
	v_lshl_add_u64 v[18:19], v[18:19], 0, s[6:7]
	s_cmpk_gt_u32 s4, 0xef
	s_cbranch_scc0 .LBB0_871
; DI unsigned pk2(float lo, float hi) { unsigned r; asm volatile("v_cvt_pk_bf16_f32 %0, %1, %2" : "=v"(r) : "v"(lo), "v"(hi)); return r; }
; template <int NB> DI void s5_c_steps(const Prm& p, int col, size_t base, float ar, float ai, float& xr, float& xi) {
;     f32x2v xl[NB];
; #pragma unroll
;     for (int i = 0; i < NB; ++i) xl[i] = *(const f32x2v*)(p.XLOC + (size_t)(col + i) * 4096 + base);
; #pragma unroll
;     for (int i = 0; i < NB; ++i) { *(unsigned*)(p.XPREV + (size_t)(col + i) * 4096 + base) = pk2(xr, xi);
;         const float nr = ar * xr - ai * xi + xl[i].x, ni = ar * xi + ai * xr + xl[i].y; xr = nr; xi = ni; }
; }
; DI void s5_c(const Prm& p, int gtid) {
;     if (gtid >= 16 * 2048) return;
;     const int seq = gtid >> 11, g = (gtid >> 6) & 31, n = gtid & 63; const bool smp = seq >= 8; const int b = seq & 7;
;     float xr = 0.f, xi = 0.f; if (smp) { xr = p.ssm_re0[(b * 32 + g) * 64 + n]; xi = p.ssm_im0[(b * 32 + g) * 64 + n]; }
;     const float ar = p.A16[2 * (g * 64 + n)], ai = p.A16[2 * (g * 64 + n) + 1];
;     const size_t base = (size_t)g * 128 + 2 * n;
;     if (smp) s5_c_steps<4>(p, 2056 + 4 * b, base, ar, ai, xr, xi);
;     else { for (int c0 = 0; c0 < 256; c0 += 16) s5_c_steps<16>(p, 257 * b + c0, base, ar, ai, xr, xi); s5_c_steps<1>(p, 257 * b + 256, base, ar, ai, xr, xi); }
	s_mov_b32 s4, 0x101000
	v_mov_b32_e32 v3, 0x100000
	v_mad_u32_u24 v3, v71, s4, v3
	v_readlane_b32 s12, v255, 8
	v_lshlrev_b32_e32 v4, 2, v3
	v_mov_b32_e32 v5, 0
	v_readlane_b32 s16, v255, 12
	v_readlane_b32 s17, v255, 13
	v_mov_b32_e32 v7, v5
	v_readlane_b32 s18, v255, 14
	v_lshl_add_u64 v[8:9], s[16:17], 0, v[4:5]
	v_lshl_add_u64 v[6:7], v[8:9], 0, v[6:7]
	global_load_dwordx2 v[6:7], v[6:7], off nt
	v_readlane_b32 s19, v255, 15
	v_lshlrev_b32_e32 v4, 1, v3
	v_mov_b32_e32 v3, v5
	v_lshl_add_u64 v[8:9], s[18:19], 0, v[4:5]
	v_lshl_add_u64 v[2:3], v[8:9], 0, v[2:3]
	v_cvt_pk_bf16_f32 v12, v14, v15
	global_store_dword v[2:3], v12, off
	v_pk_mul_f32 v[2:3], v[10:11], v[14:15] op_sel:[0,1]
	v_readlane_b32 s13, v255, 9
	v_pk_fma_f32 v[4:5], v[0:1], v[14:15], v[2:3] neg_lo:[0,0,1] neg_hi:[0,0,1]
	v_pk_fma_f32 v[0:1], v[0:1], v[14:15], v[2:3] op_sel_hi:[1,0,1]
	v_readlane_b32 s14, v255, 10
	v_mov_b32_e32 v5, v1
	v_readlane_b32 s15, v255, 11
	v_readlane_b32 s20, v255, 16
	v_readlane_b32 s21, v255, 17
	v_readlane_b32 s22, v255, 18
	v_readlane_b32 s23, v255, 19
	v_readlane_b32 s24, v255, 20
	v_readlane_b32 s25, v255, 21
	v_readlane_b32 s26, v255, 22
	v_readlane_b32 s27, v255, 23
	s_waitcnt vmcnt(1)
	v_pk_add_f32 v[10:11], v[4:5], v[6:7]
.LBB0_873:
	s_or_saveexec_b64 s[0:1], s[0:1]
	v_mov_b64_e32 v[4:5], 0x2180000
	v_mov_b64_e32 v[6:7], 0x2184000
	s_xor_b64 exec, exec, s[0:1]
	s_cbranch_execz .LBB0_875
	v_lshlrev_b32_e32 v3, 14, v71
	v_add_u32_e32 v22, 0x808000, v3
	v_lshlrev_b32_e32 v6, 2, v22
	v_mov_b32_e32 v7, 0
	v_lshl_add_u64 v[4:5], v[8:9], 0, v[6:7]
	global_load_dwordx2 v[10:11], v[4:5], off nt
	v_add_u32_e32 v23, 0x809000, v3
	v_lshlrev_b32_e32 v6, 2, v23
	v_lshl_add_u64 v[4:5], v[8:9], 0, v[6:7]
	global_load_dwordx2 v[12:13], v[4:5], off nt
	v_add_u32_e32 v24, 0x80a000, v3
	v_lshlrev_b32_e32 v6, 2, v24
	v_lshl_add_u64 v[4:5], v[8:9], 0, v[6:7]
	global_load_dwordx2 v[16:17], v[4:5], off nt
	v_add_u32_e32 v25, 0x80b000, v3
	v_lshlrev_b32_e32 v6, 2, v25
	v_lshl_add_u64 v[4:5], v[8:9], 0, v[6:7]
	global_load_dwordx2 v[8:9], v[4:5], off nt
	s_waitcnt vmcnt(4)
	v_mul_f32_e32 v6, v15, v1
	v_readlane_b32 s12, v255, 8
	v_mul_f32_e32 v18, v14, v1
	v_pk_fma_f32 v[20:21], v[14:15], v[0:1], v[6:7] op_sel_hi:[1,1,0] neg_lo:[0,0,1] neg_hi:[0,0,1]
	v_lshlrev_b32_e32 v6, 1, v22
	v_readlane_b32 s18, v255, 14
	v_readlane_b32 s19, v255, 15
	v_mov_b32_e32 v3, v7
	v_pk_fma_f32 v[18:19], v[14:15], v[0:1], v[18:19] op_sel:[1,0,0] op_sel_hi:[0,1,0]
	v_cvt_pk_bf16_f32 v26, v14, v15
	v_lshl_add_u64 v[14:15], s[18:19], 0, v[6:7]
	v_lshlrev_b32_e32 v6, 1, v23
	v_lshl_add_u64 v[14:15], v[14:15], 0, v[2:3]
	v_lshl_add_u64 v[22:23], s[18:19], 0, v[6:7]
	v_lshlrev_b32_e32 v6, 1, v24
	global_store_dword v[14:15], v26, off
	v_lshl_add_u64 v[14:15], v[22:23], 0, v[2:3]
	v_lshl_add_u64 v[22:23], s[18:19], 0, v[6:7]
	v_lshlrev_b32_e32 v6, 1, v25
	v_lshl_add_u64 v[6:7], s[18:19], 0, v[6:7]
	v_lshl_add_u64 v[22:23], v[22:23], 0, v[2:3]
	v_lshl_add_u64 v[2:3], v[6:7], 0, v[2:3]
	v_mov_b64_e32 v[4:5], 0x2188000
	v_readlane_b32 s13, v255, 9
	v_readlane_b32 s14, v255, 10
	v_readlane_b32 s15, v255, 11
	v_readlane_b32 s16, v255, 12
	v_readlane_b32 s17, v255, 13
	v_readlane_b32 s20, v255, 16
	v_readlane_b32 s21, v255, 17
	v_readlane_b32 s22, v255, 18
	v_readlane_b32 s23, v255, 19
	v_readlane_b32 s24, v255, 20
	v_readlane_b32 s25, v255, 21
	v_readlane_b32 s26, v255, 22
	v_readlane_b32 s27, v255, 23
	s_waitcnt vmcnt(4)
	v_pk_add_f32 v[6:7], v[20:21], v[10:11]
	v_pk_add_f32 v[10:11], v[18:19], v[10:11] op_sel:[0,1] op_sel_hi:[1,0]
	s_nop 0
	v_cvt_pk_bf16_f32 v18, v6, v10
	v_pk_mul_f32 v[10:11], v[0:1], v[10:11] op_sel:[1,0] op_sel_hi:[0,0]
	global_store_dword v[14:15], v18, off
	v_pk_fma_f32 v[14:15], v[0:1], v[6:7], v[10:11] neg_lo:[0,0,1] neg_hi:[0,0,1]
	v_pk_fma_f32 v[6:7], v[0:1], v[6:7], v[10:11] op_sel_hi:[1,0,1]
	s_nop 0
	v_mov_b32_e32 v15, v7
	s_waitcnt vmcnt(4)
	v_pk_add_f32 v[6:7], v[12:13], v[14:15]
	s_nop 0
	v_cvt_pk_bf16_f32 v11, v6, v7
	v_mul_f32_e32 v10, v1, v7
	v_mul_f32_e32 v12, v0, v7
	global_store_dword v[22:23], v11, off
	v_pk_fma_f32 v[10:11], v[0:1], v[6:7], v[10:11] op_sel_hi:[1,1,0] neg_lo:[0,0,1] neg_hi:[0,0,1]
	v_pk_fma_f32 v[6:7], v[0:1], v[6:7], v[12:13] op_sel:[1,0,0] op_sel_hi:[0,1,0]
	s_waitcnt vmcnt(4)
	v_pk_add_f32 v[6:7], v[16:17], v[6:7] op_sel:[1,0] op_sel_hi:[0,1]
	v_pk_add_f32 v[10:11], v[16:17], v[10:11]
	s_nop 0
	v_cvt_pk_bf16_f32 v12, v10, v6
	v_pk_mul_f32 v[6:7], v[0:1], v[6:7] op_sel:[1,0] op_sel_hi:[0,0]
	global_store_dword v[2:3], v12, off
	v_pk_fma_f32 v[2:3], v[0:1], v[10:11], v[6:7] neg_lo:[0,0,1] neg_hi:[0,0,1]
	v_pk_fma_f32 v[0:1], v[0:1], v[10:11], v[6:7] op_sel_hi:[1,0,1]
	v_mov_b64_e32 v[6:7], 0x218c000
	v_mov_b32_e32 v3, v1
	s_waitcnt vmcnt(4)
	v_pk_add_f32 v[10:11], v[8:9], v[2:3]

; DI unsigned pk2(float lo, float hi) { unsigned r; asm volatile("v_cvt_pk_bf16_f32 %0, %1, %2" : "=v"(r) : "v"(lo), "v"(hi)); return r; }
; DI float bflo(unsigned u) { return __uint_as_float(u << 16); }
; DI float bfhi(unsigned u) { return __uint_as_float(u & 0xffff0000u); }
; template <int NB> DI void hgrn_b2_steps(const Prm& p, int item, int v, int d4, float (&S)[4]) {
;     u32x2 uu[NB]; f32x4 al[NB];
; #pragma unroll
;     for (int i = 0; i < NB; ++i) { uu[i] = *(const u32x2*)(p.UT + (size_t)(item + i) * 16384 + v * 128 + d4); al[i] = *(const f32x4*)(p.AL + (size_t)(item + i) * 128 + d4); }
; #pragma unroll
;     for (int i = 0; i < NB; ++i) { u32x2 o; o.x = pk2(S[0], S[1]); o.y = pk2(S[2], S[3]);
;         *(u32x2*)(p.UT + (size_t)(item + i) * 16384 + v * 128 + d4) = o;
;         S[0] = al[i][0] * S[0] + bflo(uu[i].x); S[1] = al[i][1] * S[1] + bfhi(uu[i].x); S[2] = al[i][2] * S[2] + bflo(uu[i].y); S[3] = al[i][3] * S[3] + bfhi(uu[i].y); }
; }
; DI void hgrn_b2(const Prm& p, int gtid, int GT) {
;     ...
;         else { for (int c0 = 0; c0 < 65; c0 += 13) hgrn_b2_steps<13>(p, bhx * 65 + c0, v, d4, S); }
.LBB0_884:
	v_add_co_u32_e32 v76, vcc, 0x8000, v68
	v_add_u32_e32 v14, s13, v62
	global_load_dwordx2 v[78:79], v[68:69], off nt
	v_addc_co_u32_e32 v77, vcc, 0, v69, vcc
	v_add_u32_e32 v52, 15, v14
	global_load_dwordx4 v[4:7], v[70:71], off offset:-512 nt
	global_load_dwordx4 v[0:3], v[70:71], off nt
	global_load_dwordx2 v[130:131], v[76:77], off nt
	v_lshlrev_b64 v[8:9], 15, v[52:53]
	v_lshlrev_b64 v[10:11], 9, v[52:53]
	v_add_u32_e32 v52, 16, v14
	v_lshl_add_u64 v[122:123], v[64:65], 0, v[8:9]
	v_lshl_add_u64 v[8:9], v[66:67], 0, v[10:11]
	v_lshlrev_b64 v[10:11], 15, v[52:53]
	v_lshlrev_b64 v[12:13], 9, v[52:53]
	v_add_u32_e32 v52, 17, v14
	global_load_dwordx2 v[128:129], v[122:123], off nt
	global_load_dwordx4 v[48:51], v[8:9], off nt
	v_lshl_add_u64 v[106:107], v[64:65], 0, v[10:11]
	v_lshl_add_u64 v[8:9], v[66:67], 0, v[12:13]
	v_lshlrev_b64 v[10:11], 15, v[52:53]
	v_lshlrev_b64 v[12:13], 9, v[52:53]
	v_add_u32_e32 v52, 18, v14
	global_load_dwordx2 v[126:127], v[106:107], off nt
	global_load_dwordx4 v[44:47], v[8:9], off nt
	v_lshl_add_u64 v[102:103], v[64:65], 0, v[10:11]
	v_lshl_add_u64 v[8:9], v[66:67], 0, v[12:13]
	v_lshlrev_b64 v[10:11], 15, v[52:53]
	v_lshlrev_b64 v[12:13], 9, v[52:53]
	v_add_u32_e32 v52, 19, v14
	global_load_dwordx2 v[124:125], v[102:103], off nt
	global_load_dwordx4 v[40:43], v[8:9], off nt
	v_lshl_add_u64 v[94:95], v[64:65], 0, v[10:11]
	v_lshl_add_u64 v[8:9], v[66:67], 0, v[12:13]
	v_lshlrev_b64 v[10:11], 15, v[52:53]
	v_lshlrev_b64 v[12:13], 9, v[52:53]
	v_add_u32_e32 v52, 20, v14
	global_load_dwordx2 v[120:121], v[94:95], off nt
	global_load_dwordx4 v[36:39], v[8:9], off nt
	v_lshl_add_u64 v[100:101], v[64:65], 0, v[10:11]
	v_lshl_add_u64 v[8:9], v[66:67], 0, v[12:13]
	v_lshlrev_b64 v[10:11], 15, v[52:53]
	v_lshlrev_b64 v[12:13], 9, v[52:53]
	v_add_u32_e32 v52, 21, v14
	global_load_dwordx2 v[118:119], v[100:101], off nt
	global_load_dwordx4 v[32:35], v[8:9], off nt
	v_lshl_add_u64 v[96:97], v[64:65], 0, v[10:11]
	v_lshl_add_u64 v[8:9], v[66:67], 0, v[12:13]
	v_lshlrev_b64 v[10:11], 15, v[52:53]
	v_lshlrev_b64 v[12:13], 9, v[52:53]
	v_add_u32_e32 v52, 22, v14
	global_load_dwordx2 v[114:115], v[96:97], off nt
	global_load_dwordx4 v[20:23], v[8:9], off nt
	v_lshl_add_u64 v[90:91], v[64:65], 0, v[10:11]
	v_lshl_add_u64 v[8:9], v[66:67], 0, v[12:13]
	v_lshlrev_b64 v[10:11], 15, v[52:53]
	v_lshlrev_b64 v[12:13], 9, v[52:53]
	v_add_u32_e32 v52, 23, v14
	global_load_dwordx2 v[116:117], v[90:91], off nt
	global_load_dwordx4 v[24:27], v[8:9], off nt
	v_lshl_add_u64 v[84:85], v[64:65], 0, v[10:11]
	v_lshl_add_u64 v[8:9], v[66:67], 0, v[12:13]
	v_lshlrev_b64 v[10:11], 15, v[52:53]
	v_lshlrev_b64 v[12:13], 9, v[52:53]
	v_add_u32_e32 v52, 24, v14
	global_load_dwordx2 v[110:111], v[84:85], off nt
	global_load_dwordx4 v[28:31], v[8:9], off nt
	v_lshl_add_u64 v[86:87], v[64:65], 0, v[10:11]
	v_lshl_add_u64 v[8:9], v[66:67], 0, v[12:13]
	v_lshlrev_b64 v[10:11], 15, v[52:53]
	v_lshlrev_b64 v[12:13], 9, v[52:53]
	v_add_u32_e32 v52, 25, v14
	global_load_dwordx2 v[112:113], v[86:87], off nt
	global_load_dwordx4 v[16:19], v[8:9], off nt
	v_lshl_add_u64 v[88:89], v[64:65], 0, v[10:11]
	v_lshl_add_u64 v[8:9], v[66:67], 0, v[12:13]
	v_lshlrev_b64 v[10:11], 15, v[52:53]
	v_lshlrev_b64 v[98:99], 9, v[52:53]
	global_load_dwordx2 v[108:109], v[88:89], off nt
	global_load_dwordx4 v[12:15], v[8:9], off nt
	v_lshl_add_u64 v[92:93], v[64:65], 0, v[10:11]
	v_lshl_add_u64 v[8:9], v[66:67], 0, v[98:99]
	global_load_dwordx2 v[98:99], v[92:93], off nt
	s_nop 0
	global_load_dwordx4 v[8:11], v[8:9], off nt
	v_cvt_pk_bf16_f32 v80, v80, v81
	v_cvt_pk_bf16_f32 v81, v82, v83
	global_store_dwordx2 v[68:69], v[80:81], off
	s_add_i32 s13, s13, 13
	s_mov_b64 s[14:15], 0x68000
	v_lshl_add_u64 v[70:71], v[70:71], 0, s[6:7]
	s_cmp_lt_u32 s13, 52
	v_lshl_add_u64 v[68:69], v[68:69], 0, s[14:15]
	s_waitcnt vmcnt(26)
	v_lshlrev_b32_e32 v80, 16, v78
	v_and_b32_e32 v81, 0xffff0000, v78
	v_lshlrev_b32_e32 v78, 16, v79
	v_and_b32_e32 v79, 0xffff0000, v79
	s_waitcnt vmcnt(25)
	v_pk_fma_f32 v[4:5], v[72:73], v[4:5], v[80:81]
	v_pk_fma_f32 v[6:7], v[74:75], v[6:7], v[78:79]
	v_cvt_pk_bf16_f32 v72, v4, v5
	s_waitcnt vmcnt(23)
	v_lshlrev_b32_e32 v74, 16, v130
	v_and_b32_e32 v75, 0xffff0000, v130
	v_cvt_pk_bf16_f32 v73, v6, v7
	v_lshlrev_b32_e32 v78, 16, v131
	v_and_b32_e32 v79, 0xffff0000, v131
	v_pk_fma_f32 v[0:1], v[0:1], v[4:5], v[74:75]
	global_store_dwordx2 v[76:77], v[72:73], off
	v_pk_fma_f32 v[2:3], v[2:3], v[6:7], v[78:79]
	v_cvt_pk_bf16_f32 v4, v0, v1
	s_waitcnt vmcnt(23)
	v_lshlrev_b32_e32 v6, 16, v128
	v_cvt_pk_bf16_f32 v5, v2, v3
	v_and_b32_e32 v7, 0xffff0000, v128
	v_lshlrev_b32_e32 v72, 16, v129
	v_and_b32_e32 v73, 0xffff0000, v129
	global_store_dwordx2 v[122:123], v[4:5], off
	s_waitcnt vmcnt(23)
	v_pk_fma_f32 v[0:1], v[48:49], v[0:1], v[6:7]
	s_waitcnt vmcnt(22)
	v_lshlrev_b32_e32 v4, 16, v126
	v_and_b32_e32 v5, 0xffff0000, v126
	v_pk_fma_f32 v[2:3], v[50:51], v[2:3], v[72:73]
	v_lshlrev_b32_e32 v6, 16, v127
	v_and_b32_e32 v7, 0xffff0000, v127
	v_cvt_pk_bf16_f32 v48, v0, v1
	s_waitcnt vmcnt(21)
	v_pk_fma_f32 v[0:1], v[44:45], v[0:1], v[4:5]
	s_waitcnt vmcnt(20)
	v_lshlrev_b32_e32 v4, 16, v124
	v_and_b32_e32 v5, 0xffff0000, v124
	v_cvt_pk_bf16_f32 v49, v2, v3
	v_pk_fma_f32 v[2:3], v[46:47], v[2:3], v[6:7]
	v_lshlrev_b32_e32 v6, 16, v125
	v_and_b32_e32 v7, 0xffff0000, v125
	s_waitcnt vmcnt(19)
	v_pk_fma_f32 v[4:5], v[40:41], v[0:1], v[4:5]
	s_waitcnt vmcnt(18)
; DI unsigned pk2(float lo, float hi) { unsigned r; asm volatile("v_cvt_pk_bf16_f32 %0, %1, %2" : "=v"(r) : "v"(lo), "v"(hi)); return r; }
; DI float bflo(unsigned u) { return __uint_as_float(u << 16); }
; DI float bfhi(unsigned u) { return __uint_as_float(u & 0xffff0000u); }
; template <int NB> DI void hgrn_b2_steps(const Prm& p, int item, int v, int d4, float (&S)[4]) {
;     u32x2 uu[NB]; f32x4 al[NB];
; #pragma unroll
;     for (int i = 0; i < NB; ++i) { uu[i] = *(const u32x2*)(p.UT + (size_t)(item + i) * 16384 + v * 128 + d4); al[i] = *(const f32x4*)(p.AL + (size_t)(item + i) * 128 + d4); }
; #pragma unroll
;     for (int i = 0; i < NB; ++i) { u32x2 o; o.x = pk2(S[0], S[1]); o.y = pk2(S[2], S[3]);
;         *(u32x2*)(p.UT + (size_t)(item + i) * 16384 + v * 128 + d4) = o;
;         S[0] = al[i][0] * S[0] + bflo(uu[i].x); S[1] = al[i][1] * S[1] + bfhi(uu[i].x); S[2] = al[i][2] * S[2] + bflo(uu[i].y); S[3] = al[i][3] * S[3] + bfhi(uu[i].y); }
; }
; DI void hgrn_b2(const Prm& p, int gtid, int GT) {
;     for (int idx = gtid; idx < 64 * 4096; idx += GT) {
;         const int bhx = idx >> 12, e = idx & 4095, v = e >> 5, d4 = (e & 31) * 4; const bool smp = bhx >= 32;
;         float S[4] = {0.f, 0.f, 0.f, 0.f};
;         if (smp) {
; #pragma unroll
;             for (int j = 0; j < 4; ++j) S[j] = p.state_hgrn[((size_t)(bhx - 32) * 128 + d4 + j) * 128 + v];
;             hgrn_b2_steps<1>(p, 2080 + (bhx - 32), v, d4, S); }
	v_lshlrev_b32_e32 v40, 16, v120
	v_and_b32_e32 v41, 0xffff0000, v120
	global_store_dwordx2 v[106:107], v[48:49], off
	v_cvt_pk_bf16_f32 v0, v0, v1
	v_cvt_pk_bf16_f32 v1, v2, v3
	v_pk_fma_f32 v[2:3], v[42:43], v[2:3], v[6:7]
	v_lshlrev_b32_e32 v6, 16, v121
	v_and_b32_e32 v7, 0xffff0000, v121
	s_waitcnt vmcnt(18)
	v_pk_fma_f32 v[36:37], v[36:37], v[4:5], v[40:41]
	s_waitcnt vmcnt(17)
	v_lshlrev_b32_e32 v40, 16, v118
	v_and_b32_e32 v41, 0xffff0000, v118
	global_store_dwordx2 v[102:103], v[0:1], off
	v_cvt_pk_bf16_f32 v0, v4, v5
	v_cvt_pk_bf16_f32 v1, v2, v3
	v_pk_fma_f32 v[2:3], v[38:39], v[2:3], v[6:7]
	v_lshlrev_b32_e32 v4, 16, v119
	v_and_b32_e32 v5, 0xffff0000, v119
	s_waitcnt vmcnt(16)
	v_lshlrev_b32_e32 v6, 16, v114
	v_pk_fma_f32 v[32:33], v[32:33], v[36:37], v[40:41]
	v_and_b32_e32 v7, 0xffff0000, v114
	v_lshlrev_b32_e32 v38, 16, v115
	global_store_dwordx2 v[94:95], v[0:1], off
	v_cvt_pk_bf16_f32 v0, v36, v37
	v_cvt_pk_bf16_f32 v1, v2, v3
	v_pk_fma_f32 v[2:3], v[34:35], v[2:3], v[4:5]
	v_and_b32_e32 v39, 0xffff0000, v115
	global_store_dwordx2 v[100:101], v[0:1], off
	v_cvt_pk_bf16_f32 v0, v32, v33
	v_cvt_pk_bf16_f32 v1, v2, v3
	s_waitcnt vmcnt(16)
	v_lshlrev_b32_e32 v4, 16, v116
	v_and_b32_e32 v5, 0xffff0000, v116
	v_lshlrev_b32_e32 v34, 16, v117
	v_and_b32_e32 v35, 0xffff0000, v117
	v_pk_fma_f32 v[6:7], v[20:21], v[32:33], v[6:7]
	v_pk_fma_f32 v[2:3], v[22:23], v[2:3], v[38:39]
	global_store_dwordx2 v[96:97], v[0:1], off
	v_cvt_pk_bf16_f32 v0, v6, v7
	s_waitcnt vmcnt(16)
	v_pk_fma_f32 v[4:5], v[24:25], v[6:7], v[4:5]
	s_waitcnt vmcnt(15)
	v_lshlrev_b32_e32 v6, 16, v110
	v_and_b32_e32 v7, 0xffff0000, v110
	v_pk_fma_f32 v[20:21], v[26:27], v[2:3], v[34:35]
	v_lshlrev_b32_e32 v22, 16, v111
	v_and_b32_e32 v23, 0xffff0000, v111
	v_cvt_pk_bf16_f32 v1, v2, v3
	s_waitcnt vmcnt(14)
	v_pk_fma_f32 v[2:3], v[28:29], v[4:5], v[6:7]
	s_waitcnt vmcnt(13)
	v_lshlrev_b32_e32 v6, 16, v112
	v_and_b32_e32 v7, 0xffff0000, v112
	v_pk_fma_f32 v[22:23], v[30:31], v[20:21], v[22:23]
	v_lshlrev_b32_e32 v24, 16, v113
	v_and_b32_e32 v25, 0xffff0000, v113
	global_store_dwordx2 v[90:91], v[0:1], off
	v_cvt_pk_bf16_f32 v0, v4, v5
	v_cvt_pk_bf16_f32 v1, v20, v21
	s_waitcnt vmcnt(13)
	v_pk_fma_f32 v[4:5], v[16:17], v[2:3], v[6:7]
	s_waitcnt vmcnt(12)
	v_lshlrev_b32_e32 v6, 16, v108
	v_and_b32_e32 v7, 0xffff0000, v108
	v_pk_fma_f32 v[16:17], v[18:19], v[22:23], v[24:25]
	v_lshlrev_b32_e32 v18, 16, v109
	v_and_b32_e32 v19, 0xffff0000, v109
	global_store_dwordx2 v[84:85], v[0:1], off
	v_cvt_pk_bf16_f32 v0, v2, v3
	v_cvt_pk_bf16_f32 v1, v22, v23
	s_waitcnt vmcnt(12)
	v_pk_fma_f32 v[2:3], v[12:13], v[4:5], v[6:7]
	s_waitcnt vmcnt(11)
	v_lshlrev_b32_e32 v6, 16, v98
	v_and_b32_e32 v7, 0xffff0000, v98
	v_pk_fma_f32 v[12:13], v[14:15], v[16:17], v[18:19]
	global_store_dwordx2 v[86:87], v[0:1], off
	v_cvt_pk_bf16_f32 v0, v4, v5
	v_lshlrev_b32_e32 v4, 16, v99
	v_and_b32_e32 v5, 0xffff0000, v99
	s_waitcnt vmcnt(11)
	v_pk_fma_f32 v[80:81], v[8:9], v[2:3], v[6:7]
	v_pk_fma_f32 v[82:83], v[10:11], v[12:13], v[4:5]
	v_cvt_pk_bf16_f32 v1, v16, v17
	v_mov_b32_e32 v72, v80
	v_mov_b32_e32 v73, v81
	v_mov_b32_e32 v74, v82
	v_mov_b32_e32 v75, v83
	global_store_dwordx2 v[88:89], v[0:1], off
	v_cvt_pk_bf16_f32 v0, v2, v3
	v_cvt_pk_bf16_f32 v1, v12, v13
	global_store_dwordx2 v[92:93], v[0:1], off
	s_cbranch_scc1 .LBB0_884
	v_mov_b32_e32 v61, v53
	v_lshlrev_b64 v[0:1], 16, v[60:61]
.LBB0_886:
	s_or_saveexec_b64 s[10:11], s[10:11]
	v_mov_b64_e32 v[4:5], 0x2080000
	s_xor_b64 exec, exec, s[10:11]
	s_cbranch_execz .LBB0_881
	v_subrev_u32_e32 v0, 32, v60
	v_mov_b32_e32 v1, v53
	v_lshlrev_b64 v[0:1], 16, v[0:1]
	v_lshlrev_b32_e32 v4, 9, v134
	v_mov_b32_e32 v5, v53
	v_lshl_add_u64 v[6:7], v[58:59], 0, v[0:1]
	v_lshl_add_u64 v[4:5], v[6:7], 0, v[4:5]
	v_add_u32_e32 v10, 0x800, v60
	v_mov_b32_e32 v11, v53
	global_load_dword v6, v[4:5], off
	global_load_dword v7, v[4:5], off offset:512
	global_load_dword v8, v[4:5], off offset:1024
	global_load_dword v9, v[4:5], off offset:1536
	v_lshlrev_b64 v[4:5], 15, v[10:11]
	v_lshl_add_u64 v[4:5], v[54:55], 0, v[4:5]
	v_lshl_add_u64 v[4:5], v[4:5], 0, v[52:53]
	v_readlane_b32 s16, v255, 8
	global_load_dwordx2 v[12:13], v[4:5], off nt
	v_lshlrev_b32_e32 v4, 9, v10
	v_mov_b32_e32 v5, v53
	v_readlane_b32 s18, v255, 10
	v_readlane_b32 s19, v255, 11
	v_mov_b32_e32 v3, v53
	v_lshlrev_b32_e32 v10, 15, v10
	v_lshl_add_u64 v[4:5], s[18:19], 0, v[4:5]
	v_lshl_add_u64 v[2:3], v[4:5], 0, v[2:3]
	global_load_dwordx4 v[2:5], v[2:3], off nt
	v_lshl_add_u64 v[10:11], v[54:55], 0, v[10:11]
	v_lshl_add_u64 v[10:11], v[10:11], 0, v[52:53]
	v_readlane_b32 s17, v255, 9
	v_readlane_b32 s20, v255, 12
	v_readlane_b32 s21, v255, 13
	v_readlane_b32 s22, v255, 14
	v_readlane_b32 s23, v255, 15
	v_readlane_b32 s24, v255, 16
	v_readlane_b32 s25, v255, 17
	v_readlane_b32 s26, v255, 18
	v_readlane_b32 s27, v255, 19
	v_readlane_b32 s28, v255, 20
	v_readlane_b32 s29, v255, 21
	v_readlane_b32 s30, v255, 22
	v_readlane_b32 s31, v255, 23
	s_waitcnt vmcnt(4)
	v_cvt_pk_bf16_f32 v14, v6, v7
	s_waitcnt vmcnt(2)
	v_cvt_pk_bf16_f32 v15, v8, v9
	global_store_dwordx2 v[10:11], v[14:15], off
	s_waitcnt vmcnt(2)
	v_lshlrev_b32_e32 v16, 16, v12
	v_and_b32_e32 v17, 0xffff0000, v12
	v_lshlrev_b32_e32 v12, 16, v13
	v_and_b32_e32 v13, 0xffff0000, v13
	s_waitcnt vmcnt(1)
	v_pk_fma_f32 v[80:81], v[6:7], v[2:3], v[16:17]
	v_pk_fma_f32 v[82:83], v[8:9], v[4:5], v[12:13]
	v_mov_b64_e32 v[4:5], 0x2100000
	s_branch .LBB0_881

; template <class Epi> DI void gemm_fixup(int N, int K, const Epi& E, const float* part, int tid) {
;     ...
;     for (int it = blockIdx.x; it < S.ntail * 8; it += gridDim.x) { const int j = it >> 3, ai = (it >> 2) & 1, m = it & 3; Unit u; S.map(S.nwhole * S.G + j, u);
;         f32x4 a4[2][2];
; #pragma unroll
;         for (int b = 0; b < 2; ++b)
; #pragma unroll
;             for (int n = 0; n < 2; ++n) { const f32x4* pp = (const f32x4*)part + ((size_t)(j * S.S) * 32 + (((ai * 2 + b) * 4 + m) * 2 + n)) * 512 + tid;
;                 f32x4 v0 = {0.f, 0.f, 0.f, 0.f}, v1 = v0, v2 = v0, v3 = v0;
;                 for (int sl = 0; sl + 3 < S.S; sl += 4) { v0 += pp[(size_t)sl * 16384]; v1 += pp[(size_t)(sl + 1) * 16384]; v2 += pp[(size_t)(sl + 2) * 16384]; v3 += pp[(size_t)(sl + 3) * 16384]; }
;                 for (int sl = S.S & ~3; sl < S.S; ++sl) v0 += pp[(size_t)sl * 16384];
;                 a4[b][n] = (v0 + v1) + (v2 + v3); }
.LBB0_1404:
	s_mul_i32 s2, s5, s16
	s_bfe_u32 s25, s24, 0x10002
	s_and_b32 s26, s24, 3
	s_ashr_i32 s3, s2, 31
	s_lshl_b64 s[22:23], s[2:3], 18
	s_lshl_b32 s2, s26, 14
	s_lshl_b32 s3, s25, 17
	s_waitcnt lgkmcnt(0)
	v_lshl_add_u64 v[2:3], v[20:21], 0, s[22:23]
	s_or_b32 s18, s3, s2
	v_lshl_add_u64 v[16:17], v[2:3], 0, s[18:19]
	s_and_b64 vcc, exec, s[10:11]
	s_cbranch_vccz .LBB0_1406
	v_add_co_u32_e32 v6, vcc, 0xc0000, v16
	s_nop 1
	v_addc_co_u32_e32 v7, vcc, 0, v17, vcc
	v_add_co_u32_e32 v2, vcc, 0x80000, v16
	s_nop 1
	v_addc_co_u32_e32 v3, vcc, 0, v17, vcc
	v_add_co_u32_e32 v14, vcc, 0x40000, v16
	global_load_dwordx4 v[2:5], v[2:3], off nt
	s_nop 0
	v_addc_co_u32_e32 v15, vcc, 0, v17, vcc
	global_load_dwordx4 v[6:9], v[6:7], off nt
	s_nop 0
	global_load_dwordx4 v[10:13], v[16:17], off nt
	global_load_dwordx4 v[44:47], v[14:15], off nt
	s_waitcnt vmcnt(3)
	v_pk_add_f32 v[38:39], v[4:5], 0 op_sel_hi:[1,0]
	v_pk_add_f32 v[40:41], v[2:3], 0 op_sel_hi:[1,0]
	s_waitcnt vmcnt(2)
	v_pk_add_f32 v[34:35], v[8:9], 0 op_sel_hi:[1,0]
	v_pk_add_f32 v[36:37], v[6:7], 0 op_sel_hi:[1,0]
	s_waitcnt vmcnt(1)
	v_pk_add_f32 v[6:7], v[12:13], 0 op_sel_hi:[1,0]
	s_waitcnt vmcnt(0)
	v_pk_add_f32 v[42:43], v[46:47], 0 op_sel_hi:[1,0]
	v_pk_add_f32 v[32:33], v[44:45], 0 op_sel_hi:[1,0]
	v_pk_add_f32 v[4:5], v[10:11], 0 op_sel_hi:[1,0]
	s_branch .LBB0_1407

; template <class Epi> DI void gemm_fixup(int N, int K, const Epi& E, const float* part, int tid) {
;     ...
;         for (int b = 0; b < 2; ++b)
; #pragma unroll
;             for (int n = 0; n < 2; ++n) { const f32x4* pp = (const f32x4*)part + ((size_t)(j * S.S) * 32 + (((ai * 2 + b) * 4 + m) * 2 + n)) * 512 + tid;
;                 f32x4 v0 = {0.f, 0.f, 0.f, 0.f}, v1 = v0, v2 = v0, v3 = v0;
;                 for (int sl = 0; sl + 3 < S.S; sl += 4) { v0 += pp[(size_t)sl * 16384]; v1 += pp[(size_t)(sl + 1) * 16384]; v2 += pp[(size_t)(sl + 2) * 16384]; v3 += pp[(size_t)(sl + 3) * 16384]; }
;                 for (int sl = S.S & ~3; sl < S.S; ++sl) v0 += pp[(size_t)sl * 16384];
;                 a4[b][n] = (v0 + v1) + (v2 + v3); }
.LBB0_1409:
	global_load_dwordx4 v[8:11], v[2:3], off nt
	s_add_i32 s5, s5, 1
	v_lshl_add_u64 v[2:3], v[2:3], 0, s[20:21]
	s_cmp_ge_i32 s5, s16
	s_waitcnt vmcnt(0)
	v_pk_add_f32 v[6:7], v[6:7], v[10:11]
	v_pk_add_f32 v[4:5], v[4:5], v[8:9]
	s_cbranch_scc0 .LBB0_1409
.LBB0_1410:
	v_cndmask_b32_e64 v1, 0, 1, s[10:11]
	s_ashr_i32 s18, s4, 3
	v_cmp_ne_u32_e64 s[4:5], 1, v1
	s_andn2_b64 vcc, exec, s[10:11]
	s_cbranch_vccnz .LBB0_1412
	v_add_co_u32_e32 v2, vcc, 0xc2000, v16
	s_nop 1
	v_addc_co_u32_e32 v3, vcc, 0, v17, vcc
	v_add_co_u32_e32 v12, vcc, 0x82000, v16
	s_nop 1
	v_addc_co_u32_e32 v13, vcc, 0, v17, vcc
	global_load_dwordx4 v[8:11], v[2:3], off nt
	s_nop 0
	global_load_dwordx4 v[12:15], v[12:13], off nt
	v_add_co_u32_e32 v2, vcc, 0x42000, v16
	s_waitcnt vmcnt(1)
	v_pk_add_f32 v[52:53], v[10:11], 0 op_sel_hi:[1,0]
	v_addc_co_u32_e32 v3, vcc, 0, v17, vcc
	global_load_dwordx4 v[56:59], v[2:3], off nt
	v_add_co_u32_e32 v2, vcc, 0x2000, v16
	v_pk_add_f32 v[54:55], v[8:9], 0 op_sel_hi:[1,0]
	s_nop 0
	v_addc_co_u32_e32 v3, vcc, 0, v17, vcc
	global_load_dwordx4 v[60:63], v[2:3], off nt
	s_waitcnt vmcnt(2)
	v_pk_add_f32 v[46:47], v[14:15], 0 op_sel_hi:[1,0]
	v_pk_add_f32 v[48:49], v[12:13], 0 op_sel_hi:[1,0]
	s_waitcnt vmcnt(1)
	v_pk_add_f32 v[50:51], v[58:59], 0 op_sel_hi:[1,0]
	v_pk_add_f32 v[44:45], v[56:57], 0 op_sel_hi:[1,0]
	s_waitcnt vmcnt(0)
	v_pk_add_f32 v[10:11], v[62:63], 0 op_sel_hi:[1,0]
	v_pk_add_f32 v[8:9], v[60:61], 0 op_sel_hi:[1,0]
	s_and_b64 vcc, exec, s[2:3]
	s_cbranch_vccz .LBB0_1413
	s_branch .LBB0_1415

; template <class Epi> DI void gemm_fixup(int N, int K, const Epi& E, const float* part, int tid) {
;     ...
;         for (int b = 0; b < 2; ++b)
; #pragma unroll
;             for (int n = 0; n < 2; ++n) { const f32x4* pp = (const f32x4*)part + ((size_t)(j * S.S) * 32 + (((ai * 2 + b) * 4 + m) * 2 + n)) * 512 + tid;
;                 f32x4 v0 = {0.f, 0.f, 0.f, 0.f}, v1 = v0, v2 = v0, v3 = v0;
;                 for (int sl = 0; sl + 3 < S.S; sl += 4) { v0 += pp[(size_t)sl * 16384]; v1 += pp[(size_t)(sl + 1) * 16384]; v2 += pp[(size_t)(sl + 2) * 16384]; v3 += pp[(size_t)(sl + 3) * 16384]; }
;                 for (int sl = S.S & ~3; sl < S.S; ++sl) v0 += pp[(size_t)sl * 16384];
;                 a4[b][n] = (v0 + v1) + (v2 + v3); }
.LBB0_1414:
	global_load_dwordx4 v[12:15], v[2:3], off nt
	s_add_i32 s31, s31, 1
	v_lshl_add_u64 v[2:3], v[2:3], 0, s[20:21]
	s_cmp_lt_i32 s31, s16
	s_waitcnt vmcnt(0)
	v_pk_add_f32 v[10:11], v[10:11], v[14:15]
	v_pk_add_f32 v[8:9], v[8:9], v[12:13]
	s_cbranch_scc1 .LBB0_1414
.LBB0_1415:
	s_and_b64 vcc, exec, s[4:5]
	s_cbranch_vccnz .LBB0_1417
	v_add_co_u32_e32 v2, vcc, 0xd0000, v16
	s_nop 1
	v_addc_co_u32_e32 v3, vcc, 0, v17, vcc
	v_add_co_u32_e32 v18, vcc, 0x90000, v16
	s_nop 1
	v_addc_co_u32_e32 v19, vcc, 0, v17, vcc
	global_load_dwordx4 v[12:15], v[2:3], off nt
	global_load_dwordx4 v[56:59], v[18:19], off nt
	v_add_co_u32_e32 v2, vcc, 0x50000, v16
	s_waitcnt vmcnt(1)
	v_pk_add_f32 v[64:65], v[14:15], 0 op_sel_hi:[1,0]
	v_addc_co_u32_e32 v3, vcc, 0, v17, vcc
	global_load_dwordx4 v[68:71], v[2:3], off nt
	v_add_co_u32_e32 v2, vcc, 0x10000, v16
	v_pk_add_f32 v[66:67], v[12:13], 0 op_sel_hi:[1,0]
	s_nop 0
	v_addc_co_u32_e32 v3, vcc, 0, v17, vcc
	global_load_dwordx4 v[72:75], v[2:3], off nt
	s_waitcnt vmcnt(2)
	v_pk_add_f32 v[58:59], v[58:59], 0 op_sel_hi:[1,0]
	v_pk_add_f32 v[60:61], v[56:57], 0 op_sel_hi:[1,0]
	s_waitcnt vmcnt(1)
	v_pk_add_f32 v[62:63], v[70:71], 0 op_sel_hi:[1,0]
	v_pk_add_f32 v[56:57], v[68:69], 0 op_sel_hi:[1,0]
	s_waitcnt vmcnt(0)
	v_pk_add_f32 v[14:15], v[74:75], 0 op_sel_hi:[1,0]
	v_pk_add_f32 v[12:13], v[72:73], 0 op_sel_hi:[1,0]
	s_and_b64 vcc, exec, s[2:3]
	s_cbranch_vccz .LBB0_1418
	s_branch .LBB0_1420

; template <class Epi> DI void gemm_fixup(int N, int K, const Epi& E, const float* part, int tid) {
;     ...
;         for (int b = 0; b < 2; ++b)
; #pragma unroll
;             for (int n = 0; n < 2; ++n) { const f32x4* pp = (const f32x4*)part + ((size_t)(j * S.S) * 32 + (((ai * 2 + b) * 4 + m) * 2 + n)) * 512 + tid;
;                 f32x4 v0 = {0.f, 0.f, 0.f, 0.f}, v1 = v0, v2 = v0, v3 = v0;
;                 for (int sl = 0; sl + 3 < S.S; sl += 4) { v0 += pp[(size_t)sl * 16384]; v1 += pp[(size_t)(sl + 1) * 16384]; v2 += pp[(size_t)(sl + 2) * 16384]; v3 += pp[(size_t)(sl + 3) * 16384]; }
;                 for (int sl = S.S & ~3; sl < S.S; ++sl) v0 += pp[(size_t)sl * 16384];
;                 a4[b][n] = (v0 + v1) + (v2 + v3); }
.LBB0_1419:
	global_load_dwordx4 v[68:71], v[2:3], off nt
	s_add_i32 s31, s31, 1
	v_lshl_add_u64 v[2:3], v[2:3], 0, s[20:21]
	s_cmp_lt_i32 s31, s16
	s_waitcnt vmcnt(0)
	v_pk_add_f32 v[14:15], v[14:15], v[70:71]
	v_pk_add_f32 v[12:13], v[12:13], v[68:69]
	s_cbranch_scc1 .LBB0_1419
.LBB0_1420:
	s_and_b64 vcc, exec, s[4:5]
	s_cbranch_vccnz .LBB0_1422
	v_add_co_u32_e32 v2, vcc, 0xd2000, v16
	s_nop 1
	v_addc_co_u32_e32 v3, vcc, 0, v17, vcc
	v_add_co_u32_e32 v18, vcc, 0x92000, v16
	s_nop 1
	v_addc_co_u32_e32 v19, vcc, 0, v17, vcc
	global_load_dwordx4 v[68:71], v[2:3], off nt
	global_load_dwordx4 v[84:87], v[18:19], off nt
	v_add_co_u32_e32 v2, vcc, 0x52000, v16
	s_waitcnt vmcnt(1)
	v_pk_add_f32 v[74:75], v[70:71], 0 op_sel_hi:[1,0]
	v_addc_co_u32_e32 v3, vcc, 0, v17, vcc
	global_load_dwordx4 v[88:91], v[2:3], off nt
	v_add_co_u32_e32 v2, vcc, 0x12000, v16
	v_pk_add_f32 v[76:77], v[68:69], 0 op_sel_hi:[1,0]
	s_nop 0
	v_addc_co_u32_e32 v3, vcc, 0, v17, vcc
	global_load_dwordx4 v[16:19], v[2:3], off nt
	s_waitcnt vmcnt(2)
	v_pk_add_f32 v[2:3], v[86:87], 0 op_sel_hi:[1,0]
	v_pk_add_f32 v[70:71], v[84:85], 0 op_sel_hi:[1,0]
	s_waitcnt vmcnt(1)
	v_pk_add_f32 v[72:73], v[90:91], 0 op_sel_hi:[1,0]
	v_pk_add_f32 v[68:69], v[88:89], 0 op_sel_hi:[1,0]
	s_waitcnt vmcnt(0)
	v_pk_add_f32 v[18:19], v[18:19], 0 op_sel_hi:[1,0]
	v_pk_add_f32 v[16:17], v[16:17], 0 op_sel_hi:[1,0]
	s_and_b64 vcc, exec, s[2:3]
	s_cbranch_vccz .LBB0_1423
	s_branch .LBB0_1425

; DI unsigned pk2(float lo, float hi) { unsigned r; asm volatile("v_cvt_pk_bf16_f32 %0, %1, %2" : "=v"(r) : "v"(lo), "v"(hi)); return r; }
; DI float bflo(unsigned u) { return __uint_as_float(u << 16); }
;     DI float upd(u32x4v* px, const u32x4v x, const f32x4 v0, const f32x4 v1) const {
;         u32x4v o; o.x = pk2(bflo(x.x) + v0[0], bfhi(x.x) + v0[1]); o.y = pk2(bflo(x.y) + v0[2], bfhi(x.y) + v0[3]);
;         o.z = pk2(bflo(x.z) + v1[0], bfhi(x.z) + v1[1]); o.w = pk2(bflo(x.w) + v1[2], bfhi(x.w) + v1[3]); *px = o;
;         const float a0 = bflo(o.x), a1 = bfhi(o.x), a2 = bflo(o.y), a3 = bfhi(o.y), a4 = bflo(o.z), a5 = bfhi(o.z), a6 = bflo(o.w), a7 = bfhi(o.w);
;         return ((a0 * a0 + a1 * a1) + (a2 * a2 + a3 * a3)) + ((a4 * a4 + a5 * a5) + (a6 * a6 + a7 * a7));
;     }
;     DI void row(const f32x4 (&a4)[2][2], const Unit& u, int ai, int m, int wr, int wc, int fr, int fq) const {
;         const int cb = u.pn * 256 + wc * 32 + 8 * fq, row = u.pm * 256 + wr * 64 + fr + ai * 128 + m * 16;
;         u32x4v* p0 = (u32x4v*)(XB + (size_t)row * 1024 + cb); u32x4v* p1 = (u32x4v*)(XB + (size_t)row * 1024 + cb + 128);
;         const u32x4v x0 = *p0, x1 = *p1;
;         float ss = upd(p0, x0, a4[0][0], a4[0][1]) + upd(p1, x1, a4[1][0], a4[1][1]);
;         ss += __shfl_xor(ss, 16); ss += __shfl_xor(ss, 32);
;         if (fq == 0) SSQ[(size_t)row * 16 + u.pn * 4 + wc] = ss;
;     }
; template <class Epi> DI void gemm_fixup(int N, int K, const Epi& E, const float* part, int tid) {
;     ...
;     for (int it = blockIdx.x; it < S.ntail * 8; it += gridDim.x) { const int j = it >> 3, ai = (it >> 2) & 1, m = it & 3; Unit u; S.map(S.nwhole * S.G + j, u);
;         f32x4 a4[2][2];
; #pragma unroll
;         for (int b = 0; b < 2; ++b)
; #pragma unroll
;             for (int n = 0; n < 2; ++n) { const f32x4* pp = (const f32x4*)part + ((size_t)(j * S.S) * 32 + (((ai * 2 + b) * 4 + m) * 2 + n)) * 512 + tid;
;                 f32x4 v0 = {0.f, 0.f, 0.f, 0.f}, v1 = v0, v2 = v0, v3 = v0;
;                 for (int sl = 0; sl + 3 < S.S; sl += 4) { v0 += pp[(size_t)sl * 16384]; v1 += pp[(size_t)(sl + 1) * 16384]; v2 += pp[(size_t)(sl + 2) * 16384]; v3 += pp[(size_t)(sl + 3) * 16384]; }
;                 for (int sl = S.S & ~3; sl < S.S; ++sl) v0 += pp[(size_t)sl * 16384];
;                 a4[b][n] = (v0 + v1) + (v2 + v3); }
;         E.row(a4, u, ai, m, wr, wc, fr, fq); }
.LBB0_1424:
	global_load_dwordx4 v[84:87], v[78:79], off nt
	s_add_i32 s2, s2, 1
	v_lshl_add_u64 v[78:79], v[78:79], 0, s[20:21]
	s_cmp_lt_i32 s2, s16
	s_waitcnt vmcnt(0)
	v_pk_add_f32 v[18:19], v[18:19], v[86:87]
	v_pk_add_f32 v[16:17], v[16:17], v[84:85]
	s_cbranch_scc1 .LBB0_1424
.LBB0_1425:
	s_add_i32 s2, s27, s18
	s_ashr_i32 s3, s2, 31
	s_lshr_b32 s3, s3, 27
	s_add_i32 s3, s2, s3
	s_ashr_i32 s4, s3, 5
	s_lshl_b32 s5, s4, 3
	s_sub_i32 s4, 0x83, s5
	s_min_i32 s18, s4, 8
	s_abs_i32 s4, s18
	v_cvt_f32_u32_e32 v1, s4
	s_sub_i32 s23, 0, s4
	s_andn2_b32 s3, s3, 31
	s_sub_i32 s2, s2, s3
	v_rcp_iflag_f32_e32 v1, v1
	s_abs_i32 s3, s2
	s_xor_b32 s22, s2, s18
	s_ashr_i32 s22, s22, 31
	v_mul_f32_e32 v1, 0x4f7ffffe, v1
	v_cvt_u32_f32_e32 v1, v1
	v_pk_add_f32 v[14:15], v[62:63], v[14:15]
	v_pk_add_f32 v[12:13], v[56:57], v[12:13]
	v_pk_add_f32 v[56:57], v[60:61], v[66:67]
	v_readfirstlane_b32 s27, v1
	s_mul_i32 s23, s23, s27
	s_mul_hi_u32 s23, s27, s23
	s_add_i32 s27, s27, s23
	s_mul_hi_u32 s23, s3, s27
	s_mul_i32 s27, s23, s4
	s_sub_i32 s3, s3, s27
	s_add_i32 s29, s23, 1
	s_sub_i32 s27, s3, s4
	s_cmp_ge_u32 s3, s4
	s_cselect_b32 s23, s29, s23
	s_cselect_b32 s3, s27, s3
	s_add_i32 s27, s23, 1
	s_cmp_ge_u32 s3, s4
	s_cselect_b32 s3, s27, s23
	s_xor_b32 s3, s3, s22
	s_sub_i32 s4, s3, s22
	s_mul_i32 s3, s4, s18
	s_sub_i32 s2, s2, s3
	s_add_i32 s5, s5, s2
	s_lshl_b32 s2, s5, 8
	s_lshl_b32 s3, s25, 7
	v_lshl_or_b32 v1, s26, 4, v81
	s_or_b32 s2, s2, s3
	v_add_u32_e32 v78, s2, v1
	v_ashrrev_i32_e32 v79, 31, v78
	v_lshl_or_b32 v84, s4, 8, v80
	v_lshlrev_b64 v[86:87], 11, v[78:79]
	v_lshl_add_u64 v[86:87], s[48:49], 0, v[86:87]
	v_ashrrev_i32_e32 v85, 31, v84
	v_lshl_add_u64 v[92:93], v[84:85], 1, v[86:87]
	global_load_dwordx4 v[84:87], v[92:93], off nt
	global_load_dwordx4 v[88:91], v[92:93], off offset:256 nt
	v_pk_add_f32 v[58:59], v[58:59], v[64:65]
	v_pk_add_f32 v[10:11], v[50:51], v[10:11]
	v_pk_add_f32 v[8:9], v[44:45], v[8:9]
	v_pk_add_f32 v[44:45], v[48:49], v[54:55]
	v_pk_add_f32 v[46:47], v[46:47], v[52:53]
	v_pk_add_f32 v[6:7], v[42:43], v[6:7]
	v_pk_add_f32 v[4:5], v[32:33], v[4:5]
	v_pk_add_f32 v[32:33], v[40:41], v[36:37]
	v_pk_add_f32 v[34:35], v[38:39], v[34:35]
	v_pk_add_f32 v[18:19], v[72:73], v[18:19]
	v_pk_add_f32 v[16:17], v[68:69], v[16:17]
	v_pk_add_f32 v[36:37], v[70:71], v[76:77]
	v_pk_add_f32 v[2:3], v[2:3], v[74:75]
	v_pk_add_f32 v[14:15], v[58:59], v[14:15]
	v_pk_add_f32 v[12:13], v[56:57], v[12:13]
	v_pk_add_f32 v[10:11], v[46:47], v[10:11]
	v_pk_add_f32 v[8:9], v[44:45], v[8:9]
	v_pk_add_f32 v[6:7], v[34:35], v[6:7]
	v_pk_add_f32 v[4:5], v[32:33], v[4:5]
	v_pk_add_f32 v[2:3], v[2:3], v[18:19]
	v_pk_add_f32 v[16:17], v[36:37], v[16:17]
	s_waitcnt vmcnt(1)
	v_lshlrev_b32_e32 v1, 16, v84
	v_and_b32_e32 v18, 0xffff0000, v84
	v_lshlrev_b32_e32 v19, 16, v85
	v_and_b32_e32 v31, 0xffff0000, v85
	v_lshlrev_b32_e32 v32, 16, v86
	v_and_b32_e32 v33, 0xffff0000, v86
	v_lshlrev_b32_e32 v34, 16, v87
	v_and_b32_e32 v35, 0xffff0000, v87
	s_waitcnt vmcnt(0)
	v_lshlrev_b32_e32 v36, 16, v88
	v_and_b32_e32 v37, 0xffff0000, v88
	v_lshlrev_b32_e32 v38, 16, v89
	v_and_b32_e32 v39, 0xffff0000, v89
	v_lshlrev_b32_e32 v40, 16, v90
	v_and_b32_e32 v41, 0xffff0000, v90
	v_lshlrev_b32_e32 v42, 16, v91
	v_and_b32_e32 v43, 0xffff0000, v91
	v_add_f32_e32 v1, v4, v1
	v_add_f32_e32 v4, v5, v18
	v_add_f32_e32 v5, v6, v19
	v_add_f32_e32 v6, v7, v31
	v_add_f32_e32 v7, v8, v32
	v_add_f32_e32 v8, v9, v33
	v_add_f32_e32 v9, v10, v34
	v_add_f32_e32 v10, v11, v35
	v_add_f32_e32 v11, v12, v36
	v_add_f32_e32 v12, v13, v37
	v_add_f32_e32 v13, v14, v38
	v_add_f32_e32 v14, v15, v39
	v_add_f32_e32 v15, v16, v40
	v_add_f32_e32 v16, v17, v41
	v_add_f32_e32 v17, v2, v42
	v_add_f32_e32 v18, v3, v43
	v_cvt_pk_bf16_f32 v2, v1, v4
	v_cvt_pk_bf16_f32 v3, v5, v6
	v_cvt_pk_bf16_f32 v4, v7, v8
	v_cvt_pk_bf16_f32 v5, v9, v10
	global_store_dwordx4 v[92:93], v[2:5], off
	v_lshlrev_b32_e32 v1, 16, v2
	v_lshlrev_b32_e32 v7, 16, v3
	v_and_b32_e32 v2, 0xffff0000, v2
	v_and_b32_e32 v3, 0xffff0000, v3
	v_and_b32_e32 v9, 0xffff0000, v4
	v_and_b32_e32 v19, 0xffff0000, v5
	v_lshlrev_b32_e32 v8, 16, v4
	v_lshlrev_b32_e32 v10, 16, v5
	v_cvt_pk_bf16_f32 v4, v11, v12
	v_mul_f32_e32 v2, v2, v2
	v_mul_f32_e32 v3, v3, v3
	v_mul_f32_e32 v9, v9, v9
	v_mul_f32_e32 v11, v19, v19
	v_fmac_f32_e32 v2, v1, v1
	v_fmac_f32_e32 v3, v7, v7
	v_fmac_f32_e32 v9, v8, v8
	v_fmac_f32_e32 v11, v10, v10
	v_add_f32_e32 v1, v2, v3
	v_add_f32_e32 v2, v9, v11
	v_and_b32_e32 v3, 0xffff0000, v4
	v_cvt_pk_bf16_f32 v5, v13, v14
	v_add_f32_e32 v1, v1, v2
	v_lshlrev_b32_e32 v2, 16, v4
	v_and_b32_e32 v9, 0xffff0000, v5
	v_mul_f32_e32 v3, v3, v3
	v_lshlrev_b32_e32 v8, 16, v5
	v_fmac_f32_e32 v3, v2, v2
	v_mul_f32_e32 v2, v9, v9
	v_cvt_pk_bf16_f32 v6, v15, v16
	v_cvt_pk_bf16_f32 v7, v17, v18
	v_fmac_f32_e32 v2, v8, v8
	v_and_b32_e32 v11, 0xffff0000, v6
	v_and_b32_e32 v13, 0xffff0000, v7
	v_lshlrev_b32_e32 v10, 16, v6
	v_lshlrev_b32_e32 v12, 16, v7
	v_add_f32_e32 v2, v3, v2
	v_mul_f32_e32 v3, v11, v11
	v_mul_f32_e32 v8, v13, v13
	v_fmac_f32_e32 v3, v10, v10
	v_fmac_f32_e32 v8, v12, v12
	v_add_f32_e32 v3, v3, v8
	v_add_f32_e32 v2, v2, v3
	v_and_b32_e32 v3, 64, v82
	v_add_f32_e32 v1, v1, v2
	v_xor_b32_e32 v2, 16, v82
	v_add_u32_e32 v3, 64, v3
	v_cmp_lt_i32_e32 vcc, v2, v3
	global_store_dwordx4 v[92:93], v[4:7], off offset:256
	s_nop 0
	v_cndmask_b32_e32 v2, v82, v2, vcc
	v_lshlrev_b32_e32 v2, 2, v2
	ds_bpermute_b32 v2, v2, v1
	s_waitcnt lgkmcnt(0)
	v_add_f32_e32 v1, v1, v2
	v_xor_b32_e32 v2, 32, v82
	v_cmp_lt_i32_e32 vcc, v2, v3
	s_nop 1
	v_cndmask_b32_e32 v2, v82, v2, vcc
	v_lshlrev_b32_e32 v2, 2, v2
	ds_bpermute_b32 v2, v2, v1
	s_and_saveexec_b64 s[2:3], s[0:1]
	s_xor_b64 s[2:3], exec, s[2:3]
	s_cbranch_execz .LBB0_1399
	s_waitcnt lgkmcnt(0)
	v_add_f32_e32 v1, v1, v2
	s_lshl_b32 s4, s4, 2
	v_lshlrev_b64 v[2:3], 6, v[78:79]
	s_ashr_i32 s5, s4, 31
	v_lshl_add_u64 v[2:3], s[50:51], 0, v[2:3]
	v_lshl_add_u64 v[2:3], s[4:5], 2, v[2:3]
	v_mov_b32_e32 v31, v0
	v_lshl_add_u64 v[2:3], v[2:3], 0, v[30:31]
	global_store_dword v[2:3], v1, off
	s_branch .LBB0_1399

; DI void rinv_pass(const Prm& p, int K, int tid) {
;     SplitOrder S; S.init2(1024, K);
;     for (int pm = blockIdx.x; pm < MP / 256; pm += gridDim.x) {
;         bool tail = false;
;         if (S.S) for (int j = 0; j < S.ntail; ++j) { Unit u; S.map(S.nwhole * S.G + j, u); tail = tail || (u.pm == pm); }
;         if (tid < 256) { const int row = pm * 256 + tid; float v = -1.f;
;             if (!tail) { const f32x4* q = (const f32x4*)(p.SSQ + (size_t)row * 16); const f32x4 a = q[0] + q[1] + q[2] + q[3]; v = rsqrtf(((a.x + a.y) + (a.z + a.w)) * (1.f / 1024.f) + EPSN); }
;             if (row >= NT) v = 1.f;
;             p.RINV[row] = v; }
;     }
; }
.LBB0_1446:
	s_and_saveexec_b64 s[10:11], s[0:1]
	s_cbranch_execz .LBB0_1438
	v_lshl_or_b32 v0, s14, 8, v154
	s_xor_b64 s[8:9], s[8:9], -1
	v_ashrrev_i32_e32 v1, 31, v0
	s_andn2_b64 vcc, exec, s[8:9]
	v_mov_b32_e32 v3, -1.0
	s_cbranch_vccnz .LBB0_1437
	v_lshlrev_b64 v[4:5], 6, v[0:1]
	v_lshl_add_u64 v[16:17], s[50:51], 0, v[4:5]
	global_load_dwordx4 v[4:7], v[16:17], off nt
	global_load_dwordx4 v[8:11], v[16:17], off offset:16 nt
	global_load_dwordx4 v[12:15], v[16:17], off offset:32 nt
	s_nop 0
	global_load_dwordx4 v[16:19], v[16:17], off offset:48 nt
	s_waitcnt vmcnt(2)
	v_pk_add_f32 v[6:7], v[6:7], v[10:11]
	v_pk_add_f32 v[4:5], v[4:5], v[8:9]
	s_waitcnt vmcnt(1)
	v_pk_add_f32 v[6:7], v[6:7], v[14:15]
	v_pk_add_f32 v[4:5], v[4:5], v[12:13]
	s_waitcnt vmcnt(0)
	v_pk_add_f32 v[6:7], v[6:7], v[18:19]
	v_pk_add_f32 v[4:5], v[4:5], v[16:17]
	s_nop 0
	v_pk_mov_b32 v[8:9], v[4:5], v[6:7] op_sel:[1,0]
	v_mov_b32_e32 v5, v7
	v_pk_add_f32 v[4:5], v[8:9], v[4:5]
	s_nop 0
	v_add_f32_e32 v3, v4, v5
	v_fmamk_f32 v3, v3, 0x3a800000, v2
	v_mul_f32_e32 v4, 0x4b800000, v3
	v_cmp_gt_f32_e32 vcc, s2, v3
	s_nop 1
	v_cndmask_b32_e32 v3, v3, v4, vcc
	v_rsq_f32_e32 v3, v3
	s_nop 0
	v_mul_f32_e32 v4, 0x45800000, v3
	v_cndmask_b32_e32 v3, v3, v4, vcc
	s_branch .LBB0_1437

; template <class Epi> DI void gemm_fixup(int N, int K, const Epi& E, const float* part, int tid) {
;     ...
;         for (int b = 0; b < 2; ++b)
; #pragma unroll
;             for (int n = 0; n < 2; ++n) { const f32x4* pp = (const f32x4*)part + ((size_t)(j * S.S) * 32 + (((ai * 2 + b) * 4 + m) * 2 + n)) * 512 + tid;
;                 f32x4 v0 = {0.f, 0.f, 0.f, 0.f}, v1 = v0, v2 = v0, v3 = v0;
;                 for (int sl = 0; sl + 3 < S.S; sl += 4) { v0 += pp[(size_t)sl * 16384]; v1 += pp[(size_t)(sl + 1) * 16384]; v2 += pp[(size_t)(sl + 2) * 16384]; v3 += pp[(size_t)(sl + 3) * 16384]; }
;                 for (int sl = S.S & ~3; sl < S.S; ++sl) v0 += pp[(size_t)sl * 16384];
;                 a4[b][n] = (v0 + v1) + (v2 + v3); }
.LBB0_1727:
	s_and_b32 s8, s16, 3
	s_lshl_b32 s9, s17, 15
	s_and_b32 s9, s9, 0x20000
	s_lshl_b32 s8, s8, 14
	s_or_b32 s19, s9, s8
	s_mul_i32 s8, s25, s2
	s_ashr_i32 s9, s8, 31
	s_and_b64 vcc, exec, s[6:7]
	s_lshl_b64 s[26:27], s[8:9], 18
	s_cbranch_vccnz .LBB0_1730
	s_add_u32 s8, s26, s19
	s_addc_u32 s9, s27, 0
	v_mov_b32_e32 v38, 0
	v_lshl_add_u64 v[2:3], v[20:21], 0, s[8:9]
	s_mov_b32 s8, 3
	v_mov_b32_e32 v39, v38
	v_mov_b32_e32 v40, v38
	v_mov_b32_e32 v41, v38
	v_mov_b32_e32 v44, v38
	v_mov_b32_e32 v45, v38
	v_mov_b32_e32 v42, v38
	v_mov_b32_e32 v43, v38
	v_mov_b32_e32 v46, v38
	v_mov_b32_e32 v47, v38
	v_mov_b32_e32 v48, v38
	v_mov_b32_e32 v49, v38
	s_waitcnt lgkmcnt(0)
	v_mov_b32_e32 v4, v38
	v_mov_b32_e32 v5, v38
	v_mov_b32_e32 v6, v38
	v_mov_b32_e32 v7, v38
	s_cmp_eq_u32 s2, 16
	s_cbranch_scc0 .LBB0_1729
	v_add_co_u32_e32 v12, vcc, s4, v2
	global_load_dwordx4 v[8:11], v[2:3], off nt
	s_nop 0
	v_addc_co_u32_e32 v13, vcc, -1, v3, vcc
	v_add_co_u32_e32 v16, vcc, s5, v2
	s_nop 0
	s_nop 0
	v_addc_co_u32_e32 v17, vcc, -1, v3, vcc
	v_add_co_u32_e32 v50, vcc, s11, v2
	s_nop 0
	s_nop 0
	v_addc_co_u32_e32 v51, vcc, 0, v3, vcc
	global_load_dwordx4 v[12:15], v[12:13], off nt
	s_nop 0
	global_load_dwordx4 v[16:19], v[16:17], off nt
	s_nop 0
	global_load_dwordx4 v[50:53], v[50:51], off nt
	v_lshl_add_u64 v[2:3], v[2:3], 0, s[20:21]
	v_add_co_u32_e32 v188, vcc, s4, v2
	global_load_dwordx4 v[184:187], v[2:3], off nt
	s_nop 0
	v_addc_co_u32_e32 v189, vcc, -1, v3, vcc
	v_add_co_u32_e32 v192, vcc, s5, v2
	s_nop 0
	s_nop 0
	v_addc_co_u32_e32 v193, vcc, -1, v3, vcc
	v_add_co_u32_e32 v196, vcc, s11, v2
	s_nop 0
	s_nop 0
	v_addc_co_u32_e32 v197, vcc, 0, v3, vcc
	global_load_dwordx4 v[188:191], v[188:189], off nt
	s_nop 0
	global_load_dwordx4 v[192:195], v[192:193], off nt
	s_nop 0
	global_load_dwordx4 v[196:199], v[196:197], off nt
	v_lshl_add_u64 v[2:3], v[2:3], 0, s[20:21]
	v_add_co_u32_e32 v204, vcc, s4, v2
	global_load_dwordx4 v[200:203], v[2:3], off nt
	s_nop 0
	v_addc_co_u32_e32 v205, vcc, -1, v3, vcc
	v_add_co_u32_e32 v208, vcc, s5, v2
	s_nop 0
	s_nop 0
	v_addc_co_u32_e32 v209, vcc, -1, v3, vcc
	v_add_co_u32_e32 v212, vcc, s11, v2
	s_nop 0
	s_nop 0
	v_addc_co_u32_e32 v213, vcc, 0, v3, vcc
	global_load_dwordx4 v[204:207], v[204:205], off nt
	s_nop 0
	global_load_dwordx4 v[208:211], v[208:209], off nt
	s_nop 0
	global_load_dwordx4 v[212:215], v[212:213], off nt
	v_lshl_add_u64 v[2:3], v[2:3], 0, s[20:21]
	v_add_co_u32_e32 v220, vcc, s4, v2
	global_load_dwordx4 v[216:219], v[2:3], off nt
	s_nop 0
	v_addc_co_u32_e32 v221, vcc, -1, v3, vcc
	v_add_co_u32_e32 v224, vcc, s5, v2
	s_nop 0
	s_nop 0
	v_addc_co_u32_e32 v225, vcc, -1, v3, vcc
	v_add_co_u32_e32 v228, vcc, s11, v2
	s_nop 0
	s_nop 0
	v_addc_co_u32_e32 v229, vcc, 0, v3, vcc
	global_load_dwordx4 v[220:223], v[220:221], off nt
	s_nop 0
	global_load_dwordx4 v[224:227], v[224:225], off nt
	s_nop 0
	global_load_dwordx4 v[228:231], v[228:229], off nt
	v_lshl_add_u64 v[2:3], v[2:3], 0, s[20:21]
	s_waitcnt vmcnt(12)
	v_pk_add_f32 v[42:43], v[42:43], v[10:11]
	v_pk_add_f32 v[44:45], v[44:45], v[8:9]
	v_pk_add_f32 v[6:7], v[6:7], v[14:15]
	v_pk_add_f32 v[4:5], v[4:5], v[12:13]
	v_pk_add_f32 v[48:49], v[48:49], v[18:19]
	v_pk_add_f32 v[46:47], v[46:47], v[16:17]
	v_pk_add_f32 v[40:41], v[40:41], v[52:53]
	v_pk_add_f32 v[38:39], v[38:39], v[50:51]
	s_waitcnt vmcnt(8)
	v_pk_add_f32 v[42:43], v[42:43], v[186:187]
	v_pk_add_f32 v[44:45], v[44:45], v[184:185]
	v_pk_add_f32 v[6:7], v[6:7], v[190:191]
	v_pk_add_f32 v[4:5], v[4:5], v[188:189]
	v_pk_add_f32 v[48:49], v[48:49], v[194:195]
	v_pk_add_f32 v[46:47], v[46:47], v[192:193]
	v_pk_add_f32 v[40:41], v[40:41], v[198:199]
	v_pk_add_f32 v[38:39], v[38:39], v[196:197]
	s_waitcnt vmcnt(4)
	v_pk_add_f32 v[42:43], v[42:43], v[202:203]
	v_pk_add_f32 v[44:45], v[44:45], v[200:201]
	v_pk_add_f32 v[6:7], v[6:7], v[206:207]
	v_pk_add_f32 v[4:5], v[4:5], v[204:205]
	v_pk_add_f32 v[48:49], v[48:49], v[210:211]
	v_pk_add_f32 v[46:47], v[46:47], v[208:209]
	v_pk_add_f32 v[40:41], v[40:41], v[214:215]
	v_pk_add_f32 v[38:39], v[38:39], v[212:213]
	s_waitcnt vmcnt(0)
	v_pk_add_f32 v[42:43], v[42:43], v[218:219]
	v_pk_add_f32 v[44:45], v[44:45], v[216:217]
	v_pk_add_f32 v[6:7], v[6:7], v[222:223]
	v_pk_add_f32 v[4:5], v[4:5], v[220:221]
	v_pk_add_f32 v[48:49], v[48:49], v[226:227]
	v_pk_add_f32 v[46:47], v[46:47], v[224:225]
	v_pk_add_f32 v[40:41], v[40:41], v[230:231]
	v_pk_add_f32 v[38:39], v[38:39], v[228:229]
	s_branch .Lfx_after_7
.LBB0_1729:
	v_add_co_u32_e32 v12, vcc, s4, v2
	global_load_dwordx4 v[8:11], v[2:3], off nt
	s_nop 0
	v_addc_co_u32_e32 v13, vcc, -1, v3, vcc
	v_add_co_u32_e32 v16, vcc, s5, v2
	s_add_i32 s8, s8, 4
	s_nop 0
	v_addc_co_u32_e32 v17, vcc, -1, v3, vcc
	v_add_co_u32_e32 v50, vcc, s11, v2
	s_cmp_ge_i32 s8, s2
	s_nop 0
	v_addc_co_u32_e32 v51, vcc, 0, v3, vcc
	global_load_dwordx4 v[12:15], v[12:13], off nt
	s_nop 0
	global_load_dwordx4 v[16:19], v[16:17], off nt
	s_nop 0
	global_load_dwordx4 v[50:53], v[50:51], off nt
	v_lshl_add_u64 v[2:3], v[2:3], 0, s[20:21]
	s_waitcnt vmcnt(3)
	v_pk_add_f32 v[42:43], v[42:43], v[10:11]
	v_pk_add_f32 v[44:45], v[44:45], v[8:9]
	s_waitcnt vmcnt(2)
	v_pk_add_f32 v[6:7], v[6:7], v[14:15]
	v_pk_add_f32 v[4:5], v[4:5], v[12:13]
	s_waitcnt vmcnt(1)
	v_pk_add_f32 v[48:49], v[48:49], v[18:19]
	v_pk_add_f32 v[46:47], v[46:47], v[16:17]
	s_waitcnt vmcnt(0)
	v_pk_add_f32 v[40:41], v[40:41], v[52:53]
	v_pk_add_f32 v[38:39], v[38:39], v[50:51]
	s_cbranch_scc0 .LBB0_1729

; template <class Epi> DI void gemm_fixup(int N, int K, const Epi& E, const float* part, int tid) {
;     ...
;         for (int b = 0; b < 2; ++b)
; #pragma unroll
;             for (int n = 0; n < 2; ++n) { const f32x4* pp = (const f32x4*)part + ((size_t)(j * S.S) * 32 + (((ai * 2 + b) * 4 + m) * 2 + n)) * 512 + tid;
;                 f32x4 v0 = {0.f, 0.f, 0.f, 0.f}, v1 = v0, v2 = v0, v3 = v0;
;                 for (int sl = 0; sl + 3 < S.S; sl += 4) { v0 += pp[(size_t)sl * 16384]; v1 += pp[(size_t)(sl + 1) * 16384]; v2 += pp[(size_t)(sl + 2) * 16384]; v3 += pp[(size_t)(sl + 3) * 16384]; }
;                 for (int sl = S.S & ~3; sl < S.S; ++sl) v0 += pp[(size_t)sl * 16384];
;                 a4[b][n] = (v0 + v1) + (v2 + v3); }
.LBB0_1733:
	global_load_dwordx4 v[8:11], v[2:3], off nt
	s_add_i32 s29, s29, 1
	v_lshl_add_u64 v[2:3], v[2:3], 0, s[22:23]
	s_cmp_ge_i32 s29, s2
	s_waitcnt vmcnt(0)
	v_pk_add_f32 v[6:7], v[6:7], v[10:11]
	v_pk_add_f32 v[4:5], v[4:5], v[8:9]
	s_cbranch_scc0 .LBB0_1733
.LBB0_1734:
	s_and_b64 vcc, exec, s[6:7]
	s_cbranch_vccnz .LBB0_1738
	s_add_u32 s34, s26, s19
	s_addc_u32 s35, s27, 0
	v_mov_b32_e32 v50, 0
	v_lshl_add_u64 v[2:3], v[24:25], 0, s[34:35]
	s_mov_b32 s29, 3
	v_mov_b32_e32 v51, v50
	v_mov_b32_e32 v52, v50
	v_mov_b32_e32 v53, v50
	v_mov_b32_e32 v56, v50
	v_mov_b32_e32 v57, v50
	v_mov_b32_e32 v54, v50
	v_mov_b32_e32 v55, v50
	v_mov_b32_e32 v58, v50
	v_mov_b32_e32 v59, v50
	v_mov_b32_e32 v60, v50
	v_mov_b32_e32 v61, v50
	v_mov_b32_e32 v8, v50
	v_mov_b32_e32 v9, v50
	v_mov_b32_e32 v10, v50
	v_mov_b32_e32 v11, v50
	s_cmp_eq_u32 s2, 16
	s_cbranch_scc0 .LBB0_1736
	v_add_co_u32_e32 v16, vcc, s4, v2
	global_load_dwordx4 v[12:15], v[2:3], off nt
	s_nop 0
	v_addc_co_u32_e32 v17, vcc, -1, v3, vcc
	v_add_co_u32_e32 v62, vcc, s5, v2
	s_nop 0
	s_nop 0
	v_addc_co_u32_e32 v63, vcc, -1, v3, vcc
	v_add_co_u32_e32 v66, vcc, s11, v2
	s_nop 0
	s_nop 0
	v_addc_co_u32_e32 v67, vcc, 0, v3, vcc
	global_load_dwordx4 v[16:19], v[16:17], off nt
	s_nop 0
	global_load_dwordx4 v[62:65], v[62:63], off nt
	s_nop 0
	global_load_dwordx4 v[66:69], v[66:67], off nt
	v_lshl_add_u64 v[2:3], v[2:3], 0, s[20:21]
	v_add_co_u32_e32 v188, vcc, s4, v2
	global_load_dwordx4 v[184:187], v[2:3], off nt
	s_nop 0
	v_addc_co_u32_e32 v189, vcc, -1, v3, vcc
	v_add_co_u32_e32 v192, vcc, s5, v2
	s_nop 0
	s_nop 0
	v_addc_co_u32_e32 v193, vcc, -1, v3, vcc
	v_add_co_u32_e32 v196, vcc, s11, v2
	s_nop 0
	s_nop 0
	v_addc_co_u32_e32 v197, vcc, 0, v3, vcc
	global_load_dwordx4 v[188:191], v[188:189], off nt
	s_nop 0
	global_load_dwordx4 v[192:195], v[192:193], off nt
	s_nop 0
	global_load_dwordx4 v[196:199], v[196:197], off nt
	v_lshl_add_u64 v[2:3], v[2:3], 0, s[20:21]
	v_add_co_u32_e32 v204, vcc, s4, v2
	global_load_dwordx4 v[200:203], v[2:3], off nt
	s_nop 0
	v_addc_co_u32_e32 v205, vcc, -1, v3, vcc
	v_add_co_u32_e32 v208, vcc, s5, v2
	s_nop 0
	s_nop 0
	v_addc_co_u32_e32 v209, vcc, -1, v3, vcc
	v_add_co_u32_e32 v212, vcc, s11, v2
	s_nop 0
	s_nop 0
	v_addc_co_u32_e32 v213, vcc, 0, v3, vcc
	global_load_dwordx4 v[204:207], v[204:205], off nt
	s_nop 0
	global_load_dwordx4 v[208:211], v[208:209], off nt
	s_nop 0
	global_load_dwordx4 v[212:215], v[212:213], off nt
	v_lshl_add_u64 v[2:3], v[2:3], 0, s[20:21]
	v_add_co_u32_e32 v220, vcc, s4, v2
	global_load_dwordx4 v[216:219], v[2:3], off nt
	s_nop 0
	v_addc_co_u32_e32 v221, vcc, -1, v3, vcc
	v_add_co_u32_e32 v224, vcc, s5, v2
	s_nop 0
	s_nop 0
	v_addc_co_u32_e32 v225, vcc, -1, v3, vcc
	v_add_co_u32_e32 v228, vcc, s11, v2
	s_nop 0
	s_nop 0
	v_addc_co_u32_e32 v229, vcc, 0, v3, vcc
	global_load_dwordx4 v[220:223], v[220:221], off nt
	s_nop 0
	global_load_dwordx4 v[224:227], v[224:225], off nt
	s_nop 0
	global_load_dwordx4 v[228:231], v[228:229], off nt
	v_lshl_add_u64 v[2:3], v[2:3], 0, s[20:21]
	s_waitcnt vmcnt(12)
	v_pk_add_f32 v[54:55], v[54:55], v[14:15]
	v_pk_add_f32 v[56:57], v[56:57], v[12:13]
	v_pk_add_f32 v[10:11], v[10:11], v[18:19]
	v_pk_add_f32 v[8:9], v[8:9], v[16:17]
	v_pk_add_f32 v[60:61], v[60:61], v[64:65]
	v_pk_add_f32 v[58:59], v[58:59], v[62:63]
	v_pk_add_f32 v[52:53], v[52:53], v[68:69]
	v_pk_add_f32 v[50:51], v[50:51], v[66:67]
	s_waitcnt vmcnt(8)
	v_pk_add_f32 v[54:55], v[54:55], v[186:187]
	v_pk_add_f32 v[56:57], v[56:57], v[184:185]
	v_pk_add_f32 v[10:11], v[10:11], v[190:191]
	v_pk_add_f32 v[8:9], v[8:9], v[188:189]
	v_pk_add_f32 v[60:61], v[60:61], v[194:195]
	v_pk_add_f32 v[58:59], v[58:59], v[192:193]
	v_pk_add_f32 v[52:53], v[52:53], v[198:199]
	v_pk_add_f32 v[50:51], v[50:51], v[196:197]
	s_waitcnt vmcnt(4)
	v_pk_add_f32 v[54:55], v[54:55], v[202:203]
	v_pk_add_f32 v[56:57], v[56:57], v[200:201]
	v_pk_add_f32 v[10:11], v[10:11], v[206:207]
	v_pk_add_f32 v[8:9], v[8:9], v[204:205]
	v_pk_add_f32 v[60:61], v[60:61], v[210:211]
	v_pk_add_f32 v[58:59], v[58:59], v[208:209]
	v_pk_add_f32 v[52:53], v[52:53], v[214:215]
	v_pk_add_f32 v[50:51], v[50:51], v[212:213]
	s_waitcnt vmcnt(0)
	v_pk_add_f32 v[54:55], v[54:55], v[218:219]
	v_pk_add_f32 v[56:57], v[56:57], v[216:217]
	v_pk_add_f32 v[10:11], v[10:11], v[222:223]
	v_pk_add_f32 v[8:9], v[8:9], v[220:221]
	v_pk_add_f32 v[60:61], v[60:61], v[226:227]
	v_pk_add_f32 v[58:59], v[58:59], v[224:225]
	v_pk_add_f32 v[52:53], v[52:53], v[230:231]
	v_pk_add_f32 v[50:51], v[50:51], v[228:229]
	s_branch .Lfx_after_6
.LBB0_1736:
	v_add_co_u32_e32 v16, vcc, s4, v2
	global_load_dwordx4 v[12:15], v[2:3], off nt
	s_nop 0
	v_addc_co_u32_e32 v17, vcc, -1, v3, vcc
	v_add_co_u32_e32 v62, vcc, s5, v2
	s_add_i32 s29, s29, 4
	s_nop 0
	v_addc_co_u32_e32 v63, vcc, -1, v3, vcc
	v_add_co_u32_e32 v66, vcc, s11, v2
	s_cmp_lt_i32 s29, s2
	s_nop 0
	v_addc_co_u32_e32 v67, vcc, 0, v3, vcc
	global_load_dwordx4 v[16:19], v[16:17], off nt
	s_nop 0
	global_load_dwordx4 v[62:65], v[62:63], off nt
	s_nop 0
	global_load_dwordx4 v[66:69], v[66:67], off nt
	v_lshl_add_u64 v[2:3], v[2:3], 0, s[20:21]
	s_waitcnt vmcnt(3)
	v_pk_add_f32 v[54:55], v[54:55], v[14:15]
	v_pk_add_f32 v[56:57], v[56:57], v[12:13]
	s_waitcnt vmcnt(2)
	v_pk_add_f32 v[10:11], v[10:11], v[18:19]
	v_pk_add_f32 v[8:9], v[8:9], v[16:17]
	s_waitcnt vmcnt(1)
	v_pk_add_f32 v[60:61], v[60:61], v[64:65]
	v_pk_add_f32 v[58:59], v[58:59], v[62:63]
	s_waitcnt vmcnt(0)
	v_pk_add_f32 v[52:53], v[52:53], v[68:69]
	v_pk_add_f32 v[50:51], v[50:51], v[66:67]
	s_cbranch_scc1 .LBB0_1736

; template <class Epi> DI void gemm_fixup(int N, int K, const Epi& E, const float* part, int tid) {
;     ...
;         for (int b = 0; b < 2; ++b)
; #pragma unroll
;             for (int n = 0; n < 2; ++n) { const f32x4* pp = (const f32x4*)part + ((size_t)(j * S.S) * 32 + (((ai * 2 + b) * 4 + m) * 2 + n)) * 512 + tid;
;                 f32x4 v0 = {0.f, 0.f, 0.f, 0.f}, v1 = v0, v2 = v0, v3 = v0;
;                 for (int sl = 0; sl + 3 < S.S; sl += 4) { v0 += pp[(size_t)sl * 16384]; v1 += pp[(size_t)(sl + 1) * 16384]; v2 += pp[(size_t)(sl + 2) * 16384]; v3 += pp[(size_t)(sl + 3) * 16384]; }
;                 for (int sl = S.S & ~3; sl < S.S; ++sl) v0 += pp[(size_t)sl * 16384];
;                 a4[b][n] = (v0 + v1) + (v2 + v3); }
.LBB0_1740:
	global_load_dwordx4 v[12:15], v[2:3], off nt
	s_add_i32 s29, s29, 1
	v_lshl_add_u64 v[2:3], v[2:3], 0, s[22:23]
	s_cmp_lt_i32 s29, s2
	s_waitcnt vmcnt(0)
	v_pk_add_f32 v[10:11], v[10:11], v[14:15]
	v_pk_add_f32 v[8:9], v[8:9], v[12:13]
	s_cbranch_scc1 .LBB0_1740
.LBB0_1741:
	s_and_b64 vcc, exec, s[6:7]
	s_cbranch_vccnz .LBB0_1745
	s_add_u32 s34, s26, s19
	s_addc_u32 s35, s27, 0
	v_mov_b32_e32 v62, 0
	v_lshl_add_u64 v[2:3], v[28:29], 0, s[34:35]
	s_mov_b32 s29, 3
	v_mov_b32_e32 v63, v62
	v_mov_b32_e32 v64, v62
	v_mov_b32_e32 v65, v62
	v_mov_b32_e32 v68, v62
	v_mov_b32_e32 v69, v62
	v_mov_b32_e32 v66, v62
	v_mov_b32_e32 v67, v62
	v_mov_b32_e32 v70, v62
	v_mov_b32_e32 v71, v62
	v_mov_b32_e32 v72, v62
	v_mov_b32_e32 v73, v62
	v_mov_b32_e32 v12, v62
	v_mov_b32_e32 v13, v62
	v_mov_b32_e32 v14, v62
	v_mov_b32_e32 v15, v62
	s_cmp_eq_u32 s2, 16
	s_cbranch_scc0 .LBB0_1743
	v_add_co_u32_e32 v74, vcc, s4, v2
	global_load_dwordx4 v[16:19], v[2:3], off nt
	s_nop 0
	v_addc_co_u32_e32 v75, vcc, -1, v3, vcc
	v_add_co_u32_e32 v78, vcc, s5, v2
	s_nop 0
	s_nop 0
	v_addc_co_u32_e32 v79, vcc, -1, v3, vcc
	v_add_co_u32_e32 v82, vcc, s11, v2
	s_nop 0
	s_nop 0
	v_addc_co_u32_e32 v83, vcc, 0, v3, vcc
	global_load_dwordx4 v[74:77], v[74:75], off nt
	s_nop 0
	global_load_dwordx4 v[78:81], v[78:79], off nt
	s_nop 0
	global_load_dwordx4 v[82:85], v[82:83], off nt
	v_lshl_add_u64 v[2:3], v[2:3], 0, s[20:21]
	v_add_co_u32_e32 v188, vcc, s4, v2
	global_load_dwordx4 v[184:187], v[2:3], off nt
	s_nop 0
	v_addc_co_u32_e32 v189, vcc, -1, v3, vcc
	v_add_co_u32_e32 v192, vcc, s5, v2
	s_nop 0
	s_nop 0
	v_addc_co_u32_e32 v193, vcc, -1, v3, vcc
	v_add_co_u32_e32 v196, vcc, s11, v2
	s_nop 0
	s_nop 0
	v_addc_co_u32_e32 v197, vcc, 0, v3, vcc
	global_load_dwordx4 v[188:191], v[188:189], off nt
	s_nop 0
	global_load_dwordx4 v[192:195], v[192:193], off nt
	s_nop 0
	global_load_dwordx4 v[196:199], v[196:197], off nt
	v_lshl_add_u64 v[2:3], v[2:3], 0, s[20:21]
	v_add_co_u32_e32 v204, vcc, s4, v2
	global_load_dwordx4 v[200:203], v[2:3], off nt
	s_nop 0
	v_addc_co_u32_e32 v205, vcc, -1, v3, vcc
	v_add_co_u32_e32 v208, vcc, s5, v2
	s_nop 0
	s_nop 0
	v_addc_co_u32_e32 v209, vcc, -1, v3, vcc
	v_add_co_u32_e32 v212, vcc, s11, v2
	s_nop 0
	s_nop 0
	v_addc_co_u32_e32 v213, vcc, 0, v3, vcc
	global_load_dwordx4 v[204:207], v[204:205], off nt
	s_nop 0
	global_load_dwordx4 v[208:211], v[208:209], off nt
	s_nop 0
	global_load_dwordx4 v[212:215], v[212:213], off nt
	v_lshl_add_u64 v[2:3], v[2:3], 0, s[20:21]
	v_add_co_u32_e32 v220, vcc, s4, v2
	global_load_dwordx4 v[216:219], v[2:3], off nt
	s_nop 0
	v_addc_co_u32_e32 v221, vcc, -1, v3, vcc
	v_add_co_u32_e32 v224, vcc, s5, v2
	s_nop 0
	s_nop 0
	v_addc_co_u32_e32 v225, vcc, -1, v3, vcc
	v_add_co_u32_e32 v228, vcc, s11, v2
	s_nop 0
	s_nop 0
	v_addc_co_u32_e32 v229, vcc, 0, v3, vcc
	global_load_dwordx4 v[220:223], v[220:221], off nt
	s_nop 0
	global_load_dwordx4 v[224:227], v[224:225], off nt
	s_nop 0
	global_load_dwordx4 v[228:231], v[228:229], off nt
	v_lshl_add_u64 v[2:3], v[2:3], 0, s[20:21]
	s_waitcnt vmcnt(12)
	v_pk_add_f32 v[66:67], v[66:67], v[18:19]
	v_pk_add_f32 v[68:69], v[68:69], v[16:17]
	v_pk_add_f32 v[14:15], v[14:15], v[76:77]
	v_pk_add_f32 v[12:13], v[12:13], v[74:75]
	v_pk_add_f32 v[72:73], v[72:73], v[80:81]
	v_pk_add_f32 v[70:71], v[70:71], v[78:79]
	v_pk_add_f32 v[64:65], v[64:65], v[84:85]
	v_pk_add_f32 v[62:63], v[62:63], v[82:83]
	s_waitcnt vmcnt(8)
	v_pk_add_f32 v[66:67], v[66:67], v[186:187]
	v_pk_add_f32 v[68:69], v[68:69], v[184:185]
	v_pk_add_f32 v[14:15], v[14:15], v[190:191]
	v_pk_add_f32 v[12:13], v[12:13], v[188:189]
	v_pk_add_f32 v[72:73], v[72:73], v[194:195]
	v_pk_add_f32 v[70:71], v[70:71], v[192:193]
	v_pk_add_f32 v[64:65], v[64:65], v[198:199]
	v_pk_add_f32 v[62:63], v[62:63], v[196:197]
	s_waitcnt vmcnt(4)
	v_pk_add_f32 v[66:67], v[66:67], v[202:203]
	v_pk_add_f32 v[68:69], v[68:69], v[200:201]
	v_pk_add_f32 v[14:15], v[14:15], v[206:207]
	v_pk_add_f32 v[12:13], v[12:13], v[204:205]
	v_pk_add_f32 v[72:73], v[72:73], v[210:211]
	v_pk_add_f32 v[70:71], v[70:71], v[208:209]
	v_pk_add_f32 v[64:65], v[64:65], v[214:215]
	v_pk_add_f32 v[62:63], v[62:63], v[212:213]
	s_waitcnt vmcnt(0)
	v_pk_add_f32 v[66:67], v[66:67], v[218:219]
	v_pk_add_f32 v[68:69], v[68:69], v[216:217]
	v_pk_add_f32 v[14:15], v[14:15], v[222:223]
	v_pk_add_f32 v[12:13], v[12:13], v[220:221]
	v_pk_add_f32 v[72:73], v[72:73], v[226:227]
	v_pk_add_f32 v[70:71], v[70:71], v[224:225]
	v_pk_add_f32 v[64:65], v[64:65], v[230:231]
	v_pk_add_f32 v[62:63], v[62:63], v[228:229]
	s_branch .Lfx_after_5
.LBB0_1743:
	v_add_co_u32_e32 v74, vcc, s4, v2
	global_load_dwordx4 v[16:19], v[2:3], off nt
	s_nop 0
	v_addc_co_u32_e32 v75, vcc, -1, v3, vcc
	v_add_co_u32_e32 v78, vcc, s5, v2
	s_add_i32 s29, s29, 4
	s_nop 0
	v_addc_co_u32_e32 v79, vcc, -1, v3, vcc
	v_add_co_u32_e32 v82, vcc, s11, v2
	s_cmp_lt_i32 s29, s2
	s_nop 0
	v_addc_co_u32_e32 v83, vcc, 0, v3, vcc
	global_load_dwordx4 v[74:77], v[74:75], off nt
	s_nop 0
	global_load_dwordx4 v[78:81], v[78:79], off nt
	s_nop 0
	global_load_dwordx4 v[82:85], v[82:83], off nt
	v_lshl_add_u64 v[2:3], v[2:3], 0, s[20:21]
	s_waitcnt vmcnt(3)
	v_pk_add_f32 v[66:67], v[66:67], v[18:19]
	v_pk_add_f32 v[68:69], v[68:69], v[16:17]
	s_waitcnt vmcnt(2)
	v_pk_add_f32 v[14:15], v[14:15], v[76:77]
	v_pk_add_f32 v[12:13], v[12:13], v[74:75]
	s_waitcnt vmcnt(1)
	v_pk_add_f32 v[72:73], v[72:73], v[80:81]
	v_pk_add_f32 v[70:71], v[70:71], v[78:79]
	s_waitcnt vmcnt(0)
	v_pk_add_f32 v[64:65], v[64:65], v[84:85]
	v_pk_add_f32 v[62:63], v[62:63], v[82:83]
	s_cbranch_scc1 .LBB0_1743

; template <class Epi> DI void gemm_fixup(int N, int K, const Epi& E, const float* part, int tid) {
;     ...
;         for (int b = 0; b < 2; ++b)
; #pragma unroll
;             for (int n = 0; n < 2; ++n) { const f32x4* pp = (const f32x4*)part + ((size_t)(j * S.S) * 32 + (((ai * 2 + b) * 4 + m) * 2 + n)) * 512 + tid;
;                 f32x4 v0 = {0.f, 0.f, 0.f, 0.f}, v1 = v0, v2 = v0, v3 = v0;
;                 for (int sl = 0; sl + 3 < S.S; sl += 4) { v0 += pp[(size_t)sl * 16384]; v1 += pp[(size_t)(sl + 1) * 16384]; v2 += pp[(size_t)(sl + 2) * 16384]; v3 += pp[(size_t)(sl + 3) * 16384]; }
;                 for (int sl = S.S & ~3; sl < S.S; ++sl) v0 += pp[(size_t)sl * 16384];
;                 a4[b][n] = (v0 + v1) + (v2 + v3); }
.LBB0_1747:
	global_load_dwordx4 v[16:19], v[2:3], off nt
	s_add_i32 s29, s29, 1
	v_lshl_add_u64 v[2:3], v[2:3], 0, s[22:23]
	s_cmp_lt_i32 s29, s2
	s_waitcnt vmcnt(0)
	v_pk_add_f32 v[14:15], v[14:15], v[18:19]
	v_pk_add_f32 v[12:13], v[12:13], v[16:17]
	s_cbranch_scc1 .LBB0_1747
.LBB0_1748:
	s_and_b64 vcc, exec, s[6:7]
	s_cbranch_vccnz .LBB0_1752
	s_add_u32 s34, s26, s19
	s_addc_u32 s35, s27, 0
	v_mov_b32_e32 v74, 0
	v_lshl_add_u64 v[2:3], v[32:33], 0, s[34:35]
	s_mov_b32 s29, 3
	v_mov_b32_e32 v75, v74
	v_mov_b32_e32 v76, v74
	v_mov_b32_e32 v77, v74
	v_mov_b32_e32 v80, v74
	v_mov_b32_e32 v81, v74
	v_mov_b32_e32 v78, v74
	v_mov_b32_e32 v79, v74
	v_mov_b32_e32 v82, v74
	v_mov_b32_e32 v83, v74
	v_mov_b32_e32 v84, v74
	v_mov_b32_e32 v85, v74
	v_mov_b32_e32 v16, v74
	v_mov_b32_e32 v17, v74
	v_mov_b32_e32 v18, v74
	v_mov_b32_e32 v19, v74
	s_cmp_eq_u32 s2, 16
	s_cbranch_scc0 .LBB0_1750
	v_add_co_u32_e32 v94, vcc, s4, v2
	global_load_dwordx4 v[90:93], v[2:3], off nt
	s_nop 0
	v_addc_co_u32_e32 v95, vcc, -1, v3, vcc
	v_add_co_u32_e32 v98, vcc, s5, v2
	s_nop 0
	s_nop 0
	v_addc_co_u32_e32 v99, vcc, -1, v3, vcc
	v_add_co_u32_e32 v102, vcc, s11, v2
	s_nop 0
	s_nop 0
	v_addc_co_u32_e32 v103, vcc, 0, v3, vcc
	global_load_dwordx4 v[94:97], v[94:95], off nt
	s_nop 0
	global_load_dwordx4 v[98:101], v[98:99], off nt
	s_nop 0
	global_load_dwordx4 v[102:105], v[102:103], off nt
	v_lshl_add_u64 v[2:3], v[2:3], 0, s[20:21]
	v_add_co_u32_e32 v188, vcc, s4, v2
	global_load_dwordx4 v[184:187], v[2:3], off nt
	s_nop 0
	v_addc_co_u32_e32 v189, vcc, -1, v3, vcc
	v_add_co_u32_e32 v192, vcc, s5, v2
	s_nop 0
	s_nop 0
	v_addc_co_u32_e32 v193, vcc, -1, v3, vcc
	v_add_co_u32_e32 v196, vcc, s11, v2
	s_nop 0
	s_nop 0
	v_addc_co_u32_e32 v197, vcc, 0, v3, vcc
	global_load_dwordx4 v[188:191], v[188:189], off nt
	s_nop 0
	global_load_dwordx4 v[192:195], v[192:193], off nt
	s_nop 0
	global_load_dwordx4 v[196:199], v[196:197], off nt
	v_lshl_add_u64 v[2:3], v[2:3], 0, s[20:21]
	v_add_co_u32_e32 v204, vcc, s4, v2
	global_load_dwordx4 v[200:203], v[2:3], off nt
	s_nop 0
	v_addc_co_u32_e32 v205, vcc, -1, v3, vcc
	v_add_co_u32_e32 v208, vcc, s5, v2
	s_nop 0
	s_nop 0
	v_addc_co_u32_e32 v209, vcc, -1, v3, vcc
	v_add_co_u32_e32 v212, vcc, s11, v2
	s_nop 0
	s_nop 0
	v_addc_co_u32_e32 v213, vcc, 0, v3, vcc
	global_load_dwordx4 v[204:207], v[204:205], off nt
	s_nop 0
	global_load_dwordx4 v[208:211], v[208:209], off nt
	s_nop 0
	global_load_dwordx4 v[212:215], v[212:213], off nt
	v_lshl_add_u64 v[2:3], v[2:3], 0, s[20:21]
	v_add_co_u32_e32 v220, vcc, s4, v2
	global_load_dwordx4 v[216:219], v[2:3], off nt
	s_nop 0
	v_addc_co_u32_e32 v221, vcc, -1, v3, vcc
	v_add_co_u32_e32 v224, vcc, s5, v2
	s_nop 0
	s_nop 0
	v_addc_co_u32_e32 v225, vcc, -1, v3, vcc
	v_add_co_u32_e32 v228, vcc, s11, v2
	s_nop 0
	s_nop 0
	v_addc_co_u32_e32 v229, vcc, 0, v3, vcc
	global_load_dwordx4 v[220:223], v[220:221], off nt
	s_nop 0
	global_load_dwordx4 v[224:227], v[224:225], off nt
	s_nop 0
	global_load_dwordx4 v[228:231], v[228:229], off nt
	v_lshl_add_u64 v[2:3], v[2:3], 0, s[20:21]
	s_waitcnt vmcnt(12)
	v_pk_add_f32 v[78:79], v[78:79], v[92:93]
	v_pk_add_f32 v[80:81], v[80:81], v[90:91]
	v_pk_add_f32 v[18:19], v[18:19], v[96:97]
	v_pk_add_f32 v[16:17], v[16:17], v[94:95]
	v_pk_add_f32 v[84:85], v[84:85], v[100:101]
	v_pk_add_f32 v[82:83], v[82:83], v[98:99]
	v_pk_add_f32 v[76:77], v[76:77], v[104:105]
	v_pk_add_f32 v[74:75], v[74:75], v[102:103]
	s_waitcnt vmcnt(8)
	v_pk_add_f32 v[78:79], v[78:79], v[186:187]
	v_pk_add_f32 v[80:81], v[80:81], v[184:185]
	v_pk_add_f32 v[18:19], v[18:19], v[190:191]
	v_pk_add_f32 v[16:17], v[16:17], v[188:189]
	v_pk_add_f32 v[84:85], v[84:85], v[194:195]
	v_pk_add_f32 v[82:83], v[82:83], v[192:193]
	v_pk_add_f32 v[76:77], v[76:77], v[198:199]
	v_pk_add_f32 v[74:75], v[74:75], v[196:197]
	s_waitcnt vmcnt(4)
	v_pk_add_f32 v[78:79], v[78:79], v[202:203]
	v_pk_add_f32 v[80:81], v[80:81], v[200:201]
	v_pk_add_f32 v[18:19], v[18:19], v[206:207]
	v_pk_add_f32 v[16:17], v[16:17], v[204:205]
	v_pk_add_f32 v[84:85], v[84:85], v[210:211]
	v_pk_add_f32 v[82:83], v[82:83], v[208:209]
	v_pk_add_f32 v[76:77], v[76:77], v[214:215]
	v_pk_add_f32 v[74:75], v[74:75], v[212:213]
	s_waitcnt vmcnt(0)
	v_pk_add_f32 v[78:79], v[78:79], v[218:219]
	v_pk_add_f32 v[80:81], v[80:81], v[216:217]
	v_pk_add_f32 v[18:19], v[18:19], v[222:223]
	v_pk_add_f32 v[16:17], v[16:17], v[220:221]
	v_pk_add_f32 v[84:85], v[84:85], v[226:227]
	v_pk_add_f32 v[82:83], v[82:83], v[224:225]
	v_pk_add_f32 v[76:77], v[76:77], v[230:231]
	v_pk_add_f32 v[74:75], v[74:75], v[228:229]
	s_branch .Lfx_after_4
.LBB0_1750:
	v_add_co_u32_e32 v94, vcc, s4, v2
	global_load_dwordx4 v[90:93], v[2:3], off nt
	s_nop 0
	v_addc_co_u32_e32 v95, vcc, -1, v3, vcc
	v_add_co_u32_e32 v98, vcc, s5, v2
	s_add_i32 s29, s29, 4
	s_nop 0
	v_addc_co_u32_e32 v99, vcc, -1, v3, vcc
	v_add_co_u32_e32 v102, vcc, s11, v2
	s_cmp_lt_i32 s29, s2
	s_nop 0
	v_addc_co_u32_e32 v103, vcc, 0, v3, vcc
	global_load_dwordx4 v[94:97], v[94:95], off nt
	s_nop 0
	global_load_dwordx4 v[98:101], v[98:99], off nt
	s_nop 0
	global_load_dwordx4 v[102:105], v[102:103], off nt
	v_lshl_add_u64 v[2:3], v[2:3], 0, s[20:21]
	s_waitcnt vmcnt(3)
	v_pk_add_f32 v[78:79], v[78:79], v[92:93]
	v_pk_add_f32 v[80:81], v[80:81], v[90:91]
	s_waitcnt vmcnt(2)
	v_pk_add_f32 v[18:19], v[18:19], v[96:97]
	v_pk_add_f32 v[16:17], v[16:17], v[94:95]
	s_waitcnt vmcnt(1)
	v_pk_add_f32 v[84:85], v[84:85], v[100:101]
	v_pk_add_f32 v[82:83], v[82:83], v[98:99]
	s_waitcnt vmcnt(0)
	v_pk_add_f32 v[76:77], v[76:77], v[104:105]
	v_pk_add_f32 v[74:75], v[74:75], v[102:103]
	s_cbranch_scc1 .LBB0_1750

; template <class Epi> DI void gemm_fixup(int N, int K, const Epi& E, const float* part, int tid) {
;     ...
;                 for (int sl = 0; sl + 3 < S.S; sl += 4) { v0 += pp[(size_t)sl * 16384]; v1 += pp[(size_t)(sl + 1) * 16384]; v2 += pp[(size_t)(sl + 2) * 16384]; v3 += pp[(size_t)(sl + 3) * 16384]; }
;                 for (int sl = S.S & ~3; sl < S.S; ++sl) v0 += pp[(size_t)sl * 16384];
.LBB0_1754:
	global_load_dwordx4 v[90:93], v[2:3], off nt
	s_add_i32 s8, s8, 1
	v_lshl_add_u64 v[2:3], v[2:3], 0, s[22:23]
	s_cmp_lt_i32 s8, s2
	s_waitcnt vmcnt(0)
	v_pk_add_f32 v[18:19], v[18:19], v[92:93]
	v_pk_add_f32 v[16:17], v[16:17], v[90:91]
	s_cbranch_scc1 .LBB0_1754
; DI unsigned pk2(float lo, float hi) { unsigned r; asm volatile("v_cvt_pk_bf16_f32 %0, %1, %2" : "=v"(r) : "v"(lo), "v"(hi)); return r; }
; DI float bflo(unsigned u) { return __uint_as_float(u << 16); }
;     DI float upd(u32x4v* px, const u32x4v x, const f32x4 v0, const f32x4 v1) const {
;         u32x4v o; o.x = pk2(bflo(x.x) + v0[0], bfhi(x.x) + v0[1]); o.y = pk2(bflo(x.y) + v0[2], bfhi(x.y) + v0[3]);
;         o.z = pk2(bflo(x.z) + v1[0], bfhi(x.z) + v1[1]); o.w = pk2(bflo(x.w) + v1[2], bfhi(x.w) + v1[3]); *px = o;
;         const float a0 = bflo(o.x), a1 = bfhi(o.x), a2 = bflo(o.y), a3 = bfhi(o.y), a4 = bflo(o.z), a5 = bfhi(o.z), a6 = bflo(o.w), a7 = bfhi(o.w);
;         return ((a0 * a0 + a1 * a1) + (a2 * a2 + a3 * a3)) + ((a4 * a4 + a5 * a5) + (a6 * a6 + a7 * a7));
;     }
;     DI void row(const f32x4 (&a4)[2][2], const Unit& u, int ai, int m, int wr, int wc, int fr, int fq) const {
;         const int cb = u.pn * 256 + wc * 32 + 8 * fq, row = u.pm * 256 + wr * 64 + fr + ai * 128 + m * 16;
;         u32x4v* p0 = (u32x4v*)(XB + (size_t)row * 1024 + cb); u32x4v* p1 = (u32x4v*)(XB + (size_t)row * 1024 + cb + 128);
;         const u32x4v x0 = *p0, x1 = *p1;
;         float ss = upd(p0, x0, a4[0][0], a4[0][1]) + upd(p1, x1, a4[1][0], a4[1][1]);
;         ss += __shfl_xor(ss, 16); ss += __shfl_xor(ss, 32);
;         if (fq == 0) SSQ[(size_t)row * 16 + u.pn * 4 + wc] = ss;
;     }
; template <class Epi> DI void gemm_fixup(int N, int K, const Epi& E, const float* part, int tid) {
;     ...
;     for (int it = blockIdx.x; it < S.ntail * 8; it += gridDim.x) { const int j = it >> 3, ai = (it >> 2) & 1, m = it & 3; Unit u; S.map(S.nwhole * S.G + j, u);
;         f32x4 a4[2][2];
; #pragma unroll
;         for (int b = 0; b < 2; ++b)
; #pragma unroll
;             for (int n = 0; n < 2; ++n) { const f32x4* pp = (const f32x4*)part + ((size_t)(j * S.S) * 32 + (((ai * 2 + b) * 4 + m) * 2 + n)) * 512 + tid;
;                 f32x4 v0 = {0.f, 0.f, 0.f, 0.f}, v1 = v0, v2 = v0, v3 = v0;
;                 for (int sl = 0; sl + 3 < S.S; sl += 4) { v0 += pp[(size_t)sl * 16384]; v1 += pp[(size_t)(sl + 1) * 16384]; v2 += pp[(size_t)(sl + 2) * 16384]; v3 += pp[(size_t)(sl + 3) * 16384]; }
;                 for (int sl = S.S & ~3; sl < S.S; ++sl) v0 += pp[(size_t)sl * 16384];
;                 a4[b][n] = (v0 + v1) + (v2 + v3); }
;         E.row(a4, u, ai, m, wr, wc, fr, fq); }
.LBB0_1755:
	s_add_i32 s8, s18, s25
	s_ashr_i32 s9, s8, 31
	s_lshr_b32 s9, s9, 27
	s_add_i32 s9, s8, s9
	s_ashr_i32 s18, s9, 5
	s_lshl_b32 s19, s18, 3
	s_sub_i32 s18, 0x83, s19
	s_min_i32 s25, s18, 8
	s_abs_i32 s18, s25
	v_cvt_f32_u32_e32 v1, s18
	s_sub_i32 s27, 0, s18
	s_andn2_b32 s9, s9, 31
	s_sub_i32 s8, s8, s9
	v_rcp_iflag_f32_e32 v1, v1
	s_abs_i32 s9, s8
	s_xor_b32 s26, s8, s25
	s_ashr_i32 s26, s26, 31
	v_mul_f32_e32 v1, 0x4f7ffffe, v1
	v_cvt_u32_f32_e32 v1, v1
	v_readlane_b32 s52, v254, 28
	v_readlane_b32 s64, v254, 40
	v_readlane_b32 s65, v254, 41
	v_readfirstlane_b32 s29, v1
	s_mul_i32 s27, s27, s29
	s_mul_hi_u32 s27, s29, s27
	s_add_i32 s29, s29, s27
	s_mul_hi_u32 s27, s9, s29
	s_mul_i32 s29, s27, s18
	s_sub_i32 s9, s9, s29
	s_add_i32 s30, s27, 1
	s_sub_i32 s29, s9, s18
	s_cmp_ge_u32 s9, s18
	s_cselect_b32 s27, s30, s27
	s_cselect_b32 s9, s29, s9
	s_add_i32 s29, s27, 1
	s_cmp_ge_u32 s9, s18
	s_cselect_b32 s9, s29, s27
	s_xor_b32 s9, s9, s26
	s_sub_i32 s18, s9, s26
	s_mul_i32 s9, s18, s25
	s_sub_i32 s8, s8, s9
	s_and_b32 s24, s24, 1
	s_add_i32 s19, s19, s8
	s_and_b32 s8, s17, 3
	s_lshl_b32 s9, s19, 8
	s_lshl_b32 s19, s24, 7
	v_lshl_or_b32 v1, s8, 4, v87
	s_or_b32 s8, s9, s19
	v_add_u32_e32 v2, s8, v1
	v_ashrrev_i32_e32 v3, 31, v2
	v_lshl_or_b32 v90, s18, 8, v86
	v_lshlrev_b64 v[92:93], 11, v[2:3]
	v_lshl_add_u64 v[92:93], s[64:65], 0, v[92:93]
	v_ashrrev_i32_e32 v91, 31, v90
	v_lshl_add_u64 v[98:99], v[90:91], 1, v[92:93]
	global_load_dwordx4 v[90:93], v[98:99], off nt
	global_load_dwordx4 v[94:97], v[98:99], off offset:256 nt
	v_pk_add_f32 v[6:7], v[48:49], v[6:7]
	v_pk_add_f32 v[4:5], v[46:47], v[4:5]
	v_pk_add_f32 v[38:39], v[44:45], v[38:39]
	v_pk_add_f32 v[40:41], v[42:43], v[40:41]
	v_pk_add_f32 v[10:11], v[60:61], v[10:11]
	v_pk_add_f32 v[8:9], v[58:59], v[8:9]
	v_pk_add_f32 v[50:51], v[56:57], v[50:51]
	v_pk_add_f32 v[52:53], v[54:55], v[52:53]
	v_pk_add_f32 v[16:17], v[82:83], v[16:17]
	v_pk_add_f32 v[42:43], v[80:81], v[74:75]
	v_pk_add_f32 v[6:7], v[40:41], v[6:7]
	v_pk_add_f32 v[4:5], v[38:39], v[4:5]
	v_pk_add_f32 v[14:15], v[72:73], v[14:15]
	v_pk_add_f32 v[12:13], v[70:71], v[12:13]
	v_pk_add_f32 v[62:63], v[68:69], v[62:63]
	v_pk_add_f32 v[64:65], v[66:67], v[64:65]
	v_pk_add_f32 v[18:19], v[84:85], v[18:19]
	v_pk_add_f32 v[44:45], v[78:79], v[76:77]
	v_pk_add_f32 v[10:11], v[52:53], v[10:11]
	v_pk_add_f32 v[8:9], v[50:51], v[8:9]
	v_pk_add_f32 v[16:17], v[42:43], v[16:17]
	v_pk_add_f32 v[14:15], v[64:65], v[14:15]
	v_pk_add_f32 v[12:13], v[62:63], v[12:13]
	v_pk_add_f32 v[18:19], v[44:45], v[18:19]
	v_readlane_b32 s53, v254, 29
	v_readlane_b32 s54, v254, 30
	v_readlane_b32 s55, v254, 31
	v_readlane_b32 s56, v254, 32
	v_readlane_b32 s57, v254, 33
	v_readlane_b32 s58, v254, 34
	v_readlane_b32 s59, v254, 35
	v_readlane_b32 s60, v254, 36
	v_readlane_b32 s61, v254, 37
	v_readlane_b32 s62, v254, 38
	v_readlane_b32 s63, v254, 39
	v_readlane_b32 s66, v254, 42
	v_readlane_b32 s67, v254, 43
	s_waitcnt vmcnt(1)
	v_lshlrev_b32_e32 v1, 16, v90
	v_and_b32_e32 v37, 0xffff0000, v90
	v_lshlrev_b32_e32 v38, 16, v91
	v_and_b32_e32 v39, 0xffff0000, v91
	v_lshlrev_b32_e32 v40, 16, v92
	v_and_b32_e32 v41, 0xffff0000, v92
	v_lshlrev_b32_e32 v42, 16, v93
	v_add_f32_e32 v1, v4, v1
	v_add_f32_e32 v4, v5, v37
	v_add_f32_e32 v5, v6, v38
	v_and_b32_e32 v43, 0xffff0000, v93
	s_waitcnt vmcnt(0)
	v_lshlrev_b32_e32 v44, 16, v94
	v_and_b32_e32 v45, 0xffff0000, v94
	v_lshlrev_b32_e32 v46, 16, v95
	v_and_b32_e32 v47, 0xffff0000, v95
	v_lshlrev_b32_e32 v48, 16, v96
	v_and_b32_e32 v49, 0xffff0000, v96
	v_lshlrev_b32_e32 v50, 16, v97
	v_add_f32_e32 v6, v7, v39
	v_add_f32_e32 v7, v8, v40
	v_add_f32_e32 v8, v9, v41
	v_add_f32_e32 v9, v10, v42
	v_cvt_pk_bf16_f32 v4, v1, v4
	v_cvt_pk_bf16_f32 v5, v5, v6
	v_add_f32_e32 v10, v11, v43
	v_add_f32_e32 v11, v12, v44
	v_add_f32_e32 v12, v13, v45
	v_add_f32_e32 v13, v14, v46
	v_add_f32_e32 v14, v15, v47
	v_add_f32_e32 v15, v16, v48
	v_add_f32_e32 v16, v17, v49
	v_add_f32_e32 v17, v18, v50
	v_cvt_pk_bf16_f32 v6, v7, v8
	v_cvt_pk_bf16_f32 v7, v9, v10
	global_store_dwordx4 v[98:99], v[4:7], off
	v_lshlrev_b32_e32 v1, 16, v4
	v_lshlrev_b32_e32 v9, 16, v5
	v_and_b32_e32 v4, 0xffff0000, v4
	v_and_b32_e32 v5, 0xffff0000, v5
	v_and_b32_e32 v18, 0xffff0000, v6
	v_and_b32_e32 v38, 0xffff0000, v7
	v_lshlrev_b32_e32 v10, 16, v6
	v_lshlrev_b32_e32 v37, 16, v7
	v_cvt_pk_bf16_f32 v6, v11, v12
	v_mul_f32_e32 v4, v4, v4
	v_mul_f32_e32 v5, v5, v5
	v_mul_f32_e32 v11, v18, v18
	v_mul_f32_e32 v12, v38, v38
	v_fmac_f32_e32 v4, v1, v1
	v_fmac_f32_e32 v5, v9, v9
	v_fmac_f32_e32 v11, v10, v10
	v_fmac_f32_e32 v12, v37, v37
	v_add_f32_e32 v1, v4, v5
	v_add_f32_e32 v4, v11, v12
	v_add_f32_e32 v1, v1, v4
	v_and_b32_e32 v4, 0xffff0000, v97
	v_add_f32_e32 v4, v19, v4
	v_and_b32_e32 v5, 0xffff0000, v6
	v_cvt_pk_bf16_f32 v7, v13, v14
	v_cvt_pk_bf16_f32 v8, v15, v16
	v_cvt_pk_bf16_f32 v9, v17, v4
	v_lshlrev_b32_e32 v4, 16, v6
	v_and_b32_e32 v11, 0xffff0000, v7
	v_mul_f32_e32 v5, v5, v5
	v_lshlrev_b32_e32 v10, 16, v7
	v_fmac_f32_e32 v5, v4, v4
	v_mul_f32_e32 v4, v11, v11
	v_and_b32_e32 v13, 0xffff0000, v8
	v_and_b32_e32 v15, 0xffff0000, v9
	v_fmac_f32_e32 v4, v10, v10
	v_lshlrev_b32_e32 v12, 16, v8
	v_lshlrev_b32_e32 v14, 16, v9
	v_add_f32_e32 v4, v5, v4
	v_mul_f32_e32 v5, v13, v13
	v_mul_f32_e32 v10, v15, v15
	v_fmac_f32_e32 v5, v12, v12
	v_fmac_f32_e32 v10, v14, v14
	v_add_f32_e32 v5, v5, v10
	v_add_f32_e32 v4, v4, v5
	v_and_b32_e32 v5, 64, v88
	v_add_f32_e32 v1, v1, v4
	v_xor_b32_e32 v4, 16, v88
	v_add_u32_e32 v5, 64, v5
	v_cmp_lt_i32_e32 vcc, v4, v5
	global_store_dwordx4 v[98:99], v[6:9], off offset:256
	s_nop 0
	v_cndmask_b32_e32 v4, v88, v4, vcc
	v_lshlrev_b32_e32 v4, 2, v4
	ds_bpermute_b32 v4, v4, v1
	s_waitcnt lgkmcnt(0)
	v_add_f32_e32 v1, v1, v4
	v_xor_b32_e32 v4, 32, v88
	v_cmp_lt_i32_e32 vcc, v4, v5
	s_nop 1
	v_cndmask_b32_e32 v4, v88, v4, vcc
	v_lshlrev_b32_e32 v4, 2, v4
	ds_bpermute_b32 v4, v4, v1
	s_and_saveexec_b64 s[8:9], s[0:1]
	s_xor_b64 s[8:9], exec, s[8:9]
	s_cbranch_execz .LBB0_1722
	v_readlane_b32 s52, v254, 28
	s_lshl_b32 s18, s18, 2
	v_lshlrev_b64 v[2:3], 6, v[2:3]
	v_readlane_b32 s66, v254, 42
	v_readlane_b32 s67, v254, 43
	s_ashr_i32 s19, s18, 31
	v_mov_b32_e32 v37, v0
	v_lshl_add_u64 v[2:3], s[66:67], 0, v[2:3]
	v_lshl_add_u64 v[2:3], s[18:19], 2, v[2:3]
	s_waitcnt lgkmcnt(0)
	v_add_f32_e32 v1, v1, v4
	v_lshl_add_u64 v[2:3], v[2:3], 0, v[36:37]
	v_readlane_b32 s53, v254, 29
	v_readlane_b32 s54, v254, 30
	v_readlane_b32 s55, v254, 31
	v_readlane_b32 s56, v254, 32
	v_readlane_b32 s57, v254, 33
	v_readlane_b32 s58, v254, 34
	v_readlane_b32 s59, v254, 35
	v_readlane_b32 s60, v254, 36
	v_readlane_b32 s61, v254, 37
	v_readlane_b32 s62, v254, 38
	v_readlane_b32 s63, v254, 39
	v_readlane_b32 s64, v254, 40
	v_readlane_b32 s65, v254, 41
	global_store_dword v[2:3], v1, off
	s_branch .LBB0_1722

; DI void rinv_pass(const Prm& p, int K, int tid) {
;     SplitOrder S; S.init2(1024, K);
;     for (int pm = blockIdx.x; pm < MP / 256; pm += gridDim.x) {
;         bool tail = false;
;         if (S.S) for (int j = 0; j < S.ntail; ++j) { Unit u; S.map(S.nwhole * S.G + j, u); tail = tail || (u.pm == pm); }
;         if (tid < 256) { const int row = pm * 256 + tid; float v = -1.f;
;             if (!tail) { const f32x4* q = (const f32x4*)(p.SSQ + (size_t)row * 16); const f32x4 a = q[0] + q[1] + q[2] + q[3]; v = rsqrtf(((a.x + a.y) + (a.z + a.w)) * (1.f / 1024.f) + EPSN); }
;             if (row >= NT) v = 1.f;
;             p.RINV[row] = v; }
;     }
; }
.LBB0_1776:
	s_and_saveexec_b64 s[12:13], s[0:1]
	s_cbranch_execz .LBB0_1768
	v_lshl_or_b32 v0, s4, 8, v154
	s_xor_b64 s[6:7], s[10:11], -1
	v_ashrrev_i32_e32 v1, 31, v0
	s_andn2_b64 vcc, exec, s[6:7]
	v_mov_b32_e32 v3, -1.0
	s_cbranch_vccnz .LBB0_1767
	v_readlane_b32 s16, v254, 28
	s_waitcnt lgkmcnt(0)
	v_lshlrev_b64 v[4:5], 6, v[0:1]
	v_readlane_b32 s30, v254, 42
	v_readlane_b32 s31, v254, 43
	v_readlane_b32 s17, v254, 29
	v_readlane_b32 s18, v254, 30
	v_lshl_add_u64 v[16:17], s[30:31], 0, v[4:5]
	global_load_dwordx4 v[4:7], v[16:17], off nt
	global_load_dwordx4 v[8:11], v[16:17], off offset:16 nt
	global_load_dwordx4 v[12:15], v[16:17], off offset:32 nt
	s_nop 0
	global_load_dwordx4 v[16:19], v[16:17], off offset:48 nt
	v_readlane_b32 s19, v254, 31
	v_readlane_b32 s20, v254, 32
	v_readlane_b32 s21, v254, 33
	v_readlane_b32 s22, v254, 34
	v_readlane_b32 s23, v254, 35
	v_readlane_b32 s24, v254, 36
	v_readlane_b32 s25, v254, 37
	v_readlane_b32 s26, v254, 38
	v_readlane_b32 s27, v254, 39
	v_readlane_b32 s28, v254, 40
	v_readlane_b32 s29, v254, 41
	s_waitcnt vmcnt(2)
	v_pk_add_f32 v[6:7], v[6:7], v[10:11]
	v_pk_add_f32 v[4:5], v[4:5], v[8:9]
	s_waitcnt vmcnt(1)
	v_pk_add_f32 v[6:7], v[6:7], v[14:15]
	v_pk_add_f32 v[4:5], v[4:5], v[12:13]
	s_waitcnt vmcnt(0)
	v_pk_add_f32 v[6:7], v[6:7], v[18:19]
	v_pk_add_f32 v[4:5], v[4:5], v[16:17]
	s_nop 0
	v_pk_mov_b32 v[8:9], v[4:5], v[6:7] op_sel:[1,0]
	v_mov_b32_e32 v5, v7
	v_pk_add_f32 v[4:5], v[8:9], v[4:5]
	s_nop 0
	v_add_f32_e32 v3, v4, v5
	v_fmamk_f32 v3, v3, 0x3a800000, v2
	v_mul_f32_e32 v4, 0x4b800000, v3
	v_cmp_gt_f32_e32 vcc, s2, v3
	s_nop 1
	v_cndmask_b32_e32 v3, v3, v4, vcc
	v_rsq_f32_e32 v3, v3
	s_nop 0
	v_mul_f32_e32 v4, 0x45800000, v3
	v_cndmask_b32_e32 v3, v3, v4, vcc
	s_branch .LBB0_1767

; template <class Epi> DI void gemm_fixup(int N, int K, const Epi& E, const float* part, int tid) {
;     ...
;     for (int it = blockIdx.x; it < S.ntail * 8; it += gridDim.x) { const int j = it >> 3, ai = (it >> 2) & 1, m = it & 3; Unit u; S.map(S.nwhole * S.G + j, u);
;         f32x4 a4[2][2];
; #pragma unroll
;         for (int b = 0; b < 2; ++b)
; #pragma unroll
;             for (int n = 0; n < 2; ++n) { const f32x4* pp = (const f32x4*)part + ((size_t)(j * S.S) * 32 + (((ai * 2 + b) * 4 + m) * 2 + n)) * 512 + tid;
;                 f32x4 v0 = {0.f, 0.f, 0.f, 0.f}, v1 = v0, v2 = v0, v3 = v0;
;                 for (int sl = 0; sl + 3 < S.S; sl += 4) { v0 += pp[(size_t)sl * 16384]; v1 += pp[(size_t)(sl + 1) * 16384]; v2 += pp[(size_t)(sl + 2) * 16384]; v3 += pp[(size_t)(sl + 3) * 16384]; }
;                 for (int sl = S.S & ~3; sl < S.S; ++sl) v0 += pp[(size_t)sl * 16384];
;                 a4[b][n] = (v0 + v1) + (v2 + v3); }
.LBB0_2342:
	s_mul_i32 s8, s13, s2
	s_bfe_u32 s6, s5, 0x10002
	s_and_b32 s7, s5, 3
	s_ashr_i32 s9, s8, 31
	s_lshl_b64 s[26:27], s[8:9], 18
	s_lshl_b32 s8, s7, 14
	s_lshl_b32 s9, s6, 17
	s_waitcnt lgkmcnt(0)
	v_lshl_add_u64 v[2:3], v[20:21], 0, s[26:27]
	s_or_b32 s22, s9, s8
	v_lshl_add_u64 v[16:17], v[2:3], 0, s[22:23]
	s_and_b64 vcc, exec, s[10:11]
	s_cbranch_vccz .LBB0_2344
	v_add_co_u32_e32 v6, vcc, 0xc0000, v16
	s_nop 1
	v_addc_co_u32_e32 v7, vcc, 0, v17, vcc
	v_add_co_u32_e32 v2, vcc, 0x80000, v16
	s_nop 1
	v_addc_co_u32_e32 v3, vcc, 0, v17, vcc
	v_add_co_u32_e32 v14, vcc, 0x40000, v16
	global_load_dwordx4 v[2:5], v[2:3], off nt
	s_nop 0
	v_addc_co_u32_e32 v15, vcc, 0, v17, vcc
	global_load_dwordx4 v[6:9], v[6:7], off nt
	s_nop 0
	global_load_dwordx4 v[10:13], v[16:17], off nt
	global_load_dwordx4 v[44:47], v[14:15], off nt
	s_waitcnt vmcnt(3)
	v_pk_add_f32 v[38:39], v[4:5], 0 op_sel_hi:[1,0]
	v_pk_add_f32 v[40:41], v[2:3], 0 op_sel_hi:[1,0]
	s_waitcnt vmcnt(2)
	v_pk_add_f32 v[34:35], v[8:9], 0 op_sel_hi:[1,0]
	v_pk_add_f32 v[36:37], v[6:7], 0 op_sel_hi:[1,0]
	s_waitcnt vmcnt(1)
	v_pk_add_f32 v[6:7], v[12:13], 0 op_sel_hi:[1,0]
	s_waitcnt vmcnt(0)
	v_pk_add_f32 v[42:43], v[46:47], 0 op_sel_hi:[1,0]
	v_pk_add_f32 v[32:33], v[44:45], 0 op_sel_hi:[1,0]
	v_pk_add_f32 v[4:5], v[10:11], 0 op_sel_hi:[1,0]
	s_branch .LBB0_2345

; template <class Epi> DI void gemm_fixup(int N, int K, const Epi& E, const float* part, int tid) {
;     ...
;         for (int b = 0; b < 2; ++b)
; #pragma unroll
;             for (int n = 0; n < 2; ++n) { const f32x4* pp = (const f32x4*)part + ((size_t)(j * S.S) * 32 + (((ai * 2 + b) * 4 + m) * 2 + n)) * 512 + tid;
;                 f32x4 v0 = {0.f, 0.f, 0.f, 0.f}, v1 = v0, v2 = v0, v3 = v0;
;                 for (int sl = 0; sl + 3 < S.S; sl += 4) { v0 += pp[(size_t)sl * 16384]; v1 += pp[(size_t)(sl + 1) * 16384]; v2 += pp[(size_t)(sl + 2) * 16384]; v3 += pp[(size_t)(sl + 3) * 16384]; }
;                 for (int sl = S.S & ~3; sl < S.S; ++sl) v0 += pp[(size_t)sl * 16384];
;                 a4[b][n] = (v0 + v1) + (v2 + v3); }
.LBB0_2347:
	global_load_dwordx4 v[8:11], v[2:3], off nt
	s_add_i32 s13, s13, 1
	v_lshl_add_u64 v[2:3], v[2:3], 0, s[24:25]
	s_cmp_ge_i32 s13, s2
	s_waitcnt vmcnt(0)
	v_pk_add_f32 v[6:7], v[6:7], v[10:11]
	v_pk_add_f32 v[4:5], v[4:5], v[8:9]
	s_cbranch_scc0 .LBB0_2347
.LBB0_2348:
	v_cndmask_b32_e64 v1, 0, 1, s[10:11]
	s_ashr_i32 s16, s12, 3
	v_cmp_ne_u32_e64 s[12:13], 1, v1
	s_andn2_b64 vcc, exec, s[10:11]
	s_cbranch_vccnz .LBB0_2350
	v_add_co_u32_e32 v2, vcc, 0xc2000, v16
	s_nop 1
	v_addc_co_u32_e32 v3, vcc, 0, v17, vcc
	v_add_co_u32_e32 v12, vcc, 0x82000, v16
	s_nop 1
	v_addc_co_u32_e32 v13, vcc, 0, v17, vcc
	global_load_dwordx4 v[8:11], v[2:3], off nt
	s_nop 0
	global_load_dwordx4 v[12:15], v[12:13], off nt
	v_add_co_u32_e32 v2, vcc, 0x42000, v16
	s_waitcnt vmcnt(1)
	v_pk_add_f32 v[52:53], v[10:11], 0 op_sel_hi:[1,0]
	v_addc_co_u32_e32 v3, vcc, 0, v17, vcc
	global_load_dwordx4 v[56:59], v[2:3], off nt
	v_add_co_u32_e32 v2, vcc, 0x2000, v16
	v_pk_add_f32 v[54:55], v[8:9], 0 op_sel_hi:[1,0]
	s_nop 0
	v_addc_co_u32_e32 v3, vcc, 0, v17, vcc
	global_load_dwordx4 v[60:63], v[2:3], off nt
	s_waitcnt vmcnt(2)
	v_pk_add_f32 v[46:47], v[14:15], 0 op_sel_hi:[1,0]
	v_pk_add_f32 v[48:49], v[12:13], 0 op_sel_hi:[1,0]
	s_waitcnt vmcnt(1)
	v_pk_add_f32 v[50:51], v[58:59], 0 op_sel_hi:[1,0]
	v_pk_add_f32 v[44:45], v[56:57], 0 op_sel_hi:[1,0]
	s_waitcnt vmcnt(0)
	v_pk_add_f32 v[10:11], v[62:63], 0 op_sel_hi:[1,0]
	v_pk_add_f32 v[8:9], v[60:61], 0 op_sel_hi:[1,0]
	s_and_b64 vcc, exec, s[8:9]
	s_cbranch_vccz .LBB0_2351
	s_branch .LBB0_2353

; template <class Epi> DI void gemm_fixup(int N, int K, const Epi& E, const float* part, int tid) {
;     ...
;         for (int b = 0; b < 2; ++b)
; #pragma unroll
;             for (int n = 0; n < 2; ++n) { const f32x4* pp = (const f32x4*)part + ((size_t)(j * S.S) * 32 + (((ai * 2 + b) * 4 + m) * 2 + n)) * 512 + tid;
;                 f32x4 v0 = {0.f, 0.f, 0.f, 0.f}, v1 = v0, v2 = v0, v3 = v0;
;                 for (int sl = 0; sl + 3 < S.S; sl += 4) { v0 += pp[(size_t)sl * 16384]; v1 += pp[(size_t)(sl + 1) * 16384]; v2 += pp[(size_t)(sl + 2) * 16384]; v3 += pp[(size_t)(sl + 3) * 16384]; }
;                 for (int sl = S.S & ~3; sl < S.S; ++sl) v0 += pp[(size_t)sl * 16384];
;                 a4[b][n] = (v0 + v1) + (v2 + v3); }
.LBB0_2352:
	global_load_dwordx4 v[12:15], v[2:3], off nt
	s_add_i32 s18, s18, 1
	v_lshl_add_u64 v[2:3], v[2:3], 0, s[24:25]
	s_cmp_lt_i32 s18, s2
	s_waitcnt vmcnt(0)
	v_pk_add_f32 v[10:11], v[10:11], v[14:15]
	v_pk_add_f32 v[8:9], v[8:9], v[12:13]
	s_cbranch_scc1 .LBB0_2352
.LBB0_2353:
	s_and_b64 vcc, exec, s[12:13]
	s_cbranch_vccnz .LBB0_2355
	v_add_co_u32_e32 v2, vcc, 0xd0000, v16
	s_nop 1
	v_addc_co_u32_e32 v3, vcc, 0, v17, vcc
	v_add_co_u32_e32 v18, vcc, 0x90000, v16
	s_nop 1
	v_addc_co_u32_e32 v19, vcc, 0, v17, vcc
	global_load_dwordx4 v[12:15], v[2:3], off nt
	global_load_dwordx4 v[56:59], v[18:19], off nt
	v_add_co_u32_e32 v2, vcc, 0x50000, v16
	s_waitcnt vmcnt(1)
	v_pk_add_f32 v[64:65], v[14:15], 0 op_sel_hi:[1,0]
	v_addc_co_u32_e32 v3, vcc, 0, v17, vcc
	global_load_dwordx4 v[68:71], v[2:3], off nt
	v_add_co_u32_e32 v2, vcc, 0x10000, v16
	v_pk_add_f32 v[66:67], v[12:13], 0 op_sel_hi:[1,0]
	s_nop 0
	v_addc_co_u32_e32 v3, vcc, 0, v17, vcc
	global_load_dwordx4 v[72:75], v[2:3], off nt
	s_waitcnt vmcnt(2)
	v_pk_add_f32 v[58:59], v[58:59], 0 op_sel_hi:[1,0]
	v_pk_add_f32 v[60:61], v[56:57], 0 op_sel_hi:[1,0]
	s_waitcnt vmcnt(1)
	v_pk_add_f32 v[62:63], v[70:71], 0 op_sel_hi:[1,0]
	v_pk_add_f32 v[56:57], v[68:69], 0 op_sel_hi:[1,0]
	s_waitcnt vmcnt(0)
	v_pk_add_f32 v[14:15], v[74:75], 0 op_sel_hi:[1,0]
	v_pk_add_f32 v[12:13], v[72:73], 0 op_sel_hi:[1,0]
	s_and_b64 vcc, exec, s[8:9]
	s_cbranch_vccz .LBB0_2356
	s_branch .LBB0_2358

; template <class Epi> DI void gemm_fixup(int N, int K, const Epi& E, const float* part, int tid) {
;     ...
;         for (int b = 0; b < 2; ++b)
; #pragma unroll
;             for (int n = 0; n < 2; ++n) { const f32x4* pp = (const f32x4*)part + ((size_t)(j * S.S) * 32 + (((ai * 2 + b) * 4 + m) * 2 + n)) * 512 + tid;
;                 f32x4 v0 = {0.f, 0.f, 0.f, 0.f}, v1 = v0, v2 = v0, v3 = v0;
;                 for (int sl = 0; sl + 3 < S.S; sl += 4) { v0 += pp[(size_t)sl * 16384]; v1 += pp[(size_t)(sl + 1) * 16384]; v2 += pp[(size_t)(sl + 2) * 16384]; v3 += pp[(size_t)(sl + 3) * 16384]; }
;                 for (int sl = S.S & ~3; sl < S.S; ++sl) v0 += pp[(size_t)sl * 16384];
;                 a4[b][n] = (v0 + v1) + (v2 + v3); }
.LBB0_2357:
	global_load_dwordx4 v[68:71], v[2:3], off nt
	s_add_i32 s18, s18, 1
	v_lshl_add_u64 v[2:3], v[2:3], 0, s[24:25]
	s_cmp_lt_i32 s18, s2
	s_waitcnt vmcnt(0)
	v_pk_add_f32 v[14:15], v[14:15], v[70:71]
	v_pk_add_f32 v[12:13], v[12:13], v[68:69]
	s_cbranch_scc1 .LBB0_2357
.LBB0_2358:
	s_and_b64 vcc, exec, s[12:13]
	s_cbranch_vccnz .LBB0_2360
	v_add_co_u32_e32 v2, vcc, 0xd2000, v16
	s_nop 1
	v_addc_co_u32_e32 v3, vcc, 0, v17, vcc
	v_add_co_u32_e32 v18, vcc, 0x92000, v16
	s_nop 1
	v_addc_co_u32_e32 v19, vcc, 0, v17, vcc
	global_load_dwordx4 v[68:71], v[2:3], off nt
	global_load_dwordx4 v[84:87], v[18:19], off nt
	v_add_co_u32_e32 v2, vcc, 0x52000, v16
	s_waitcnt vmcnt(1)
	v_pk_add_f32 v[74:75], v[70:71], 0 op_sel_hi:[1,0]
	v_addc_co_u32_e32 v3, vcc, 0, v17, vcc
	global_load_dwordx4 v[88:91], v[2:3], off nt
	v_add_co_u32_e32 v2, vcc, 0x12000, v16
	v_pk_add_f32 v[76:77], v[68:69], 0 op_sel_hi:[1,0]
	s_nop 0
	v_addc_co_u32_e32 v3, vcc, 0, v17, vcc
	global_load_dwordx4 v[16:19], v[2:3], off nt
	s_waitcnt vmcnt(2)
	v_pk_add_f32 v[2:3], v[86:87], 0 op_sel_hi:[1,0]
	v_pk_add_f32 v[70:71], v[84:85], 0 op_sel_hi:[1,0]
	s_waitcnt vmcnt(1)
	v_pk_add_f32 v[72:73], v[90:91], 0 op_sel_hi:[1,0]
	v_pk_add_f32 v[68:69], v[88:89], 0 op_sel_hi:[1,0]
	s_waitcnt vmcnt(0)
	v_pk_add_f32 v[18:19], v[18:19], 0 op_sel_hi:[1,0]
	v_pk_add_f32 v[16:17], v[16:17], 0 op_sel_hi:[1,0]
	s_and_b64 vcc, exec, s[8:9]
	s_cbranch_vccz .LBB0_2361
	s_branch .LBB0_2363

; DI unsigned pk2(float lo, float hi) { unsigned r; asm volatile("v_cvt_pk_bf16_f32 %0, %1, %2" : "=v"(r) : "v"(lo), "v"(hi)); return r; }
; DI float bflo(unsigned u) { return __uint_as_float(u << 16); }
;     DI float upd(u32x4v* px, const u32x4v x, const f32x4 v0, const f32x4 v1) const {
;         u32x4v o; o.x = pk2(bflo(x.x) + v0[0], bfhi(x.x) + v0[1]); o.y = pk2(bflo(x.y) + v0[2], bfhi(x.y) + v0[3]);
;         o.z = pk2(bflo(x.z) + v1[0], bfhi(x.z) + v1[1]); o.w = pk2(bflo(x.w) + v1[2], bfhi(x.w) + v1[3]); *px = o;
;         const float a0 = bflo(o.x), a1 = bfhi(o.x), a2 = bflo(o.y), a3 = bfhi(o.y), a4 = bflo(o.z), a5 = bfhi(o.z), a6 = bflo(o.w), a7 = bfhi(o.w);
;         return ((a0 * a0 + a1 * a1) + (a2 * a2 + a3 * a3)) + ((a4 * a4 + a5 * a5) + (a6 * a6 + a7 * a7));
;     }
;     DI void row(const f32x4 (&a4)[2][2], const Unit& u, int ai, int m, int wr, int wc, int fr, int fq) const {
;         const int cb = u.pn * 256 + wc * 32 + 8 * fq, row = u.pm * 256 + wr * 64 + fr + ai * 128 + m * 16;
;         u32x4v* p0 = (u32x4v*)(XB + (size_t)row * 1024 + cb); u32x4v* p1 = (u32x4v*)(XB + (size_t)row * 1024 + cb + 128);
;         const u32x4v x0 = *p0, x1 = *p1;
;         float ss = upd(p0, x0, a4[0][0], a4[0][1]) + upd(p1, x1, a4[1][0], a4[1][1]);
;         ss += __shfl_xor(ss, 16); ss += __shfl_xor(ss, 32);
;         if (fq == 0) SSQ[(size_t)row * 16 + u.pn * 4 + wc] = ss;
;     }
; template <class Epi> DI void gemm_fixup(int N, int K, const Epi& E, const float* part, int tid) {
;     ...
;     for (int it = blockIdx.x; it < S.ntail * 8; it += gridDim.x) { const int j = it >> 3, ai = (it >> 2) & 1, m = it & 3; Unit u; S.map(S.nwhole * S.G + j, u);
;         f32x4 a4[2][2];
; #pragma unroll
;         for (int b = 0; b < 2; ++b)
; #pragma unroll
;             for (int n = 0; n < 2; ++n) { const f32x4* pp = (const f32x4*)part + ((size_t)(j * S.S) * 32 + (((ai * 2 + b) * 4 + m) * 2 + n)) * 512 + tid;
;                 f32x4 v0 = {0.f, 0.f, 0.f, 0.f}, v1 = v0, v2 = v0, v3 = v0;
;                 for (int sl = 0; sl + 3 < S.S; sl += 4) { v0 += pp[(size_t)sl * 16384]; v1 += pp[(size_t)(sl + 1) * 16384]; v2 += pp[(size_t)(sl + 2) * 16384]; v3 += pp[(size_t)(sl + 3) * 16384]; }
;                 for (int sl = S.S & ~3; sl < S.S; ++sl) v0 += pp[(size_t)sl * 16384];
;                 a4[b][n] = (v0 + v1) + (v2 + v3); }
;         E.row(a4, u, ai, m, wr, wc, fr, fq); }
.LBB0_2362:
	global_load_dwordx4 v[84:87], v[78:79], off nt
	s_add_i32 s8, s8, 1
	v_lshl_add_u64 v[78:79], v[78:79], 0, s[24:25]
	s_cmp_lt_i32 s8, s2
	s_waitcnt vmcnt(0)
	v_pk_add_f32 v[18:19], v[18:19], v[86:87]
	v_pk_add_f32 v[16:17], v[16:17], v[84:85]
	s_cbranch_scc1 .LBB0_2362
.LBB0_2363:
	s_add_i32 s8, s15, s16
	s_ashr_i32 s9, s8, 31
	s_lshr_b32 s9, s9, 27
	s_add_i32 s9, s8, s9
	s_ashr_i32 s12, s9, 5
	s_lshl_b32 s13, s12, 3
	s_sub_i32 s12, 0x83, s13
	s_min_i32 s15, s12, 8
	s_abs_i32 s12, s15
	v_cvt_f32_u32_e32 v1, s12
	s_sub_i32 s17, 0, s12
	s_andn2_b32 s9, s9, 31
	s_sub_i32 s8, s8, s9
	v_rcp_iflag_f32_e32 v1, v1
	s_abs_i32 s9, s8
	s_xor_b32 s16, s8, s15
	s_ashr_i32 s16, s16, 31
	v_mul_f32_e32 v1, 0x4f7ffffe, v1
	v_cvt_u32_f32_e32 v1, v1
	v_readlane_b32 s40, v254, 28
	v_readlane_b32 s52, v254, 40
	v_readlane_b32 s53, v254, 41
	v_readfirstlane_b32 s18, v1
	s_mul_i32 s17, s17, s18
	s_mul_hi_u32 s17, s18, s17
	s_add_i32 s18, s18, s17
	s_mul_hi_u32 s17, s9, s18
	s_mul_i32 s18, s17, s12
	s_sub_i32 s9, s9, s18
	s_add_i32 s19, s17, 1
	s_sub_i32 s18, s9, s12
	s_cmp_ge_u32 s9, s12
	s_cselect_b32 s17, s19, s17
	s_cselect_b32 s9, s18, s9
	s_add_i32 s18, s17, 1
	s_cmp_ge_u32 s9, s12
	s_cselect_b32 s9, s18, s17
	s_xor_b32 s9, s9, s16
	s_sub_i32 s12, s9, s16
	s_mul_i32 s9, s12, s15
	s_sub_i32 s8, s8, s9
	s_add_i32 s13, s13, s8
	s_lshl_b32 s8, s13, 8
	s_lshl_b32 s6, s6, 7
	v_lshl_or_b32 v1, s7, 4, v81
	s_or_b32 s6, s8, s6
	v_add_u32_e32 v78, s6, v1
	v_ashrrev_i32_e32 v79, 31, v78
	v_lshl_or_b32 v84, s12, 8, v80
	v_lshlrev_b64 v[86:87], 11, v[78:79]
	v_lshl_add_u64 v[86:87], s[52:53], 0, v[86:87]
	v_ashrrev_i32_e32 v85, 31, v84
	v_lshl_add_u64 v[92:93], v[84:85], 1, v[86:87]
	global_load_dwordx4 v[84:87], v[92:93], off nt
	global_load_dwordx4 v[88:91], v[92:93], off offset:256 nt
	v_pk_add_f32 v[14:15], v[62:63], v[14:15]
	v_pk_add_f32 v[12:13], v[56:57], v[12:13]
	v_pk_add_f32 v[56:57], v[60:61], v[66:67]
	v_pk_add_f32 v[58:59], v[58:59], v[64:65]
	v_pk_add_f32 v[10:11], v[50:51], v[10:11]
	v_pk_add_f32 v[8:9], v[44:45], v[8:9]
	v_pk_add_f32 v[44:45], v[48:49], v[54:55]
	v_pk_add_f32 v[46:47], v[46:47], v[52:53]
	v_pk_add_f32 v[6:7], v[42:43], v[6:7]
	v_pk_add_f32 v[4:5], v[32:33], v[4:5]
	v_pk_add_f32 v[32:33], v[40:41], v[36:37]
	v_pk_add_f32 v[34:35], v[38:39], v[34:35]
	v_pk_add_f32 v[18:19], v[72:73], v[18:19]
	v_pk_add_f32 v[16:17], v[68:69], v[16:17]
	v_pk_add_f32 v[36:37], v[70:71], v[76:77]
	v_pk_add_f32 v[2:3], v[2:3], v[74:75]
	v_pk_add_f32 v[14:15], v[58:59], v[14:15]
	v_pk_add_f32 v[12:13], v[56:57], v[12:13]
	v_pk_add_f32 v[10:11], v[46:47], v[10:11]
	v_pk_add_f32 v[8:9], v[44:45], v[8:9]
	v_pk_add_f32 v[6:7], v[34:35], v[6:7]
	v_pk_add_f32 v[4:5], v[32:33], v[4:5]
	v_pk_add_f32 v[2:3], v[2:3], v[18:19]
	v_pk_add_f32 v[16:17], v[36:37], v[16:17]
	v_readlane_b32 s41, v254, 29
	v_readlane_b32 s42, v254, 30
	v_readlane_b32 s43, v254, 31
	v_readlane_b32 s44, v254, 32
	v_readlane_b32 s45, v254, 33
	v_readlane_b32 s46, v254, 34
	v_readlane_b32 s47, v254, 35
	v_readlane_b32 s48, v254, 36
	v_readlane_b32 s49, v254, 37
	v_readlane_b32 s50, v254, 38
	v_readlane_b32 s51, v254, 39
	v_readlane_b32 s54, v254, 42
	v_readlane_b32 s55, v254, 43
	s_waitcnt vmcnt(1)
	v_lshlrev_b32_e32 v1, 16, v84
	v_and_b32_e32 v18, 0xffff0000, v84
	v_lshlrev_b32_e32 v19, 16, v85
	v_and_b32_e32 v31, 0xffff0000, v85
	v_lshlrev_b32_e32 v32, 16, v86
	v_and_b32_e32 v33, 0xffff0000, v86
	v_lshlrev_b32_e32 v34, 16, v87
	v_and_b32_e32 v35, 0xffff0000, v87
	s_waitcnt vmcnt(0)
	v_lshlrev_b32_e32 v36, 16, v88
	v_and_b32_e32 v37, 0xffff0000, v88
	v_lshlrev_b32_e32 v38, 16, v89
	v_and_b32_e32 v39, 0xffff0000, v89
	v_lshlrev_b32_e32 v40, 16, v90
	v_and_b32_e32 v41, 0xffff0000, v90
	v_lshlrev_b32_e32 v42, 16, v91
	v_and_b32_e32 v43, 0xffff0000, v91
	v_add_f32_e32 v1, v4, v1
	v_add_f32_e32 v4, v5, v18
	v_add_f32_e32 v5, v6, v19
	v_add_f32_e32 v6, v7, v31
	v_add_f32_e32 v7, v8, v32
	v_add_f32_e32 v8, v9, v33
	v_add_f32_e32 v9, v10, v34
	v_add_f32_e32 v10, v11, v35
	v_add_f32_e32 v11, v12, v36
	v_add_f32_e32 v12, v13, v37
	v_add_f32_e32 v13, v14, v38
	v_add_f32_e32 v14, v15, v39
	v_add_f32_e32 v15, v16, v40
	v_add_f32_e32 v16, v17, v41
	v_add_f32_e32 v17, v2, v42
	v_add_f32_e32 v18, v3, v43
	v_cvt_pk_bf16_f32 v2, v1, v4
	v_cvt_pk_bf16_f32 v3, v5, v6
	v_cvt_pk_bf16_f32 v4, v7, v8
	v_cvt_pk_bf16_f32 v5, v9, v10
	global_store_dwordx4 v[92:93], v[2:5], off
	v_lshlrev_b32_e32 v1, 16, v2
	v_lshlrev_b32_e32 v7, 16, v3
	v_and_b32_e32 v2, 0xffff0000, v2
	v_and_b32_e32 v3, 0xffff0000, v3
	v_and_b32_e32 v9, 0xffff0000, v4
	v_and_b32_e32 v19, 0xffff0000, v5
	v_lshlrev_b32_e32 v8, 16, v4
	v_lshlrev_b32_e32 v10, 16, v5
	v_cvt_pk_bf16_f32 v4, v11, v12
	v_mul_f32_e32 v2, v2, v2
	v_mul_f32_e32 v3, v3, v3
	v_mul_f32_e32 v9, v9, v9
	v_mul_f32_e32 v11, v19, v19
	v_fmac_f32_e32 v2, v1, v1
	v_fmac_f32_e32 v3, v7, v7
	v_fmac_f32_e32 v9, v8, v8
	v_fmac_f32_e32 v11, v10, v10
	v_add_f32_e32 v1, v2, v3
	v_add_f32_e32 v2, v9, v11
	v_and_b32_e32 v3, 0xffff0000, v4
	v_cvt_pk_bf16_f32 v5, v13, v14
	v_add_f32_e32 v1, v1, v2
	v_lshlrev_b32_e32 v2, 16, v4
	v_and_b32_e32 v9, 0xffff0000, v5
	v_mul_f32_e32 v3, v3, v3
	v_lshlrev_b32_e32 v8, 16, v5
	v_fmac_f32_e32 v3, v2, v2
	v_mul_f32_e32 v2, v9, v9
	v_cvt_pk_bf16_f32 v6, v15, v16
	v_cvt_pk_bf16_f32 v7, v17, v18
	v_fmac_f32_e32 v2, v8, v8
	v_and_b32_e32 v11, 0xffff0000, v6
	v_and_b32_e32 v13, 0xffff0000, v7
	v_lshlrev_b32_e32 v10, 16, v6
	v_lshlrev_b32_e32 v12, 16, v7
	v_add_f32_e32 v2, v3, v2
	v_mul_f32_e32 v3, v11, v11
	v_mul_f32_e32 v8, v13, v13
	v_fmac_f32_e32 v3, v10, v10
	v_fmac_f32_e32 v8, v12, v12
	v_add_f32_e32 v3, v3, v8
	v_add_f32_e32 v2, v2, v3
	v_and_b32_e32 v3, 64, v82
	v_add_f32_e32 v1, v1, v2
	v_xor_b32_e32 v2, 16, v82
	v_add_u32_e32 v3, 64, v3
	v_cmp_lt_i32_e32 vcc, v2, v3
	global_store_dwordx4 v[92:93], v[4:7], off offset:256
	s_nop 0
	v_cndmask_b32_e32 v2, v82, v2, vcc
	v_lshlrev_b32_e32 v2, 2, v2
	ds_bpermute_b32 v2, v2, v1
	s_waitcnt lgkmcnt(0)
	v_add_f32_e32 v1, v1, v2
	v_xor_b32_e32 v2, 32, v82
	v_cmp_lt_i32_e32 vcc, v2, v3
	s_nop 1
	v_cndmask_b32_e32 v2, v82, v2, vcc
	v_lshlrev_b32_e32 v2, 2, v2
	ds_bpermute_b32 v2, v2, v1
	s_and_saveexec_b64 s[6:7], s[0:1]
	s_xor_b64 s[8:9], exec, s[6:7]
	s_cbranch_execz .LBB0_2337
	v_readlane_b32 s40, v254, 28
	s_waitcnt lgkmcnt(0)
	v_add_f32_e32 v1, v1, v2
	s_lshl_b32 s6, s12, 2
	v_lshlrev_b64 v[2:3], 6, v[78:79]
	v_readlane_b32 s54, v254, 42
	v_readlane_b32 s55, v254, 43
	s_ashr_i32 s7, s6, 31
	v_mov_b32_e32 v31, v0
	v_lshl_add_u64 v[2:3], s[54:55], 0, v[2:3]
	v_lshl_add_u64 v[2:3], s[6:7], 2, v[2:3]
	v_lshl_add_u64 v[2:3], v[2:3], 0, v[30:31]
	v_readlane_b32 s41, v254, 29
	v_readlane_b32 s42, v254, 30
	v_readlane_b32 s43, v254, 31
	v_readlane_b32 s44, v254, 32
	v_readlane_b32 s45, v254, 33
	v_readlane_b32 s46, v254, 34
	v_readlane_b32 s47, v254, 35
	v_readlane_b32 s48, v254, 36
	v_readlane_b32 s49, v254, 37
	v_readlane_b32 s50, v254, 38
	v_readlane_b32 s51, v254, 39
	v_readlane_b32 s52, v254, 40
	v_readlane_b32 s53, v254, 41
	global_store_dword v[2:3], v1, off
	s_branch .LBB0_2337

; DI void rinv_pass(const Prm& p, int K, int tid) {
;     SplitOrder S; S.init2(1024, K);
;     for (int pm = blockIdx.x; pm < MP / 256; pm += gridDim.x) {
;         bool tail = false;
;         if (S.S) for (int j = 0; j < S.ntail; ++j) { Unit u; S.map(S.nwhole * S.G + j, u); tail = tail || (u.pm == pm); }
;         if (tid < 256) { const int row = pm * 256 + tid; float v = -1.f;
;             if (!tail) { const f32x4* q = (const f32x4*)(p.SSQ + (size_t)row * 16); const f32x4 a = q[0] + q[1] + q[2] + q[3]; v = rsqrtf(((a.x + a.y) + (a.z + a.w)) * (1.f / 1024.f) + EPSN); }
;             if (row >= NT) v = 1.f;
;             p.RINV[row] = v; }
;     }
; }
.LBB0_2384:
	s_and_saveexec_b64 s[10:11], s[0:1]
	s_cbranch_execz .LBB0_2376
	v_lshl_or_b32 v0, s4, 8, v154
	s_xor_b64 s[8:9], s[8:9], -1
	v_ashrrev_i32_e32 v1, 31, v0
	s_andn2_b64 vcc, exec, s[8:9]
	v_mov_b32_e32 v3, -1.0
	s_cbranch_vccnz .LBB0_2375
	v_readlane_b32 s12, v254, 28
	v_lshlrev_b64 v[4:5], 6, v[0:1]
	v_readlane_b32 s26, v254, 42
	v_readlane_b32 s27, v254, 43
	v_readlane_b32 s13, v254, 29
	v_readlane_b32 s14, v254, 30
	v_lshl_add_u64 v[20:21], s[26:27], 0, v[4:5]
	global_load_dwordx4 v[4:7], v[20:21], off nt
	global_load_dwordx4 v[8:11], v[20:21], off offset:16 nt
	global_load_dwordx4 v[12:15], v[20:21], off offset:32 nt
	global_load_dwordx4 v[16:19], v[20:21], off offset:48 nt
	v_readlane_b32 s15, v254, 31
	v_readlane_b32 s16, v254, 32
	v_readlane_b32 s17, v254, 33
	v_readlane_b32 s18, v254, 34
	v_readlane_b32 s19, v254, 35
	v_readlane_b32 s20, v254, 36
	v_readlane_b32 s21, v254, 37
	v_readlane_b32 s22, v254, 38
	v_readlane_b32 s23, v254, 39
	v_readlane_b32 s24, v254, 40
	v_readlane_b32 s25, v254, 41
	s_waitcnt vmcnt(2)
	v_pk_add_f32 v[6:7], v[6:7], v[10:11]
	v_pk_add_f32 v[4:5], v[4:5], v[8:9]
	s_waitcnt vmcnt(1)
	v_pk_add_f32 v[6:7], v[6:7], v[14:15]
	v_pk_add_f32 v[4:5], v[4:5], v[12:13]
	s_waitcnt vmcnt(0)
	v_pk_add_f32 v[6:7], v[6:7], v[18:19]
	v_pk_add_f32 v[4:5], v[4:5], v[16:17]
	s_nop 0
	v_pk_mov_b32 v[8:9], v[4:5], v[6:7] op_sel:[1,0]
	v_mov_b32_e32 v5, v7
	v_pk_add_f32 v[4:5], v[8:9], v[4:5]
	s_nop 0
	v_add_f32_e32 v3, v4, v5
	v_fmamk_f32 v3, v3, 0x3a800000, v2
	v_mul_f32_e32 v4, 0x4b800000, v3
	v_cmp_gt_f32_e32 vcc, s2, v3
	s_nop 1
	v_cndmask_b32_e32 v3, v3, v4, vcc
	v_rsq_f32_e32 v3, v3
	s_nop 0
	v_mul_f32_e32 v4, 0x45800000, v3
	v_cndmask_b32_e32 v3, v3, v4, vcc
	s_branch .LBB0_2375

; template <class Epi> DI void gemm_fixup(int N, int K, const Epi& E, const float* part, int tid) {
;     ...
;         for (int b = 0; b < 2; ++b)
; #pragma unroll
;             for (int n = 0; n < 2; ++n) { const f32x4* pp = (const f32x4*)part + ((size_t)(j * S.S) * 32 + (((ai * 2 + b) * 4 + m) * 2 + n)) * 512 + tid;
;                 f32x4 v0 = {0.f, 0.f, 0.f, 0.f}, v1 = v0, v2 = v0, v3 = v0;
;                 for (int sl = 0; sl + 3 < S.S; sl += 4) { v0 += pp[(size_t)sl * 16384]; v1 += pp[(size_t)(sl + 1) * 16384]; v2 += pp[(size_t)(sl + 2) * 16384]; v3 += pp[(size_t)(sl + 3) * 16384]; }
;                 for (int sl = S.S & ~3; sl < S.S; ++sl) v0 += pp[(size_t)sl * 16384];
;                 a4[b][n] = (v0 + v1) + (v2 + v3); }
.LBB0_2665:
	s_and_b32 s4, s20, 3
	s_lshl_b32 s5, s84, 15
	s_and_b32 s5, s5, 0x20000
	s_lshl_b32 s4, s4, 14
	s_or_b32 s22, s5, s4
	s_mul_i32 s4, s14, s16
	s_ashr_i32 s5, s4, 31
	s_and_b64 vcc, exec, s[2:3]
	s_lshl_b64 s[14:15], s[4:5], 18
	s_cbranch_vccnz .LBB0_2668
	s_add_u32 s4, s14, s22
	s_addc_u32 s5, s15, 0
	v_mov_b32_e32 v38, 0
	v_lshl_add_u64 v[2:3], v[20:21], 0, s[4:5]
	s_mov_b32 s4, 3
	v_mov_b32_e32 v39, v38
	v_mov_b32_e32 v40, v38
	v_mov_b32_e32 v41, v38
	v_mov_b32_e32 v44, v38
	v_mov_b32_e32 v45, v38
	v_mov_b32_e32 v42, v38
	v_mov_b32_e32 v43, v38
	v_mov_b32_e32 v46, v38
	v_mov_b32_e32 v47, v38
	v_mov_b32_e32 v48, v38
	v_mov_b32_e32 v49, v38
	s_waitcnt lgkmcnt(0)
	v_mov_b32_e32 v4, v38
	v_mov_b32_e32 v5, v38
	v_mov_b32_e32 v6, v38
	v_mov_b32_e32 v7, v38
	s_cmp_eq_u32 s16, 16
	s_cbranch_scc0 .LBB0_2667
	v_add_co_u32_e32 v54, vcc, s7, v2
	global_load_dwordx4 v[8:11], v[2:3], off nt
	s_nop 0
	v_addc_co_u32_e32 v55, vcc, -1, v3, vcc
	v_add_co_u32_e32 v56, vcc, s18, v2
	s_nop 0
	s_nop 0
	v_addc_co_u32_e32 v57, vcc, -1, v3, vcc
	v_add_co_u32_e32 v58, vcc, s19, v2
	s_nop 0
	s_nop 0
	v_addc_co_u32_e32 v59, vcc, 0, v3, vcc
	global_load_dwordx4 v[12:15], v[54:55], off nt
	global_load_dwordx4 v[16:19], v[56:57], off nt
	global_load_dwordx4 v[50:53], v[58:59], off nt
	v_lshl_add_u64 v[2:3], v[2:3], 0, s[10:11]
	v_add_co_u32_e32 v54, vcc, s7, v2
	global_load_dwordx4 v[184:187], v[2:3], off nt
	s_nop 0
	v_addc_co_u32_e32 v55, vcc, -1, v3, vcc
	v_add_co_u32_e32 v56, vcc, s18, v2
	s_nop 0
	s_nop 0
	v_addc_co_u32_e32 v57, vcc, -1, v3, vcc
	v_add_co_u32_e32 v58, vcc, s19, v2
	s_nop 0
	s_nop 0
	v_addc_co_u32_e32 v59, vcc, 0, v3, vcc
	global_load_dwordx4 v[188:191], v[54:55], off nt
	global_load_dwordx4 v[192:195], v[56:57], off nt
	global_load_dwordx4 v[196:199], v[58:59], off nt
	v_lshl_add_u64 v[2:3], v[2:3], 0, s[10:11]
	v_add_co_u32_e32 v54, vcc, s7, v2
	global_load_dwordx4 v[200:203], v[2:3], off nt
	s_nop 0
	v_addc_co_u32_e32 v55, vcc, -1, v3, vcc
	v_add_co_u32_e32 v56, vcc, s18, v2
	s_nop 0
	s_nop 0
	v_addc_co_u32_e32 v57, vcc, -1, v3, vcc
	v_add_co_u32_e32 v58, vcc, s19, v2
	s_nop 0
	s_nop 0
	v_addc_co_u32_e32 v59, vcc, 0, v3, vcc
	global_load_dwordx4 v[204:207], v[54:55], off nt
	global_load_dwordx4 v[208:211], v[56:57], off nt
	global_load_dwordx4 v[212:215], v[58:59], off nt
	v_lshl_add_u64 v[2:3], v[2:3], 0, s[10:11]
	v_add_co_u32_e32 v54, vcc, s7, v2
	global_load_dwordx4 v[216:219], v[2:3], off nt
	s_nop 0
	v_addc_co_u32_e32 v55, vcc, -1, v3, vcc
	v_add_co_u32_e32 v56, vcc, s18, v2
	s_nop 0
	s_nop 0
	v_addc_co_u32_e32 v57, vcc, -1, v3, vcc
	v_add_co_u32_e32 v58, vcc, s19, v2
	s_nop 0
	s_nop 0
	v_addc_co_u32_e32 v59, vcc, 0, v3, vcc
	global_load_dwordx4 v[220:223], v[54:55], off nt
	global_load_dwordx4 v[224:227], v[56:57], off nt
	global_load_dwordx4 v[228:231], v[58:59], off nt
	v_lshl_add_u64 v[2:3], v[2:3], 0, s[10:11]
	s_waitcnt vmcnt(12)
	v_pk_add_f32 v[42:43], v[42:43], v[10:11]
	v_pk_add_f32 v[44:45], v[44:45], v[8:9]
	v_pk_add_f32 v[6:7], v[6:7], v[14:15]
	v_pk_add_f32 v[4:5], v[4:5], v[12:13]
	v_pk_add_f32 v[48:49], v[48:49], v[18:19]
	v_pk_add_f32 v[46:47], v[46:47], v[16:17]
	v_pk_add_f32 v[40:41], v[40:41], v[52:53]
	v_pk_add_f32 v[38:39], v[38:39], v[50:51]
	s_waitcnt vmcnt(8)
	v_pk_add_f32 v[42:43], v[42:43], v[186:187]
	v_pk_add_f32 v[44:45], v[44:45], v[184:185]
	v_pk_add_f32 v[6:7], v[6:7], v[190:191]
	v_pk_add_f32 v[4:5], v[4:5], v[188:189]
	v_pk_add_f32 v[48:49], v[48:49], v[194:195]
	v_pk_add_f32 v[46:47], v[46:47], v[192:193]
	v_pk_add_f32 v[40:41], v[40:41], v[198:199]
	v_pk_add_f32 v[38:39], v[38:39], v[196:197]
	s_waitcnt vmcnt(4)
	v_pk_add_f32 v[42:43], v[42:43], v[202:203]
	v_pk_add_f32 v[44:45], v[44:45], v[200:201]
	v_pk_add_f32 v[6:7], v[6:7], v[206:207]
	v_pk_add_f32 v[4:5], v[4:5], v[204:205]
	v_pk_add_f32 v[48:49], v[48:49], v[210:211]
	v_pk_add_f32 v[46:47], v[46:47], v[208:209]
	v_pk_add_f32 v[40:41], v[40:41], v[214:215]
	v_pk_add_f32 v[38:39], v[38:39], v[212:213]
	s_waitcnt vmcnt(0)
	v_pk_add_f32 v[42:43], v[42:43], v[218:219]
	v_pk_add_f32 v[44:45], v[44:45], v[216:217]
	v_pk_add_f32 v[6:7], v[6:7], v[222:223]
	v_pk_add_f32 v[4:5], v[4:5], v[220:221]
	v_pk_add_f32 v[48:49], v[48:49], v[226:227]
	v_pk_add_f32 v[46:47], v[46:47], v[224:225]
	v_pk_add_f32 v[40:41], v[40:41], v[230:231]
	v_pk_add_f32 v[38:39], v[38:39], v[228:229]
	s_branch .Lfx_after_3
.LBB0_2667:
	v_add_co_u32_e32 v54, vcc, s7, v2
	global_load_dwordx4 v[8:11], v[2:3], off nt
	s_nop 0
	v_addc_co_u32_e32 v55, vcc, -1, v3, vcc
	v_add_co_u32_e32 v56, vcc, s18, v2
	s_add_i32 s4, s4, 4
	s_nop 0
	v_addc_co_u32_e32 v57, vcc, -1, v3, vcc
	v_add_co_u32_e32 v58, vcc, s19, v2
	s_cmp_ge_i32 s4, s16
	s_nop 0
	v_addc_co_u32_e32 v59, vcc, 0, v3, vcc
	global_load_dwordx4 v[12:15], v[54:55], off nt
	global_load_dwordx4 v[16:19], v[56:57], off nt
	global_load_dwordx4 v[50:53], v[58:59], off nt
	v_lshl_add_u64 v[2:3], v[2:3], 0, s[10:11]
	s_waitcnt vmcnt(3)
	v_pk_add_f32 v[42:43], v[42:43], v[10:11]
	v_pk_add_f32 v[44:45], v[44:45], v[8:9]
	s_waitcnt vmcnt(2)
	v_pk_add_f32 v[6:7], v[6:7], v[14:15]
	v_pk_add_f32 v[4:5], v[4:5], v[12:13]
	s_waitcnt vmcnt(1)
	v_pk_add_f32 v[48:49], v[48:49], v[18:19]
	v_pk_add_f32 v[46:47], v[46:47], v[16:17]
	s_waitcnt vmcnt(0)
	v_pk_add_f32 v[40:41], v[40:41], v[52:53]
	v_pk_add_f32 v[38:39], v[38:39], v[50:51]
	s_cbranch_scc0 .LBB0_2667

; template <class Epi> DI void gemm_fixup(int N, int K, const Epi& E, const float* part, int tid) {
;     ...
;         for (int b = 0; b < 2; ++b)
; #pragma unroll
;             for (int n = 0; n < 2; ++n) { const f32x4* pp = (const f32x4*)part + ((size_t)(j * S.S) * 32 + (((ai * 2 + b) * 4 + m) * 2 + n)) * 512 + tid;
;                 f32x4 v0 = {0.f, 0.f, 0.f, 0.f}, v1 = v0, v2 = v0, v3 = v0;
;                 for (int sl = 0; sl + 3 < S.S; sl += 4) { v0 += pp[(size_t)sl * 16384]; v1 += pp[(size_t)(sl + 1) * 16384]; v2 += pp[(size_t)(sl + 2) * 16384]; v3 += pp[(size_t)(sl + 3) * 16384]; }
;                 for (int sl = S.S & ~3; sl < S.S; ++sl) v0 += pp[(size_t)sl * 16384];
;                 a4[b][n] = (v0 + v1) + (v2 + v3); }
.LBB0_2671:
	global_load_dwordx4 v[8:11], v[2:3], off nt
	s_add_i32 s25, s25, 1
	v_lshl_add_u64 v[2:3], v[2:3], 0, s[12:13]
	s_cmp_ge_i32 s25, s16
	s_waitcnt vmcnt(0)
	v_pk_add_f32 v[6:7], v[6:7], v[10:11]
	v_pk_add_f32 v[4:5], v[4:5], v[8:9]
	s_cbranch_scc0 .LBB0_2671
.LBB0_2672:
	s_and_b64 vcc, exec, s[2:3]
	s_cbranch_vccnz .LBB0_2676
	s_add_u32 s26, s14, s22
	s_addc_u32 s27, s15, 0
	v_mov_b32_e32 v50, 0
	v_lshl_add_u64 v[2:3], v[24:25], 0, s[26:27]
	s_mov_b32 s25, 3
	v_mov_b32_e32 v51, v50
	v_mov_b32_e32 v52, v50
	v_mov_b32_e32 v53, v50
	v_mov_b32_e32 v56, v50
	v_mov_b32_e32 v57, v50
	v_mov_b32_e32 v54, v50
	v_mov_b32_e32 v55, v50
	v_mov_b32_e32 v58, v50
	v_mov_b32_e32 v59, v50
	v_mov_b32_e32 v60, v50
	v_mov_b32_e32 v61, v50
	v_mov_b32_e32 v8, v50
	v_mov_b32_e32 v9, v50
	v_mov_b32_e32 v10, v50
	v_mov_b32_e32 v11, v50
	s_cmp_eq_u32 s16, 16
	s_cbranch_scc0 .LBB0_2674
	v_add_co_u32_e32 v16, vcc, s7, v2
	global_load_dwordx4 v[12:15], v[2:3], off nt
	s_nop 0
	v_addc_co_u32_e32 v17, vcc, -1, v3, vcc
	v_add_co_u32_e32 v70, vcc, s18, v2
	s_nop 0
	s_nop 0
	v_addc_co_u32_e32 v71, vcc, -1, v3, vcc
	v_add_co_u32_e32 v72, vcc, s19, v2
	s_nop 0
	s_nop 0
	v_addc_co_u32_e32 v73, vcc, 0, v3, vcc
	global_load_dwordx4 v[16:19], v[16:17], off nt
	s_nop 0
	global_load_dwordx4 v[62:65], v[70:71], off nt
	global_load_dwordx4 v[66:69], v[72:73], off nt
	v_lshl_add_u64 v[2:3], v[2:3], 0, s[10:11]
	v_add_co_u32_e32 v188, vcc, s7, v2
	global_load_dwordx4 v[184:187], v[2:3], off nt
	s_nop 0
	v_addc_co_u32_e32 v189, vcc, -1, v3, vcc
	v_add_co_u32_e32 v70, vcc, s18, v2
	s_nop 0
	s_nop 0
	v_addc_co_u32_e32 v71, vcc, -1, v3, vcc
	v_add_co_u32_e32 v72, vcc, s19, v2
	s_nop 0
	s_nop 0
	v_addc_co_u32_e32 v73, vcc, 0, v3, vcc
	global_load_dwordx4 v[188:191], v[188:189], off nt
	s_nop 0
	global_load_dwordx4 v[192:195], v[70:71], off nt
	global_load_dwordx4 v[196:199], v[72:73], off nt
	v_lshl_add_u64 v[2:3], v[2:3], 0, s[10:11]
	v_add_co_u32_e32 v204, vcc, s7, v2
	global_load_dwordx4 v[200:203], v[2:3], off nt
	s_nop 0
	v_addc_co_u32_e32 v205, vcc, -1, v3, vcc
	v_add_co_u32_e32 v70, vcc, s18, v2
	s_nop 0
	s_nop 0
	v_addc_co_u32_e32 v71, vcc, -1, v3, vcc
	v_add_co_u32_e32 v72, vcc, s19, v2
	s_nop 0
	s_nop 0
	v_addc_co_u32_e32 v73, vcc, 0, v3, vcc
	global_load_dwordx4 v[204:207], v[204:205], off nt
	s_nop 0
	global_load_dwordx4 v[208:211], v[70:71], off nt
	global_load_dwordx4 v[212:215], v[72:73], off nt
	v_lshl_add_u64 v[2:3], v[2:3], 0, s[10:11]
	v_add_co_u32_e32 v220, vcc, s7, v2
	global_load_dwordx4 v[216:219], v[2:3], off nt
	s_nop 0
	v_addc_co_u32_e32 v221, vcc, -1, v3, vcc
	v_add_co_u32_e32 v70, vcc, s18, v2
	s_nop 0
	s_nop 0
	v_addc_co_u32_e32 v71, vcc, -1, v3, vcc
	v_add_co_u32_e32 v72, vcc, s19, v2
	s_nop 0
	s_nop 0
	v_addc_co_u32_e32 v73, vcc, 0, v3, vcc
	global_load_dwordx4 v[220:223], v[220:221], off nt
	s_nop 0
	global_load_dwordx4 v[224:227], v[70:71], off nt
	global_load_dwordx4 v[228:231], v[72:73], off nt
	v_lshl_add_u64 v[2:3], v[2:3], 0, s[10:11]
	s_waitcnt vmcnt(12)
	v_pk_add_f32 v[54:55], v[54:55], v[14:15]
	v_pk_add_f32 v[56:57], v[56:57], v[12:13]
	v_pk_add_f32 v[10:11], v[10:11], v[18:19]
	v_pk_add_f32 v[8:9], v[8:9], v[16:17]
	v_pk_add_f32 v[60:61], v[60:61], v[64:65]
	v_pk_add_f32 v[58:59], v[58:59], v[62:63]
	v_pk_add_f32 v[52:53], v[52:53], v[68:69]
	v_pk_add_f32 v[50:51], v[50:51], v[66:67]
	s_waitcnt vmcnt(8)
	v_pk_add_f32 v[54:55], v[54:55], v[186:187]
	v_pk_add_f32 v[56:57], v[56:57], v[184:185]
	v_pk_add_f32 v[10:11], v[10:11], v[190:191]
	v_pk_add_f32 v[8:9], v[8:9], v[188:189]
	v_pk_add_f32 v[60:61], v[60:61], v[194:195]
	v_pk_add_f32 v[58:59], v[58:59], v[192:193]
	v_pk_add_f32 v[52:53], v[52:53], v[198:199]
	v_pk_add_f32 v[50:51], v[50:51], v[196:197]
	s_waitcnt vmcnt(4)
	v_pk_add_f32 v[54:55], v[54:55], v[202:203]
	v_pk_add_f32 v[56:57], v[56:57], v[200:201]
	v_pk_add_f32 v[10:11], v[10:11], v[206:207]
	v_pk_add_f32 v[8:9], v[8:9], v[204:205]
	v_pk_add_f32 v[60:61], v[60:61], v[210:211]
	v_pk_add_f32 v[58:59], v[58:59], v[208:209]
	v_pk_add_f32 v[52:53], v[52:53], v[214:215]
	v_pk_add_f32 v[50:51], v[50:51], v[212:213]
	s_waitcnt vmcnt(0)
	v_pk_add_f32 v[54:55], v[54:55], v[218:219]
	v_pk_add_f32 v[56:57], v[56:57], v[216:217]
	v_pk_add_f32 v[10:11], v[10:11], v[222:223]
	v_pk_add_f32 v[8:9], v[8:9], v[220:221]
	v_pk_add_f32 v[60:61], v[60:61], v[226:227]
	v_pk_add_f32 v[58:59], v[58:59], v[224:225]
	v_pk_add_f32 v[52:53], v[52:53], v[230:231]
	v_pk_add_f32 v[50:51], v[50:51], v[228:229]
	s_branch .Lfx_after_2
.LBB0_2674:
	v_add_co_u32_e32 v16, vcc, s7, v2
	global_load_dwordx4 v[12:15], v[2:3], off nt
	s_nop 0
	v_addc_co_u32_e32 v17, vcc, -1, v3, vcc
	v_add_co_u32_e32 v70, vcc, s18, v2
	s_add_i32 s25, s25, 4
	s_nop 0
	v_addc_co_u32_e32 v71, vcc, -1, v3, vcc
	v_add_co_u32_e32 v72, vcc, s19, v2
	s_cmp_lt_i32 s25, s16
	s_nop 0
	v_addc_co_u32_e32 v73, vcc, 0, v3, vcc
	global_load_dwordx4 v[16:19], v[16:17], off nt
	s_nop 0
	global_load_dwordx4 v[62:65], v[70:71], off nt
	global_load_dwordx4 v[66:69], v[72:73], off nt
	v_lshl_add_u64 v[2:3], v[2:3], 0, s[10:11]
	s_waitcnt vmcnt(3)
	v_pk_add_f32 v[54:55], v[54:55], v[14:15]
	v_pk_add_f32 v[56:57], v[56:57], v[12:13]
	s_waitcnt vmcnt(2)
	v_pk_add_f32 v[10:11], v[10:11], v[18:19]
	v_pk_add_f32 v[8:9], v[8:9], v[16:17]
	s_waitcnt vmcnt(1)
	v_pk_add_f32 v[60:61], v[60:61], v[64:65]
	v_pk_add_f32 v[58:59], v[58:59], v[62:63]
	s_waitcnt vmcnt(0)
	v_pk_add_f32 v[52:53], v[52:53], v[68:69]
	v_pk_add_f32 v[50:51], v[50:51], v[66:67]
	s_cbranch_scc1 .LBB0_2674

; template <class Epi> DI void gemm_fixup(int N, int K, const Epi& E, const float* part, int tid) {
;     ...
;         for (int b = 0; b < 2; ++b)
; #pragma unroll
;             for (int n = 0; n < 2; ++n) { const f32x4* pp = (const f32x4*)part + ((size_t)(j * S.S) * 32 + (((ai * 2 + b) * 4 + m) * 2 + n)) * 512 + tid;
;                 f32x4 v0 = {0.f, 0.f, 0.f, 0.f}, v1 = v0, v2 = v0, v3 = v0;
;                 for (int sl = 0; sl + 3 < S.S; sl += 4) { v0 += pp[(size_t)sl * 16384]; v1 += pp[(size_t)(sl + 1) * 16384]; v2 += pp[(size_t)(sl + 2) * 16384]; v3 += pp[(size_t)(sl + 3) * 16384]; }
;                 for (int sl = S.S & ~3; sl < S.S; ++sl) v0 += pp[(size_t)sl * 16384];
;                 a4[b][n] = (v0 + v1) + (v2 + v3); }
.LBB0_2678:
	global_load_dwordx4 v[12:15], v[2:3], off nt
	s_add_i32 s25, s25, 1
	v_lshl_add_u64 v[2:3], v[2:3], 0, s[12:13]
	s_cmp_lt_i32 s25, s16
	s_waitcnt vmcnt(0)
	v_pk_add_f32 v[10:11], v[10:11], v[14:15]
	v_pk_add_f32 v[8:9], v[8:9], v[12:13]
	s_cbranch_scc1 .LBB0_2678
.LBB0_2679:
	s_and_b64 vcc, exec, s[2:3]
	s_cbranch_vccnz .LBB0_2683
	s_add_u32 s26, s14, s22
	s_addc_u32 s27, s15, 0
	v_mov_b32_e32 v62, 0
	v_lshl_add_u64 v[2:3], v[28:29], 0, s[26:27]
	s_mov_b32 s25, 3
	v_mov_b32_e32 v63, v62
	v_mov_b32_e32 v64, v62
	v_mov_b32_e32 v65, v62
	v_mov_b32_e32 v68, v62
	v_mov_b32_e32 v69, v62
	v_mov_b32_e32 v66, v62
	v_mov_b32_e32 v67, v62
	v_mov_b32_e32 v70, v62
	v_mov_b32_e32 v71, v62
	v_mov_b32_e32 v72, v62
	v_mov_b32_e32 v73, v62
	v_mov_b32_e32 v12, v62
	v_mov_b32_e32 v13, v62
	v_mov_b32_e32 v14, v62
	v_mov_b32_e32 v15, v62
	s_cmp_eq_u32 s16, 16
	s_cbranch_scc0 .LBB0_2681
	v_add_co_u32_e32 v74, vcc, s7, v2
	global_load_dwordx4 v[16:19], v[2:3], off nt
	s_nop 0
	v_addc_co_u32_e32 v75, vcc, -1, v3, vcc
	v_add_co_u32_e32 v90, vcc, s18, v2
	s_nop 0
	s_nop 0
	v_addc_co_u32_e32 v91, vcc, -1, v3, vcc
	v_add_co_u32_e32 v92, vcc, s19, v2
	s_nop 0
	s_nop 0
	v_addc_co_u32_e32 v93, vcc, 0, v3, vcc
	global_load_dwordx4 v[74:77], v[74:75], off nt
	s_nop 0
	global_load_dwordx4 v[78:81], v[90:91], off nt
	global_load_dwordx4 v[82:85], v[92:93], off nt
	v_lshl_add_u64 v[2:3], v[2:3], 0, s[10:11]
	v_add_co_u32_e32 v188, vcc, s7, v2
	global_load_dwordx4 v[184:187], v[2:3], off nt
	s_nop 0
	v_addc_co_u32_e32 v189, vcc, -1, v3, vcc
	v_add_co_u32_e32 v90, vcc, s18, v2
	s_nop 0
	s_nop 0
	v_addc_co_u32_e32 v91, vcc, -1, v3, vcc
	v_add_co_u32_e32 v92, vcc, s19, v2
	s_nop 0
	s_nop 0
	v_addc_co_u32_e32 v93, vcc, 0, v3, vcc
	global_load_dwordx4 v[188:191], v[188:189], off nt
	s_nop 0
	global_load_dwordx4 v[192:195], v[90:91], off nt
	global_load_dwordx4 v[196:199], v[92:93], off nt
	v_lshl_add_u64 v[2:3], v[2:3], 0, s[10:11]
	v_add_co_u32_e32 v204, vcc, s7, v2
	global_load_dwordx4 v[200:203], v[2:3], off nt
	s_nop 0
	v_addc_co_u32_e32 v205, vcc, -1, v3, vcc
	v_add_co_u32_e32 v90, vcc, s18, v2
	s_nop 0
	s_nop 0
	v_addc_co_u32_e32 v91, vcc, -1, v3, vcc
	v_add_co_u32_e32 v92, vcc, s19, v2
	s_nop 0
	s_nop 0
	v_addc_co_u32_e32 v93, vcc, 0, v3, vcc
	global_load_dwordx4 v[204:207], v[204:205], off nt
	s_nop 0
	global_load_dwordx4 v[208:211], v[90:91], off nt
	global_load_dwordx4 v[212:215], v[92:93], off nt
	v_lshl_add_u64 v[2:3], v[2:3], 0, s[10:11]
	v_add_co_u32_e32 v220, vcc, s7, v2
	global_load_dwordx4 v[216:219], v[2:3], off nt
	s_nop 0
	v_addc_co_u32_e32 v221, vcc, -1, v3, vcc
	v_add_co_u32_e32 v90, vcc, s18, v2
	s_nop 0
	s_nop 0
	v_addc_co_u32_e32 v91, vcc, -1, v3, vcc
	v_add_co_u32_e32 v92, vcc, s19, v2
	s_nop 0
	s_nop 0
	v_addc_co_u32_e32 v93, vcc, 0, v3, vcc
	global_load_dwordx4 v[220:223], v[220:221], off nt
	s_nop 0
	global_load_dwordx4 v[224:227], v[90:91], off nt
	global_load_dwordx4 v[228:231], v[92:93], off nt
	v_lshl_add_u64 v[2:3], v[2:3], 0, s[10:11]
	s_waitcnt vmcnt(12)
	v_pk_add_f32 v[66:67], v[66:67], v[18:19]
	v_pk_add_f32 v[68:69], v[68:69], v[16:17]
	v_pk_add_f32 v[14:15], v[14:15], v[76:77]
	v_pk_add_f32 v[12:13], v[12:13], v[74:75]
	v_pk_add_f32 v[72:73], v[72:73], v[80:81]
	v_pk_add_f32 v[70:71], v[70:71], v[78:79]
	v_pk_add_f32 v[64:65], v[64:65], v[84:85]
	v_pk_add_f32 v[62:63], v[62:63], v[82:83]
	s_waitcnt vmcnt(8)
	v_pk_add_f32 v[66:67], v[66:67], v[186:187]
	v_pk_add_f32 v[68:69], v[68:69], v[184:185]
	v_pk_add_f32 v[14:15], v[14:15], v[190:191]
	v_pk_add_f32 v[12:13], v[12:13], v[188:189]
	v_pk_add_f32 v[72:73], v[72:73], v[194:195]
	v_pk_add_f32 v[70:71], v[70:71], v[192:193]
	v_pk_add_f32 v[64:65], v[64:65], v[198:199]
	v_pk_add_f32 v[62:63], v[62:63], v[196:197]
	s_waitcnt vmcnt(4)
	v_pk_add_f32 v[66:67], v[66:67], v[202:203]
	v_pk_add_f32 v[68:69], v[68:69], v[200:201]
	v_pk_add_f32 v[14:15], v[14:15], v[206:207]
	v_pk_add_f32 v[12:13], v[12:13], v[204:205]
	v_pk_add_f32 v[72:73], v[72:73], v[210:211]
	v_pk_add_f32 v[70:71], v[70:71], v[208:209]
	v_pk_add_f32 v[64:65], v[64:65], v[214:215]
	v_pk_add_f32 v[62:63], v[62:63], v[212:213]
	s_waitcnt vmcnt(0)
	v_pk_add_f32 v[66:67], v[66:67], v[218:219]
	v_pk_add_f32 v[68:69], v[68:69], v[216:217]
	v_pk_add_f32 v[14:15], v[14:15], v[222:223]
	v_pk_add_f32 v[12:13], v[12:13], v[220:221]
	v_pk_add_f32 v[72:73], v[72:73], v[226:227]
	v_pk_add_f32 v[70:71], v[70:71], v[224:225]
	v_pk_add_f32 v[64:65], v[64:65], v[230:231]
	v_pk_add_f32 v[62:63], v[62:63], v[228:229]
	s_branch .Lfx_after_1
.LBB0_2681:
	v_add_co_u32_e32 v74, vcc, s7, v2
	global_load_dwordx4 v[16:19], v[2:3], off nt
	s_nop 0
	v_addc_co_u32_e32 v75, vcc, -1, v3, vcc
	v_add_co_u32_e32 v90, vcc, s18, v2
	s_add_i32 s25, s25, 4
	s_nop 0
	v_addc_co_u32_e32 v91, vcc, -1, v3, vcc
	v_add_co_u32_e32 v92, vcc, s19, v2
	s_cmp_lt_i32 s25, s16
	s_nop 0
	v_addc_co_u32_e32 v93, vcc, 0, v3, vcc
	global_load_dwordx4 v[74:77], v[74:75], off nt
	s_nop 0
	global_load_dwordx4 v[78:81], v[90:91], off nt
	global_load_dwordx4 v[82:85], v[92:93], off nt
	v_lshl_add_u64 v[2:3], v[2:3], 0, s[10:11]
	s_waitcnt vmcnt(3)
	v_pk_add_f32 v[66:67], v[66:67], v[18:19]
	v_pk_add_f32 v[68:69], v[68:69], v[16:17]
	s_waitcnt vmcnt(2)
	v_pk_add_f32 v[14:15], v[14:15], v[76:77]
	v_pk_add_f32 v[12:13], v[12:13], v[74:75]
	s_waitcnt vmcnt(1)
	v_pk_add_f32 v[72:73], v[72:73], v[80:81]
	v_pk_add_f32 v[70:71], v[70:71], v[78:79]
	s_waitcnt vmcnt(0)
	v_pk_add_f32 v[64:65], v[64:65], v[84:85]
	v_pk_add_f32 v[62:63], v[62:63], v[82:83]
	s_cbranch_scc1 .LBB0_2681

; template <class Epi> DI void gemm_fixup(int N, int K, const Epi& E, const float* part, int tid) {
;     ...
;         for (int b = 0; b < 2; ++b)
; #pragma unroll
;             for (int n = 0; n < 2; ++n) { const f32x4* pp = (const f32x4*)part + ((size_t)(j * S.S) * 32 + (((ai * 2 + b) * 4 + m) * 2 + n)) * 512 + tid;
;                 f32x4 v0 = {0.f, 0.f, 0.f, 0.f}, v1 = v0, v2 = v0, v3 = v0;
;                 for (int sl = 0; sl + 3 < S.S; sl += 4) { v0 += pp[(size_t)sl * 16384]; v1 += pp[(size_t)(sl + 1) * 16384]; v2 += pp[(size_t)(sl + 2) * 16384]; v3 += pp[(size_t)(sl + 3) * 16384]; }
;                 for (int sl = S.S & ~3; sl < S.S; ++sl) v0 += pp[(size_t)sl * 16384];
;                 a4[b][n] = (v0 + v1) + (v2 + v3); }
.LBB0_2685:
	global_load_dwordx4 v[16:19], v[2:3], off nt
	s_add_i32 s25, s25, 1
	v_lshl_add_u64 v[2:3], v[2:3], 0, s[12:13]
	s_cmp_lt_i32 s25, s16
	s_waitcnt vmcnt(0)
	v_pk_add_f32 v[14:15], v[14:15], v[18:19]
	v_pk_add_f32 v[12:13], v[12:13], v[16:17]
	s_cbranch_scc1 .LBB0_2685
.LBB0_2686:
	s_and_b64 vcc, exec, s[2:3]
	s_cbranch_vccnz .LBB0_2690
	s_add_u32 s26, s14, s22
	s_addc_u32 s27, s15, 0
	v_mov_b32_e32 v74, 0
	v_lshl_add_u64 v[2:3], v[32:33], 0, s[26:27]
	s_mov_b32 s25, 3
	v_mov_b32_e32 v75, v74
	v_mov_b32_e32 v76, v74
	v_mov_b32_e32 v77, v74
	v_mov_b32_e32 v80, v74
	v_mov_b32_e32 v81, v74
	v_mov_b32_e32 v78, v74
	v_mov_b32_e32 v79, v74
	v_mov_b32_e32 v82, v74
	v_mov_b32_e32 v83, v74
	v_mov_b32_e32 v84, v74
	v_mov_b32_e32 v85, v74
	v_mov_b32_e32 v16, v74
	v_mov_b32_e32 v17, v74
	v_mov_b32_e32 v18, v74
	v_mov_b32_e32 v19, v74
	s_cmp_eq_u32 s16, 16
	s_cbranch_scc0 .LBB0_2688
	v_add_co_u32_e32 v94, vcc, s7, v2
	global_load_dwordx4 v[90:93], v[2:3], off nt
	s_nop 0
	v_addc_co_u32_e32 v95, vcc, -1, v3, vcc
	v_add_co_u32_e32 v106, vcc, s18, v2
	s_nop 0
	s_nop 0
	v_addc_co_u32_e32 v107, vcc, -1, v3, vcc
	v_add_co_u32_e32 v108, vcc, s19, v2
	s_nop 0
	s_nop 0
	v_addc_co_u32_e32 v109, vcc, 0, v3, vcc
	global_load_dwordx4 v[94:97], v[94:95], off nt
	s_nop 0
	global_load_dwordx4 v[98:101], v[106:107], off nt
	global_load_dwordx4 v[102:105], v[108:109], off nt
	v_lshl_add_u64 v[2:3], v[2:3], 0, s[10:11]
	v_add_co_u32_e32 v188, vcc, s7, v2
	global_load_dwordx4 v[184:187], v[2:3], off nt
	s_nop 0
	v_addc_co_u32_e32 v189, vcc, -1, v3, vcc
	v_add_co_u32_e32 v106, vcc, s18, v2
	s_nop 0
	s_nop 0
	v_addc_co_u32_e32 v107, vcc, -1, v3, vcc
	v_add_co_u32_e32 v108, vcc, s19, v2
	s_nop 0
	s_nop 0
	v_addc_co_u32_e32 v109, vcc, 0, v3, vcc
	global_load_dwordx4 v[188:191], v[188:189], off nt
	s_nop 0
	global_load_dwordx4 v[192:195], v[106:107], off nt
	global_load_dwordx4 v[196:199], v[108:109], off nt
	v_lshl_add_u64 v[2:3], v[2:3], 0, s[10:11]
	v_add_co_u32_e32 v204, vcc, s7, v2
	global_load_dwordx4 v[200:203], v[2:3], off nt
	s_nop 0
	v_addc_co_u32_e32 v205, vcc, -1, v3, vcc
	v_add_co_u32_e32 v106, vcc, s18, v2
	s_nop 0
	s_nop 0
	v_addc_co_u32_e32 v107, vcc, -1, v3, vcc
	v_add_co_u32_e32 v108, vcc, s19, v2
	s_nop 0
	s_nop 0
	v_addc_co_u32_e32 v109, vcc, 0, v3, vcc
	global_load_dwordx4 v[204:207], v[204:205], off nt
	s_nop 0
	global_load_dwordx4 v[208:211], v[106:107], off nt
	global_load_dwordx4 v[212:215], v[108:109], off nt
	v_lshl_add_u64 v[2:3], v[2:3], 0, s[10:11]
	v_add_co_u32_e32 v220, vcc, s7, v2
	global_load_dwordx4 v[216:219], v[2:3], off nt
	s_nop 0
	v_addc_co_u32_e32 v221, vcc, -1, v3, vcc
	v_add_co_u32_e32 v106, vcc, s18, v2
	s_nop 0
	s_nop 0
	v_addc_co_u32_e32 v107, vcc, -1, v3, vcc
	v_add_co_u32_e32 v108, vcc, s19, v2
	s_nop 0
	s_nop 0
	v_addc_co_u32_e32 v109, vcc, 0, v3, vcc
	global_load_dwordx4 v[220:223], v[220:221], off nt
	s_nop 0
	global_load_dwordx4 v[224:227], v[106:107], off nt
	global_load_dwordx4 v[228:231], v[108:109], off nt
	v_lshl_add_u64 v[2:3], v[2:3], 0, s[10:11]
	s_waitcnt vmcnt(12)
	v_pk_add_f32 v[78:79], v[78:79], v[92:93]
	v_pk_add_f32 v[80:81], v[80:81], v[90:91]
	v_pk_add_f32 v[18:19], v[18:19], v[96:97]
	v_pk_add_f32 v[16:17], v[16:17], v[94:95]
	v_pk_add_f32 v[84:85], v[84:85], v[100:101]
	v_pk_add_f32 v[82:83], v[82:83], v[98:99]
	v_pk_add_f32 v[76:77], v[76:77], v[104:105]
	v_pk_add_f32 v[74:75], v[74:75], v[102:103]
	s_waitcnt vmcnt(8)
	v_pk_add_f32 v[78:79], v[78:79], v[186:187]
	v_pk_add_f32 v[80:81], v[80:81], v[184:185]
	v_pk_add_f32 v[18:19], v[18:19], v[190:191]
	v_pk_add_f32 v[16:17], v[16:17], v[188:189]
	v_pk_add_f32 v[84:85], v[84:85], v[194:195]
	v_pk_add_f32 v[82:83], v[82:83], v[192:193]
	v_pk_add_f32 v[76:77], v[76:77], v[198:199]
	v_pk_add_f32 v[74:75], v[74:75], v[196:197]
	s_waitcnt vmcnt(4)
	v_pk_add_f32 v[78:79], v[78:79], v[202:203]
	v_pk_add_f32 v[80:81], v[80:81], v[200:201]
	v_pk_add_f32 v[18:19], v[18:19], v[206:207]
	v_pk_add_f32 v[16:17], v[16:17], v[204:205]
	v_pk_add_f32 v[84:85], v[84:85], v[210:211]
	v_pk_add_f32 v[82:83], v[82:83], v[208:209]
	v_pk_add_f32 v[76:77], v[76:77], v[214:215]
	v_pk_add_f32 v[74:75], v[74:75], v[212:213]
	s_waitcnt vmcnt(0)
	v_pk_add_f32 v[78:79], v[78:79], v[218:219]
	v_pk_add_f32 v[80:81], v[80:81], v[216:217]
	v_pk_add_f32 v[18:19], v[18:19], v[222:223]
	v_pk_add_f32 v[16:17], v[16:17], v[220:221]
	v_pk_add_f32 v[84:85], v[84:85], v[226:227]
	v_pk_add_f32 v[82:83], v[82:83], v[224:225]
	v_pk_add_f32 v[76:77], v[76:77], v[230:231]
	v_pk_add_f32 v[74:75], v[74:75], v[228:229]
	s_branch .Lfx_after_0
.LBB0_2688:
	v_add_co_u32_e32 v94, vcc, s7, v2
	global_load_dwordx4 v[90:93], v[2:3], off nt
	s_nop 0
	v_addc_co_u32_e32 v95, vcc, -1, v3, vcc
	v_add_co_u32_e32 v106, vcc, s18, v2
	s_add_i32 s25, s25, 4
	s_nop 0
	v_addc_co_u32_e32 v107, vcc, -1, v3, vcc
	v_add_co_u32_e32 v108, vcc, s19, v2
	s_cmp_lt_i32 s25, s16
	s_nop 0
	v_addc_co_u32_e32 v109, vcc, 0, v3, vcc
	global_load_dwordx4 v[94:97], v[94:95], off nt
	s_nop 0
	global_load_dwordx4 v[98:101], v[106:107], off nt
	global_load_dwordx4 v[102:105], v[108:109], off nt
	v_lshl_add_u64 v[2:3], v[2:3], 0, s[10:11]
	s_waitcnt vmcnt(3)
	v_pk_add_f32 v[78:79], v[78:79], v[92:93]
	v_pk_add_f32 v[80:81], v[80:81], v[90:91]
	s_waitcnt vmcnt(2)
	v_pk_add_f32 v[18:19], v[18:19], v[96:97]
	v_pk_add_f32 v[16:17], v[16:17], v[94:95]
	s_waitcnt vmcnt(1)
	v_pk_add_f32 v[84:85], v[84:85], v[100:101]
	v_pk_add_f32 v[82:83], v[82:83], v[98:99]
	s_waitcnt vmcnt(0)
	v_pk_add_f32 v[76:77], v[76:77], v[104:105]
	v_pk_add_f32 v[74:75], v[74:75], v[102:103]
	s_cbranch_scc1 .LBB0_2688

; template <class Epi> DI void gemm_fixup(int N, int K, const Epi& E, const float* part, int tid) {
;     ...
;                 for (int sl = 0; sl + 3 < S.S; sl += 4) { v0 += pp[(size_t)sl * 16384]; v1 += pp[(size_t)(sl + 1) * 16384]; v2 += pp[(size_t)(sl + 2) * 16384]; v3 += pp[(size_t)(sl + 3) * 16384]; }
;                 for (int sl = S.S & ~3; sl < S.S; ++sl) v0 += pp[(size_t)sl * 16384];
.LBB0_2692:
	global_load_dwordx4 v[90:93], v[2:3], off nt
	s_add_i32 s4, s4, 1
	v_lshl_add_u64 v[2:3], v[2:3], 0, s[12:13]
	s_cmp_lt_i32 s4, s16
	s_waitcnt vmcnt(0)
	v_pk_add_f32 v[18:19], v[18:19], v[92:93]
	v_pk_add_f32 v[16:17], v[16:17], v[90:91]
	s_cbranch_scc1 .LBB0_2692
; DI unsigned pk2(float lo, float hi) { unsigned r; asm volatile("v_cvt_pk_bf16_f32 %0, %1, %2" : "=v"(r) : "v"(lo), "v"(hi)); return r; }
; DI float bflo(unsigned u) { return __uint_as_float(u << 16); }
;     DI float upd(u32x4v* px, const u32x4v x, const f32x4 v0, const f32x4 v1) const {
;         u32x4v o; o.x = pk2(bflo(x.x) + v0[0], bfhi(x.x) + v0[1]); o.y = pk2(bflo(x.y) + v0[2], bfhi(x.y) + v0[3]);
;         o.z = pk2(bflo(x.z) + v1[0], bfhi(x.z) + v1[1]); o.w = pk2(bflo(x.w) + v1[2], bfhi(x.w) + v1[3]); *px = o;
;         const float a0 = bflo(o.x), a1 = bfhi(o.x), a2 = bflo(o.y), a3 = bfhi(o.y), a4 = bflo(o.z), a5 = bfhi(o.z), a6 = bflo(o.w), a7 = bfhi(o.w);
;         return ((a0 * a0 + a1 * a1) + (a2 * a2 + a3 * a3)) + ((a4 * a4 + a5 * a5) + (a6 * a6 + a7 * a7));
;     }
;     DI void row(const f32x4 (&a4)[2][2], const Unit& u, int ai, int m, int wr, int wc, int fr, int fq) const {
;         const int cb = u.pn * 256 + wc * 32 + 8 * fq, row = u.pm * 256 + wr * 64 + fr + ai * 128 + m * 16;
;         u32x4v* p0 = (u32x4v*)(XB + (size_t)row * 1024 + cb); u32x4v* p1 = (u32x4v*)(XB + (size_t)row * 1024 + cb + 128);
;         const u32x4v x0 = *p0, x1 = *p1;
;         float ss = upd(p0, x0, a4[0][0], a4[0][1]) + upd(p1, x1, a4[1][0], a4[1][1]);
;         ss += __shfl_xor(ss, 16); ss += __shfl_xor(ss, 32);
;         if (fq == 0) SSQ[(size_t)row * 16 + u.pn * 4 + wc] = ss;
;     }
; template <class Epi> DI void gemm_fixup(int N, int K, const Epi& E, const float* part, int tid) {
;     ...
;     for (int it = blockIdx.x; it < S.ntail * 8; it += gridDim.x) { const int j = it >> 3, ai = (it >> 2) & 1, m = it & 3; Unit u; S.map(S.nwhole * S.G + j, u);
;         f32x4 a4[2][2];
; #pragma unroll
;         for (int b = 0; b < 2; ++b)
; #pragma unroll
;             for (int n = 0; n < 2; ++n) { const f32x4* pp = (const f32x4*)part + ((size_t)(j * S.S) * 32 + (((ai * 2 + b) * 4 + m) * 2 + n)) * 512 + tid;
;                 f32x4 v0 = {0.f, 0.f, 0.f, 0.f}, v1 = v0, v2 = v0, v3 = v0;
;                 for (int sl = 0; sl + 3 < S.S; sl += 4) { v0 += pp[(size_t)sl * 16384]; v1 += pp[(size_t)(sl + 1) * 16384]; v2 += pp[(size_t)(sl + 2) * 16384]; v3 += pp[(size_t)(sl + 3) * 16384]; }
;                 for (int sl = S.S & ~3; sl < S.S; ++sl) v0 += pp[(size_t)sl * 16384];
;                 a4[b][n] = (v0 + v1) + (v2 + v3); }
;         E.row(a4, u, ai, m, wr, wc, fr, fq); }
.LBB0_2693:
	s_add_i32 s4, s21, s24
	s_ashr_i32 s5, s4, 31
	s_lshr_b32 s5, s5, 27
	s_add_i32 s5, s4, s5
	s_ashr_i32 s14, s5, 5
	s_lshl_b32 s15, s14, 3
	s_sub_i32 s14, 0x83, s15
	s_min_i32 s21, s14, 8
	s_abs_i32 s14, s21
	v_cvt_f32_u32_e32 v1, s14
	s_sub_i32 s24, 0, s14
	s_andn2_b32 s5, s5, 31
	s_sub_i32 s4, s4, s5
	v_rcp_iflag_f32_e32 v1, v1
	s_abs_i32 s5, s4
	s_xor_b32 s22, s4, s21
	s_ashr_i32 s22, s22, 31
	v_mul_f32_e32 v1, 0x4f7ffffe, v1
	v_cvt_u32_f32_e32 v1, v1
	v_readlane_b32 s44, v254, 28
	v_readlane_b32 s56, v254, 40
	v_readlane_b32 s57, v254, 41
	v_readfirstlane_b32 s25, v1
	s_mul_i32 s24, s24, s25
	s_mul_hi_u32 s24, s25, s24
	s_add_i32 s25, s25, s24
	s_mul_hi_u32 s24, s5, s25
	s_mul_i32 s25, s24, s14
	s_sub_i32 s5, s5, s25
	s_add_i32 s26, s24, 1
	s_sub_i32 s25, s5, s14
	s_cmp_ge_u32 s5, s14
	s_cselect_b32 s24, s26, s24
	s_cselect_b32 s5, s25, s5
	s_add_i32 s25, s24, 1
	s_cmp_ge_u32 s5, s14
	s_cselect_b32 s5, s25, s24
	s_xor_b32 s5, s5, s22
	s_sub_i32 s14, s5, s22
	s_mul_i32 s5, s14, s21
	s_sub_i32 s4, s4, s5
	s_and_b32 s23, s23, 1
	s_add_i32 s15, s15, s4
	s_and_b32 s4, s84, 3
	s_lshl_b32 s5, s15, 8
	s_lshl_b32 s15, s23, 7
	v_lshl_or_b32 v1, s4, 4, v87
	s_or_b32 s4, s5, s15
	v_add_u32_e32 v2, s4, v1
	v_ashrrev_i32_e32 v3, 31, v2
	v_lshl_or_b32 v90, s14, 8, v86
	v_lshlrev_b64 v[92:93], 11, v[2:3]
	v_lshl_add_u64 v[92:93], s[56:57], 0, v[92:93]
	v_ashrrev_i32_e32 v91, 31, v90
	v_lshl_add_u64 v[98:99], v[90:91], 1, v[92:93]
	global_load_dwordx4 v[90:93], v[98:99], off nt
	global_load_dwordx4 v[94:97], v[98:99], off offset:256 nt
	v_pk_add_f32 v[6:7], v[48:49], v[6:7]
	v_pk_add_f32 v[4:5], v[46:47], v[4:5]
	v_pk_add_f32 v[38:39], v[44:45], v[38:39]
	v_pk_add_f32 v[40:41], v[42:43], v[40:41]
	v_pk_add_f32 v[10:11], v[60:61], v[10:11]
	v_pk_add_f32 v[8:9], v[58:59], v[8:9]
	v_pk_add_f32 v[50:51], v[56:57], v[50:51]
	v_pk_add_f32 v[52:53], v[54:55], v[52:53]
	v_pk_add_f32 v[16:17], v[82:83], v[16:17]
	v_pk_add_f32 v[42:43], v[80:81], v[74:75]
	v_pk_add_f32 v[6:7], v[40:41], v[6:7]
	v_pk_add_f32 v[4:5], v[38:39], v[4:5]
	v_pk_add_f32 v[14:15], v[72:73], v[14:15]
	v_pk_add_f32 v[12:13], v[70:71], v[12:13]
	v_pk_add_f32 v[62:63], v[68:69], v[62:63]
	v_pk_add_f32 v[64:65], v[66:67], v[64:65]
	v_pk_add_f32 v[18:19], v[84:85], v[18:19]
	v_pk_add_f32 v[44:45], v[78:79], v[76:77]
	v_pk_add_f32 v[10:11], v[52:53], v[10:11]
	v_pk_add_f32 v[8:9], v[50:51], v[8:9]
	v_pk_add_f32 v[16:17], v[42:43], v[16:17]
	v_pk_add_f32 v[14:15], v[64:65], v[14:15]
	v_pk_add_f32 v[12:13], v[62:63], v[12:13]
	v_pk_add_f32 v[18:19], v[44:45], v[18:19]
	v_readlane_b32 s45, v254, 29
	v_readlane_b32 s46, v254, 30
	v_readlane_b32 s47, v254, 31
	v_readlane_b32 s48, v254, 32
	v_readlane_b32 s49, v254, 33
	v_readlane_b32 s50, v254, 34
	v_readlane_b32 s51, v254, 35
	v_readlane_b32 s52, v254, 36
	v_readlane_b32 s53, v254, 37
	v_readlane_b32 s54, v254, 38
	v_readlane_b32 s55, v254, 39
	v_readlane_b32 s58, v254, 42
	v_readlane_b32 s59, v254, 43
	s_waitcnt vmcnt(1)
	v_lshlrev_b32_e32 v1, 16, v90
	v_and_b32_e32 v37, 0xffff0000, v90
	v_lshlrev_b32_e32 v38, 16, v91
	v_and_b32_e32 v39, 0xffff0000, v91
	v_lshlrev_b32_e32 v40, 16, v92
	v_and_b32_e32 v41, 0xffff0000, v92
	v_lshlrev_b32_e32 v42, 16, v93
	v_add_f32_e32 v1, v4, v1
	v_add_f32_e32 v4, v5, v37
	v_add_f32_e32 v5, v6, v38
	v_and_b32_e32 v43, 0xffff0000, v93
	s_waitcnt vmcnt(0)
	v_lshlrev_b32_e32 v44, 16, v94
	v_and_b32_e32 v45, 0xffff0000, v94
	v_lshlrev_b32_e32 v46, 16, v95
	v_and_b32_e32 v47, 0xffff0000, v95
	v_lshlrev_b32_e32 v48, 16, v96
	v_and_b32_e32 v49, 0xffff0000, v96
	v_lshlrev_b32_e32 v50, 16, v97
	v_add_f32_e32 v6, v7, v39
	v_add_f32_e32 v7, v8, v40
	v_add_f32_e32 v8, v9, v41
	v_add_f32_e32 v9, v10, v42
	v_cvt_pk_bf16_f32 v4, v1, v4
	v_cvt_pk_bf16_f32 v5, v5, v6
	v_add_f32_e32 v10, v11, v43
	v_add_f32_e32 v11, v12, v44
	v_add_f32_e32 v12, v13, v45
	v_add_f32_e32 v13, v14, v46
	v_add_f32_e32 v14, v15, v47
	v_add_f32_e32 v15, v16, v48
	v_add_f32_e32 v16, v17, v49
	v_add_f32_e32 v17, v18, v50
	v_cvt_pk_bf16_f32 v6, v7, v8
	v_cvt_pk_bf16_f32 v7, v9, v10
	global_store_dwordx4 v[98:99], v[4:7], off
	v_lshlrev_b32_e32 v1, 16, v4
	v_lshlrev_b32_e32 v9, 16, v5
	v_and_b32_e32 v4, 0xffff0000, v4
	v_and_b32_e32 v5, 0xffff0000, v5
	v_and_b32_e32 v18, 0xffff0000, v6
	v_and_b32_e32 v38, 0xffff0000, v7
	v_lshlrev_b32_e32 v10, 16, v6
	v_lshlrev_b32_e32 v37, 16, v7
	v_cvt_pk_bf16_f32 v6, v11, v12
	v_mul_f32_e32 v4, v4, v4
	v_mul_f32_e32 v5, v5, v5
	v_mul_f32_e32 v11, v18, v18
	v_mul_f32_e32 v12, v38, v38
	v_fmac_f32_e32 v4, v1, v1
	v_fmac_f32_e32 v5, v9, v9
	v_fmac_f32_e32 v11, v10, v10
	v_fmac_f32_e32 v12, v37, v37
	v_add_f32_e32 v1, v4, v5
	v_add_f32_e32 v4, v11, v12
	v_add_f32_e32 v1, v1, v4
	v_and_b32_e32 v4, 0xffff0000, v97
	v_add_f32_e32 v4, v19, v4
	v_and_b32_e32 v5, 0xffff0000, v6
	v_cvt_pk_bf16_f32 v7, v13, v14
	v_cvt_pk_bf16_f32 v8, v15, v16
	v_cvt_pk_bf16_f32 v9, v17, v4
	v_lshlrev_b32_e32 v4, 16, v6
	v_and_b32_e32 v11, 0xffff0000, v7
	v_mul_f32_e32 v5, v5, v5
	v_lshlrev_b32_e32 v10, 16, v7
	v_fmac_f32_e32 v5, v4, v4
	v_mul_f32_e32 v4, v11, v11
	v_and_b32_e32 v13, 0xffff0000, v8
	v_and_b32_e32 v15, 0xffff0000, v9
	v_fmac_f32_e32 v4, v10, v10
	v_lshlrev_b32_e32 v12, 16, v8
	v_lshlrev_b32_e32 v14, 16, v9
	v_add_f32_e32 v4, v5, v4
	v_mul_f32_e32 v5, v13, v13
	v_mul_f32_e32 v10, v15, v15
	v_fmac_f32_e32 v5, v12, v12
	v_fmac_f32_e32 v10, v14, v14
	v_add_f32_e32 v5, v5, v10
	v_add_f32_e32 v4, v4, v5
	v_and_b32_e32 v5, 64, v88
	v_add_f32_e32 v1, v1, v4
	v_xor_b32_e32 v4, 16, v88
	v_add_u32_e32 v5, 64, v5
	v_cmp_lt_i32_e32 vcc, v4, v5
	global_store_dwordx4 v[98:99], v[6:9], off offset:256
	s_nop 0
	v_cndmask_b32_e32 v4, v88, v4, vcc
	v_lshlrev_b32_e32 v4, 2, v4
	ds_bpermute_b32 v4, v4, v1
	s_waitcnt lgkmcnt(0)
	v_add_f32_e32 v1, v1, v4
	v_xor_b32_e32 v4, 32, v88
	v_cmp_lt_i32_e32 vcc, v4, v5
	s_nop 1
	v_cndmask_b32_e32 v4, v88, v4, vcc
	v_lshlrev_b32_e32 v4, 2, v4
	ds_bpermute_b32 v4, v4, v1
	s_and_saveexec_b64 s[4:5], s[0:1]
	s_xor_b64 s[4:5], exec, s[4:5]
	s_cbranch_execz .LBB0_2660
	v_readlane_b32 s44, v254, 28
	s_lshl_b32 s14, s14, 2
	v_lshlrev_b64 v[2:3], 6, v[2:3]
	v_readlane_b32 s58, v254, 42
	v_readlane_b32 s59, v254, 43
	s_ashr_i32 s15, s14, 31
	v_mov_b32_e32 v37, v0
	v_lshl_add_u64 v[2:3], s[58:59], 0, v[2:3]
	v_lshl_add_u64 v[2:3], s[14:15], 2, v[2:3]
	s_waitcnt lgkmcnt(0)
	v_add_f32_e32 v1, v1, v4
	v_lshl_add_u64 v[2:3], v[2:3], 0, v[36:37]
	v_readlane_b32 s45, v254, 29
	v_readlane_b32 s46, v254, 30
	v_readlane_b32 s47, v254, 31
	v_readlane_b32 s48, v254, 32
	v_readlane_b32 s49, v254, 33
	v_readlane_b32 s50, v254, 34
	v_readlane_b32 s51, v254, 35
	v_readlane_b32 s52, v254, 36
	v_readlane_b32 s53, v254, 37
	v_readlane_b32 s54, v254, 38
	v_readlane_b32 s55, v254, 39
	v_readlane_b32 s56, v254, 40
	v_readlane_b32 s57, v254, 41
	global_store_dword v[2:3], v1, off
	s_branch .LBB0_2660
